# in-proj pair loop: DMA issue spread 2/4/4/2 over the four quarters (last two A_X pieces moved into the next X first quarter)
# speedup vs baseline: 1.0040x; 1.0040x over previous
.Lpk_sw_pf:
	s_and_b32 s100, s100, 0xffffefff
	s_add_u32 m0, s4, 0x0
	s_nop 0
	global_load_lds_dwordx4 v98, s[6:7]
	s_add_u32 m0, s4, 0x400
	s_nop 0
	global_load_lds_dwordx4 v99, s[6:7]
	s_add_u32 m0, s4, 0x800
	s_nop 0
	global_load_lds_dwordx4 v100, s[6:7]
	s_add_u32 m0, s4, 0xc00
	s_nop 0
	global_load_lds_dwordx4 v101, s[6:7]
	v_add_u32_e32 v98, 0x80, v98
	v_add_u32_e32 v99, 0x80, v99
	v_add_u32_e32 v100, 0x80, v100
	v_add_u32_e32 v101, 0x80, v101
	s_add_u32 m0, s4, 0x8000
	s_nop 0
	global_load_lds_dwordx4 v98, s[48:49]
	s_add_u32 m0, s4, 0x8400
	s_nop 0
	global_load_lds_dwordx4 v99, s[48:49]
	s_add_u32 m0, s4, 0x8800
	s_nop 0
	global_load_lds_dwordx4 v100, s[48:49]
	s_add_u32 m0, s4, 0x8c00
	s_nop 0
	global_load_lds_dwordx4 v101, s[48:49]
	s_add_u32 m0, s4, 0x4000
	s_nop 0
	global_load_lds_dwordx4 v98, s[28:29]
	s_add_u32 m0, s4, 0x4400
	s_nop 0
	global_load_lds_dwordx4 v99, s[28:29]
	s_add_u32 m0, s4, 0x4800
	s_nop 0
	global_load_lds_dwordx4 v100, s[28:29]
	s_add_u32 m0, s4, 0x4c00
	s_nop 0
	global_load_lds_dwordx4 v101, s[28:29]
	v_mov_b32_e32 v62, 0
	v_mov_b32_e32 v106, 0
	v_mov_b32_e32 v63, 0
	v_mov_b32_e32 v107, 0
	v_mov_b32_e32 v64, 0
	v_mov_b32_e32 v108, 0
	v_mov_b32_e32 v65, 0
	v_mov_b32_e32 v109, 0
	v_mov_b32_e32 v58, 0
	v_mov_b32_e32 v110, 0
	v_mov_b32_e32 v59, 0
	v_mov_b32_e32 v111, 0
	v_mov_b32_e32 v60, 0
	v_mov_b32_e32 v112, 0
	v_mov_b32_e32 v61, 0
	v_mov_b32_e32 v113, 0
	v_mov_b32_e32 v54, 0
	v_mov_b32_e32 v114, 0
	v_mov_b32_e32 v55, 0
	v_mov_b32_e32 v115, 0
	v_mov_b32_e32 v56, 0
	v_mov_b32_e32 v116, 0
	v_mov_b32_e32 v57, 0
	v_mov_b32_e32 v117, 0
	v_mov_b32_e32 v50, 0
	v_mov_b32_e32 v118, 0
	v_mov_b32_e32 v51, 0
	v_mov_b32_e32 v119, 0
	v_mov_b32_e32 v52, 0
	v_mov_b32_e32 v120, 0
	v_mov_b32_e32 v53, 0
	v_mov_b32_e32 v121, 0
	v_mov_b32_e32 v46, 0
	v_mov_b32_e32 v122, 0
	v_mov_b32_e32 v47, 0
	v_mov_b32_e32 v123, 0
	v_mov_b32_e32 v48, 0
	v_mov_b32_e32 v124, 0
	v_mov_b32_e32 v49, 0
	v_mov_b32_e32 v125, 0
	v_mov_b32_e32 v42, 0
	v_mov_b32_e32 v126, 0
	v_mov_b32_e32 v43, 0
	v_mov_b32_e32 v127, 0
	v_mov_b32_e32 v44, 0
	v_mov_b32_e32 v128, 0
	v_mov_b32_e32 v45, 0
	v_mov_b32_e32 v129, 0
	v_mov_b32_e32 v38, 0
	v_mov_b32_e32 v130, 0
	v_mov_b32_e32 v39, 0
	v_mov_b32_e32 v131, 0
	v_mov_b32_e32 v40, 0
	v_mov_b32_e32 v132, 0
	v_mov_b32_e32 v41, 0
	v_mov_b32_e32 v133, 0
	v_mov_b32_e32 v34, 0
	v_mov_b32_e32 v134, 0
	v_mov_b32_e32 v35, 0
	v_mov_b32_e32 v135, 0
	v_mov_b32_e32 v36, 0
	v_mov_b32_e32 v136, 0
	v_mov_b32_e32 v37, 0
	v_mov_b32_e32 v137, 0
	v_mov_b32_e32 v30, 0
	v_mov_b32_e32 v138, 0
	v_mov_b32_e32 v31, 0
	v_mov_b32_e32 v139, 0
	v_mov_b32_e32 v32, 0
	v_mov_b32_e32 v140, 0
	v_mov_b32_e32 v33, 0
	v_mov_b32_e32 v141, 0
	v_mov_b32_e32 v26, 0
	v_mov_b32_e32 v142, 0
	v_mov_b32_e32 v27, 0
	v_mov_b32_e32 v143, 0
	v_mov_b32_e32 v28, 0
	v_mov_b32_e32 v144, 0
	v_mov_b32_e32 v29, 0
	v_mov_b32_e32 v145, 0
	v_mov_b32_e32 v22, 0
	v_mov_b32_e32 v154, 0
	v_mov_b32_e32 v23, 0
	v_mov_b32_e32 v155, 0
	v_mov_b32_e32 v24, 0
	v_mov_b32_e32 v156, 0
	v_mov_b32_e32 v25, 0
	v_mov_b32_e32 v157, 0
	v_mov_b32_e32 v18, 0
	v_mov_b32_e32 v158, 0
	v_mov_b32_e32 v19, 0
	v_mov_b32_e32 v159, 0
	v_mov_b32_e32 v20, 0
	v_mov_b32_e32 v160, 0
	v_mov_b32_e32 v21, 0
	v_mov_b32_e32 v161, 0
	v_mov_b32_e32 v14, 0
	v_mov_b32_e32 v162, 0
	v_mov_b32_e32 v15, 0
	v_mov_b32_e32 v163, 0
	v_mov_b32_e32 v16, 0
	v_mov_b32_e32 v164, 0
	v_mov_b32_e32 v17, 0
	v_mov_b32_e32 v165, 0
	v_mov_b32_e32 v10, 0
	v_mov_b32_e32 v166, 0
	v_mov_b32_e32 v11, 0
	v_mov_b32_e32 v167, 0
	v_mov_b32_e32 v12, 0
	v_mov_b32_e32 v168, 0
	v_mov_b32_e32 v13, 0
	v_mov_b32_e32 v169, 0
	v_mov_b32_e32 v6, 0
	v_mov_b32_e32 v170, 0
	v_mov_b32_e32 v7, 0
	v_mov_b32_e32 v171, 0
	v_mov_b32_e32 v8, 0
	v_mov_b32_e32 v172, 0
	v_mov_b32_e32 v9, 0
	v_mov_b32_e32 v173, 0
	v_mov_b32_e32 v2, 0
	v_mov_b32_e32 v174, 0
	v_mov_b32_e32 v3, 0
	v_mov_b32_e32 v175, 0
	v_mov_b32_e32 v4, 0
	v_mov_b32_e32 v176, 0
	v_mov_b32_e32 v5, 0
	v_mov_b32_e32 v177, 0
	s_waitcnt vmcnt(12)
	s_barrier
	ds_read_b128 v[218:221], v102 offset:49152
	ds_read_b128 v[222:225], v102 offset:51200
	ds_read_b128 v[226:229], v102 offset:53248
	ds_read_b128 v[230:233], v102 offset:55296
	ds_read_b128 v[66:69], v250 offset:49152
	ds_read_b128 v[70:73], v250 offset:51200
	ds_read_b128 v[74:77], v250 offset:53248
	ds_read_b128 v[78:81], v250 offset:55296
	ds_read_b128 v[234:237], v103 offset:49152
	ds_read_b128 v[238:241], v103 offset:51200
	ds_read_b128 v[242:245], v103 offset:53248
	ds_read_b128 v[246:249], v103 offset:55296
	ds_read_b128 v[82:85], v251 offset:49152
	ds_read_b128 v[86:89], v251 offset:51200
	ds_read_b128 v[90:93], v251 offset:53248
	ds_read_b128 v[94:97], v251 offset:55296
	s_waitcnt lgkmcnt(8)
	v_mfma_f32_16x16x32_bf16 v[62:65], v[66:69], v[218:221], v[62:65]
	v_mfma_f32_16x16x32_bf16 v[46:49], v[66:69], v[222:225], v[46:49]
	v_mfma_f32_16x16x32_bf16 v[30:33], v[66:69], v[226:229], v[30:33]
	v_mfma_f32_16x16x32_bf16 v[14:17], v[66:69], v[230:233], v[14:17]
	v_mfma_f32_16x16x32_bf16 v[58:61], v[70:73], v[218:221], v[58:61]
	v_mfma_f32_16x16x32_bf16 v[42:45], v[70:73], v[222:225], v[42:45]
	v_mfma_f32_16x16x32_bf16 v[26:29], v[70:73], v[226:229], v[26:29]
	v_mfma_f32_16x16x32_bf16 v[10:13], v[70:73], v[230:233], v[10:13]
	v_mfma_f32_16x16x32_bf16 v[54:57], v[74:77], v[218:221], v[54:57]
	v_mfma_f32_16x16x32_bf16 v[38:41], v[74:77], v[222:225], v[38:41]
	v_mfma_f32_16x16x32_bf16 v[22:25], v[74:77], v[226:229], v[22:25]
	v_mfma_f32_16x16x32_bf16 v[6:9], v[74:77], v[230:233], v[6:9]
	v_mfma_f32_16x16x32_bf16 v[50:53], v[78:81], v[218:221], v[50:53]
	v_mfma_f32_16x16x32_bf16 v[34:37], v[78:81], v[222:225], v[34:37]
	v_mfma_f32_16x16x32_bf16 v[18:21], v[78:81], v[226:229], v[18:21]
	v_mfma_f32_16x16x32_bf16 v[2:5], v[78:81], v[230:233], v[2:5]
	s_waitcnt lgkmcnt(0)
	s_waitcnt vmcnt(8)
	s_barrier
	ds_read_b128 v[218:221], v102 offset:0
	ds_read_b128 v[222:225], v102 offset:2048
	ds_read_b128 v[226:229], v102 offset:4096
	ds_read_b128 v[230:233], v102 offset:6144
	v_mfma_f32_16x16x32_bf16 v[62:65], v[82:85], v[234:237], v[62:65]
	s_add_u32 m0, s4, 0xc000
	v_mfma_f32_16x16x32_bf16 v[46:49], v[82:85], v[238:241], v[46:49]
	global_load_lds_dwordx4 v98, s[6:7]
	v_mfma_f32_16x16x32_bf16 v[30:33], v[82:85], v[242:245], v[30:33]
	v_mfma_f32_16x16x32_bf16 v[14:17], v[82:85], v[246:249], v[14:17]
	v_mfma_f32_16x16x32_bf16 v[58:61], v[86:89], v[234:237], v[58:61]
	s_add_u32 m0, s4, 0xc400
	v_mfma_f32_16x16x32_bf16 v[42:45], v[86:89], v[238:241], v[42:45]
	global_load_lds_dwordx4 v99, s[6:7]
	v_mfma_f32_16x16x32_bf16 v[26:29], v[86:89], v[242:245], v[26:29]
	v_mfma_f32_16x16x32_bf16 v[10:13], v[86:89], v[246:249], v[10:13]
	v_mfma_f32_16x16x32_bf16 v[54:57], v[90:93], v[234:237], v[54:57]
	s_add_u32 m0, s4, 0xc800
	v_mfma_f32_16x16x32_bf16 v[38:41], v[90:93], v[238:241], v[38:41]
	global_load_lds_dwordx4 v100, s[6:7]
	v_mfma_f32_16x16x32_bf16 v[22:25], v[90:93], v[242:245], v[22:25]
	v_mfma_f32_16x16x32_bf16 v[6:9], v[90:93], v[246:249], v[6:9]
	v_mfma_f32_16x16x32_bf16 v[50:53], v[94:97], v[234:237], v[50:53]
	s_add_u32 m0, s4, 0xcc00
	v_mfma_f32_16x16x32_bf16 v[34:37], v[94:97], v[238:241], v[34:37]
	global_load_lds_dwordx4 v101, s[6:7]
	v_mfma_f32_16x16x32_bf16 v[18:21], v[94:97], v[242:245], v[18:21]
	v_mfma_f32_16x16x32_bf16 v[2:5], v[94:97], v[246:249], v[2:5]
	v_add_u32_e32 v98, 0x80, v98
	v_add_u32_e32 v99, 0x80, v99
	v_add_u32_e32 v100, 0x80, v100
	v_add_u32_e32 v101, 0x80, v101
	ds_read_b128 v[234:237], v103 offset:0
	ds_read_b128 v[238:241], v103 offset:2048
	ds_read_b128 v[242:245], v103 offset:4096
	ds_read_b128 v[246:249], v103 offset:6144
	s_waitcnt lgkmcnt(4)
	v_mfma_f32_16x16x32_bf16 v[106:109], v[66:69], v[218:221], v[106:109]
	s_add_u32 m0, s4, 0x10000
	v_mfma_f32_16x16x32_bf16 v[122:125], v[66:69], v[222:225], v[122:125]
	global_load_lds_dwordx4 v98, s[48:49]
	v_mfma_f32_16x16x32_bf16 v[138:141], v[66:69], v[226:229], v[138:141]
	v_mfma_f32_16x16x32_bf16 v[162:165], v[66:69], v[230:233], v[162:165]
	v_mfma_f32_16x16x32_bf16 v[110:113], v[70:73], v[218:221], v[110:113]
	s_add_u32 m0, s4, 0x10400
	v_mfma_f32_16x16x32_bf16 v[126:129], v[70:73], v[222:225], v[126:129]
	global_load_lds_dwordx4 v99, s[48:49]
	v_mfma_f32_16x16x32_bf16 v[142:145], v[70:73], v[226:229], v[142:145]
	v_mfma_f32_16x16x32_bf16 v[166:169], v[70:73], v[230:233], v[166:169]
	v_mfma_f32_16x16x32_bf16 v[114:117], v[74:77], v[218:221], v[114:117]
	s_add_u32 m0, s4, 0x10800
	v_mfma_f32_16x16x32_bf16 v[130:133], v[74:77], v[222:225], v[130:133]
	global_load_lds_dwordx4 v100, s[48:49]
	v_mfma_f32_16x16x32_bf16 v[154:157], v[74:77], v[226:229], v[154:157]
	v_mfma_f32_16x16x32_bf16 v[170:173], v[74:77], v[230:233], v[170:173]
	v_mfma_f32_16x16x32_bf16 v[118:121], v[78:81], v[218:221], v[118:121]
	s_add_u32 m0, s4, 0x10c00
	v_mfma_f32_16x16x32_bf16 v[134:137], v[78:81], v[222:225], v[134:137]
	global_load_lds_dwordx4 v101, s[48:49]
	v_mfma_f32_16x16x32_bf16 v[158:161], v[78:81], v[226:229], v[158:161]
	v_mfma_f32_16x16x32_bf16 v[174:177], v[78:81], v[230:233], v[174:177]
	s_waitcnt lgkmcnt(0)
	s_waitcnt vmcnt(8)
	s_barrier
	ds_read_b128 v[218:221], v102 offset:16384
	ds_read_b128 v[222:225], v102 offset:18432
	ds_read_b128 v[226:229], v102 offset:20480
	ds_read_b128 v[230:233], v102 offset:22528
	ds_read_b128 v[66:69], v104 offset:32768
	ds_read_b128 v[70:73], v104 offset:34816
	ds_read_b128 v[74:77], v104 offset:36864
	ds_read_b128 v[78:81], v104 offset:38912
	v_mfma_f32_16x16x32_bf16 v[106:109], v[82:85], v[234:237], v[106:109]
	s_add_u32 m0, s4, 0x0
	v_mfma_f32_16x16x32_bf16 v[122:125], v[82:85], v[238:241], v[122:125]
	global_load_lds_dwordx4 v98, s[28:29]
	v_mfma_f32_16x16x32_bf16 v[138:141], v[82:85], v[242:245], v[138:141]
	v_mfma_f32_16x16x32_bf16 v[162:165], v[82:85], v[246:249], v[162:165]
	v_mfma_f32_16x16x32_bf16 v[110:113], v[86:89], v[234:237], v[110:113]
	s_add_u32 m0, s4, 0x400
	v_mfma_f32_16x16x32_bf16 v[126:129], v[86:89], v[238:241], v[126:129]
	global_load_lds_dwordx4 v99, s[28:29]
	v_mfma_f32_16x16x32_bf16 v[142:145], v[86:89], v[242:245], v[142:145]
	v_mfma_f32_16x16x32_bf16 v[166:169], v[86:89], v[246:249], v[166:169]
	v_mfma_f32_16x16x32_bf16 v[114:117], v[90:93], v[234:237], v[114:117]
	v_mfma_f32_16x16x32_bf16 v[130:133], v[90:93], v[238:241], v[130:133]
	v_mfma_f32_16x16x32_bf16 v[154:157], v[90:93], v[242:245], v[154:157]
	v_mfma_f32_16x16x32_bf16 v[170:173], v[90:93], v[246:249], v[170:173]
	v_mfma_f32_16x16x32_bf16 v[118:121], v[94:97], v[234:237], v[118:121]
	v_mfma_f32_16x16x32_bf16 v[134:137], v[94:97], v[238:241], v[134:137]
	v_mfma_f32_16x16x32_bf16 v[158:161], v[94:97], v[242:245], v[158:161]
	v_mfma_f32_16x16x32_bf16 v[174:177], v[94:97], v[246:249], v[174:177]
	ds_read_b128 v[234:237], v103 offset:16384
	ds_read_b128 v[238:241], v103 offset:18432
	ds_read_b128 v[242:245], v103 offset:20480
	ds_read_b128 v[246:249], v103 offset:22528
	ds_read_b128 v[82:85], v105 offset:32768
	ds_read_b128 v[86:89], v105 offset:34816
	ds_read_b128 v[90:93], v105 offset:36864
	ds_read_b128 v[94:97], v105 offset:38912
	s_waitcnt lgkmcnt(8)
	v_mfma_f32_16x16x32_bf16 v[62:65], v[66:69], v[218:221], v[62:65]
	s_add_u32 m0, s4, 0x800
	v_mfma_f32_16x16x32_bf16 v[46:49], v[66:69], v[222:225], v[46:49]
	global_load_lds_dwordx4 v100, s[28:29]
	v_mfma_f32_16x16x32_bf16 v[30:33], v[66:69], v[226:229], v[30:33]
	v_mfma_f32_16x16x32_bf16 v[14:17], v[66:69], v[230:233], v[14:17]
	v_mfma_f32_16x16x32_bf16 v[58:61], v[70:73], v[218:221], v[58:61]
	s_add_u32 m0, s4, 0xc00
	v_mfma_f32_16x16x32_bf16 v[42:45], v[70:73], v[222:225], v[42:45]
	global_load_lds_dwordx4 v101, s[28:29]
	v_mfma_f32_16x16x32_bf16 v[26:29], v[70:73], v[226:229], v[26:29]
	v_mfma_f32_16x16x32_bf16 v[10:13], v[70:73], v[230:233], v[10:13]
	v_mfma_f32_16x16x32_bf16 v[54:57], v[74:77], v[218:221], v[54:57]
	v_mfma_f32_16x16x32_bf16 v[38:41], v[74:77], v[222:225], v[38:41]
	v_mfma_f32_16x16x32_bf16 v[22:25], v[74:77], v[226:229], v[22:25]
	v_mfma_f32_16x16x32_bf16 v[6:9], v[74:77], v[230:233], v[6:9]
	v_mfma_f32_16x16x32_bf16 v[50:53], v[78:81], v[218:221], v[50:53]
	v_mfma_f32_16x16x32_bf16 v[34:37], v[78:81], v[222:225], v[34:37]
	v_mfma_f32_16x16x32_bf16 v[18:21], v[78:81], v[226:229], v[18:21]
	v_mfma_f32_16x16x32_bf16 v[2:5], v[78:81], v[230:233], v[2:5]
	s_waitcnt lgkmcnt(0)
	s_waitcnt vmcnt(8)
	s_barrier
	ds_read_b128 v[218:221], v102 offset:49152
	ds_read_b128 v[222:225], v102 offset:51200
	ds_read_b128 v[226:229], v102 offset:53248
	ds_read_b128 v[230:233], v102 offset:55296
	v_mfma_f32_16x16x32_bf16 v[62:65], v[82:85], v[234:237], v[62:65]
	s_add_u32 m0, s4, 0x4000
	v_mfma_f32_16x16x32_bf16 v[46:49], v[82:85], v[238:241], v[46:49]
	global_load_lds_dwordx4 v98, s[6:7]
	v_mfma_f32_16x16x32_bf16 v[30:33], v[82:85], v[242:245], v[30:33]
	v_mfma_f32_16x16x32_bf16 v[14:17], v[82:85], v[246:249], v[14:17]
	v_mfma_f32_16x16x32_bf16 v[58:61], v[86:89], v[234:237], v[58:61]
	s_add_u32 m0, s4, 0x4400
	v_mfma_f32_16x16x32_bf16 v[42:45], v[86:89], v[238:241], v[42:45]
	global_load_lds_dwordx4 v99, s[6:7]
	v_mfma_f32_16x16x32_bf16 v[26:29], v[86:89], v[242:245], v[26:29]
	v_mfma_f32_16x16x32_bf16 v[10:13], v[86:89], v[246:249], v[10:13]
	v_mfma_f32_16x16x32_bf16 v[54:57], v[90:93], v[234:237], v[54:57]
	s_add_u32 m0, s4, 0x4800
	v_mfma_f32_16x16x32_bf16 v[38:41], v[90:93], v[238:241], v[38:41]
	global_load_lds_dwordx4 v100, s[6:7]
	v_mfma_f32_16x16x32_bf16 v[22:25], v[90:93], v[242:245], v[22:25]
	v_mfma_f32_16x16x32_bf16 v[6:9], v[90:93], v[246:249], v[6:9]
	v_mfma_f32_16x16x32_bf16 v[50:53], v[94:97], v[234:237], v[50:53]
	s_add_u32 m0, s4, 0x4c00
	v_mfma_f32_16x16x32_bf16 v[34:37], v[94:97], v[238:241], v[34:37]
	global_load_lds_dwordx4 v101, s[6:7]
	v_mfma_f32_16x16x32_bf16 v[18:21], v[94:97], v[242:245], v[18:21]
	v_mfma_f32_16x16x32_bf16 v[2:5], v[94:97], v[246:249], v[2:5]
	v_add_u32_e32 v98, 0x80, v98
	v_add_u32_e32 v99, 0x80, v99
	v_add_u32_e32 v100, 0x80, v100
	v_add_u32_e32 v101, 0x80, v101
	ds_read_b128 v[234:237], v103 offset:49152
	ds_read_b128 v[238:241], v103 offset:51200
	ds_read_b128 v[242:245], v103 offset:53248
	ds_read_b128 v[246:249], v103 offset:55296
	s_waitcnt lgkmcnt(4)
	v_mfma_f32_16x16x32_bf16 v[106:109], v[66:69], v[218:221], v[106:109]
	s_add_u32 m0, s4, 0x8000
	v_mfma_f32_16x16x32_bf16 v[122:125], v[66:69], v[222:225], v[122:125]
	global_load_lds_dwordx4 v98, s[48:49]
	v_mfma_f32_16x16x32_bf16 v[138:141], v[66:69], v[226:229], v[138:141]
	v_mfma_f32_16x16x32_bf16 v[162:165], v[66:69], v[230:233], v[162:165]
	v_mfma_f32_16x16x32_bf16 v[110:113], v[70:73], v[218:221], v[110:113]
	s_add_u32 m0, s4, 0x8400
	v_mfma_f32_16x16x32_bf16 v[126:129], v[70:73], v[222:225], v[126:129]
	global_load_lds_dwordx4 v99, s[48:49]
	v_mfma_f32_16x16x32_bf16 v[142:145], v[70:73], v[226:229], v[142:145]
	v_mfma_f32_16x16x32_bf16 v[166:169], v[70:73], v[230:233], v[166:169]
	v_mfma_f32_16x16x32_bf16 v[114:117], v[74:77], v[218:221], v[114:117]
	s_add_u32 m0, s4, 0x8800
	v_mfma_f32_16x16x32_bf16 v[130:133], v[74:77], v[222:225], v[130:133]
	global_load_lds_dwordx4 v100, s[48:49]
	v_mfma_f32_16x16x32_bf16 v[154:157], v[74:77], v[226:229], v[154:157]
	v_mfma_f32_16x16x32_bf16 v[170:173], v[74:77], v[230:233], v[170:173]
	v_mfma_f32_16x16x32_bf16 v[118:121], v[78:81], v[218:221], v[118:121]
	s_add_u32 m0, s4, 0x8c00
	v_mfma_f32_16x16x32_bf16 v[134:137], v[78:81], v[222:225], v[134:137]
	global_load_lds_dwordx4 v101, s[48:49]
	v_mfma_f32_16x16x32_bf16 v[158:161], v[78:81], v[226:229], v[158:161]
	v_mfma_f32_16x16x32_bf16 v[174:177], v[78:81], v[230:233], v[174:177]
	s_waitcnt lgkmcnt(0)
	s_waitcnt vmcnt(8)
	s_barrier
	ds_read_b128 v[218:221], v102 offset:0
	ds_read_b128 v[222:225], v102 offset:2048
	ds_read_b128 v[226:229], v102 offset:4096
	ds_read_b128 v[230:233], v102 offset:6144
	ds_read_b128 v[66:69], v250 offset:49152
	ds_read_b128 v[70:73], v250 offset:51200
	ds_read_b128 v[74:77], v250 offset:53248
	ds_read_b128 v[78:81], v250 offset:55296
	v_mfma_f32_16x16x32_bf16 v[106:109], v[82:85], v[234:237], v[106:109]
	s_add_u32 m0, s4, 0xc000
	v_mfma_f32_16x16x32_bf16 v[122:125], v[82:85], v[238:241], v[122:125]
	global_load_lds_dwordx4 v98, s[28:29]
	v_mfma_f32_16x16x32_bf16 v[138:141], v[82:85], v[242:245], v[138:141]
	v_mfma_f32_16x16x32_bf16 v[162:165], v[82:85], v[246:249], v[162:165]
	v_mfma_f32_16x16x32_bf16 v[110:113], v[86:89], v[234:237], v[110:113]
	s_add_u32 m0, s4, 0xc400
	v_mfma_f32_16x16x32_bf16 v[126:129], v[86:89], v[238:241], v[126:129]
	global_load_lds_dwordx4 v99, s[28:29]
	v_mfma_f32_16x16x32_bf16 v[142:145], v[86:89], v[242:245], v[142:145]
	v_mfma_f32_16x16x32_bf16 v[166:169], v[86:89], v[246:249], v[166:169]
	v_mfma_f32_16x16x32_bf16 v[114:117], v[90:93], v[234:237], v[114:117]
	v_mfma_f32_16x16x32_bf16 v[130:133], v[90:93], v[238:241], v[130:133]
	v_mfma_f32_16x16x32_bf16 v[154:157], v[90:93], v[242:245], v[154:157]
	v_mfma_f32_16x16x32_bf16 v[170:173], v[90:93], v[246:249], v[170:173]
	v_mfma_f32_16x16x32_bf16 v[118:121], v[94:97], v[234:237], v[118:121]
	v_mfma_f32_16x16x32_bf16 v[134:137], v[94:97], v[238:241], v[134:137]
	v_mfma_f32_16x16x32_bf16 v[158:161], v[94:97], v[242:245], v[158:161]
	v_mfma_f32_16x16x32_bf16 v[174:177], v[94:97], v[246:249], v[174:177]
	ds_read_b128 v[234:237], v103 offset:0
	ds_read_b128 v[238:241], v103 offset:2048
	ds_read_b128 v[242:245], v103 offset:4096
	ds_read_b128 v[246:249], v103 offset:6144
	ds_read_b128 v[82:85], v251 offset:49152
	ds_read_b128 v[86:89], v251 offset:51200
	ds_read_b128 v[90:93], v251 offset:53248
	ds_read_b128 v[94:97], v251 offset:55296
	s_waitcnt lgkmcnt(8)
	v_mfma_f32_16x16x32_bf16 v[62:65], v[66:69], v[218:221], v[62:65]
	s_add_u32 m0, s4, 0xc800
	v_mfma_f32_16x16x32_bf16 v[46:49], v[66:69], v[222:225], v[46:49]
	global_load_lds_dwordx4 v100, s[28:29]
	v_mfma_f32_16x16x32_bf16 v[30:33], v[66:69], v[226:229], v[30:33]
	v_mfma_f32_16x16x32_bf16 v[14:17], v[66:69], v[230:233], v[14:17]
	v_mfma_f32_16x16x32_bf16 v[58:61], v[70:73], v[218:221], v[58:61]
	s_add_u32 m0, s4, 0xcc00
	v_mfma_f32_16x16x32_bf16 v[42:45], v[70:73], v[222:225], v[42:45]
	global_load_lds_dwordx4 v101, s[28:29]
	v_mfma_f32_16x16x32_bf16 v[26:29], v[70:73], v[226:229], v[26:29]
	v_mfma_f32_16x16x32_bf16 v[10:13], v[70:73], v[230:233], v[10:13]
	v_mfma_f32_16x16x32_bf16 v[54:57], v[74:77], v[218:221], v[54:57]
	v_mfma_f32_16x16x32_bf16 v[38:41], v[74:77], v[222:225], v[38:41]
	v_mfma_f32_16x16x32_bf16 v[22:25], v[74:77], v[226:229], v[22:25]
	v_mfma_f32_16x16x32_bf16 v[6:9], v[74:77], v[230:233], v[6:9]
	v_mfma_f32_16x16x32_bf16 v[50:53], v[78:81], v[218:221], v[50:53]
	v_mfma_f32_16x16x32_bf16 v[34:37], v[78:81], v[222:225], v[34:37]
	v_mfma_f32_16x16x32_bf16 v[18:21], v[78:81], v[226:229], v[18:21]
	v_mfma_f32_16x16x32_bf16 v[2:5], v[78:81], v[230:233], v[2:5]
	s_waitcnt lgkmcnt(0)
	s_waitcnt vmcnt(8)
	s_barrier
	ds_read_b128 v[218:221], v102 offset:16384
	ds_read_b128 v[222:225], v102 offset:18432
	ds_read_b128 v[226:229], v102 offset:20480
	ds_read_b128 v[230:233], v102 offset:22528
	v_mfma_f32_16x16x32_bf16 v[62:65], v[82:85], v[234:237], v[62:65]
	s_add_u32 m0, s4, 0x0
	v_mfma_f32_16x16x32_bf16 v[46:49], v[82:85], v[238:241], v[46:49]
	global_load_lds_dwordx4 v98, s[6:7]
	v_mfma_f32_16x16x32_bf16 v[30:33], v[82:85], v[242:245], v[30:33]
	v_mfma_f32_16x16x32_bf16 v[14:17], v[82:85], v[246:249], v[14:17]
	v_mfma_f32_16x16x32_bf16 v[58:61], v[86:89], v[234:237], v[58:61]
	s_add_u32 m0, s4, 0x400
	v_mfma_f32_16x16x32_bf16 v[42:45], v[86:89], v[238:241], v[42:45]
	global_load_lds_dwordx4 v99, s[6:7]
	v_mfma_f32_16x16x32_bf16 v[26:29], v[86:89], v[242:245], v[26:29]
	v_mfma_f32_16x16x32_bf16 v[10:13], v[86:89], v[246:249], v[10:13]
	v_mfma_f32_16x16x32_bf16 v[54:57], v[90:93], v[234:237], v[54:57]
	s_add_u32 m0, s4, 0x800
	v_mfma_f32_16x16x32_bf16 v[38:41], v[90:93], v[238:241], v[38:41]
	global_load_lds_dwordx4 v100, s[6:7]
	v_mfma_f32_16x16x32_bf16 v[22:25], v[90:93], v[242:245], v[22:25]
	v_mfma_f32_16x16x32_bf16 v[6:9], v[90:93], v[246:249], v[6:9]
	v_mfma_f32_16x16x32_bf16 v[50:53], v[94:97], v[234:237], v[50:53]
	s_add_u32 m0, s4, 0xc00
	v_mfma_f32_16x16x32_bf16 v[34:37], v[94:97], v[238:241], v[34:37]
	global_load_lds_dwordx4 v101, s[6:7]
	v_mfma_f32_16x16x32_bf16 v[18:21], v[94:97], v[242:245], v[18:21]
	v_mfma_f32_16x16x32_bf16 v[2:5], v[94:97], v[246:249], v[2:5]
	v_add_u32_e32 v98, 0x80, v98
	v_add_u32_e32 v99, 0x80, v99
	v_add_u32_e32 v100, 0x80, v100
	v_add_u32_e32 v101, 0x80, v101
	ds_read_b128 v[234:237], v103 offset:16384
	ds_read_b128 v[238:241], v103 offset:18432
	ds_read_b128 v[242:245], v103 offset:20480
	ds_read_b128 v[246:249], v103 offset:22528
	s_waitcnt lgkmcnt(4)
	v_mfma_f32_16x16x32_bf16 v[106:109], v[66:69], v[218:221], v[106:109]
	s_add_u32 m0, s4, 0x10000
	v_mfma_f32_16x16x32_bf16 v[122:125], v[66:69], v[222:225], v[122:125]
	global_load_lds_dwordx4 v98, s[48:49]
	v_mfma_f32_16x16x32_bf16 v[138:141], v[66:69], v[226:229], v[138:141]
	v_mfma_f32_16x16x32_bf16 v[162:165], v[66:69], v[230:233], v[162:165]
	v_mfma_f32_16x16x32_bf16 v[110:113], v[70:73], v[218:221], v[110:113]
	s_add_u32 m0, s4, 0x10400
	v_mfma_f32_16x16x32_bf16 v[126:129], v[70:73], v[222:225], v[126:129]
	global_load_lds_dwordx4 v99, s[48:49]
	v_mfma_f32_16x16x32_bf16 v[142:145], v[70:73], v[226:229], v[142:145]
	v_mfma_f32_16x16x32_bf16 v[166:169], v[70:73], v[230:233], v[166:169]
	v_mfma_f32_16x16x32_bf16 v[114:117], v[74:77], v[218:221], v[114:117]
	s_add_u32 m0, s4, 0x10800
	v_mfma_f32_16x16x32_bf16 v[130:133], v[74:77], v[222:225], v[130:133]
	global_load_lds_dwordx4 v100, s[48:49]
	v_mfma_f32_16x16x32_bf16 v[154:157], v[74:77], v[226:229], v[154:157]
	v_mfma_f32_16x16x32_bf16 v[170:173], v[74:77], v[230:233], v[170:173]
	v_mfma_f32_16x16x32_bf16 v[118:121], v[78:81], v[218:221], v[118:121]
	s_add_u32 m0, s4, 0x10c00
	v_mfma_f32_16x16x32_bf16 v[134:137], v[78:81], v[222:225], v[134:137]
	global_load_lds_dwordx4 v101, s[48:49]
	v_mfma_f32_16x16x32_bf16 v[158:161], v[78:81], v[226:229], v[158:161]
	v_mfma_f32_16x16x32_bf16 v[174:177], v[78:81], v[230:233], v[174:177]
	s_waitcnt lgkmcnt(0)
	s_waitcnt vmcnt(8)
	s_barrier
	ds_read_b128 v[218:221], v102 offset:49152
	ds_read_b128 v[222:225], v102 offset:51200
	ds_read_b128 v[226:229], v102 offset:53248
	ds_read_b128 v[230:233], v102 offset:55296
	ds_read_b128 v[66:69], v104 offset:32768
	ds_read_b128 v[70:73], v104 offset:34816
	ds_read_b128 v[74:77], v104 offset:36864
	ds_read_b128 v[78:81], v104 offset:38912
	v_mfma_f32_16x16x32_bf16 v[106:109], v[82:85], v[234:237], v[106:109]
	s_add_u32 m0, s4, 0x4000
	v_mfma_f32_16x16x32_bf16 v[122:125], v[82:85], v[238:241], v[122:125]
	global_load_lds_dwordx4 v98, s[28:29]
	v_mfma_f32_16x16x32_bf16 v[138:141], v[82:85], v[242:245], v[138:141]
	v_mfma_f32_16x16x32_bf16 v[162:165], v[82:85], v[246:249], v[162:165]
	v_mfma_f32_16x16x32_bf16 v[110:113], v[86:89], v[234:237], v[110:113]
	s_add_u32 m0, s4, 0x4400
	v_mfma_f32_16x16x32_bf16 v[126:129], v[86:89], v[238:241], v[126:129]
	global_load_lds_dwordx4 v99, s[28:29]
	v_mfma_f32_16x16x32_bf16 v[142:145], v[86:89], v[242:245], v[142:145]
	v_mfma_f32_16x16x32_bf16 v[166:169], v[86:89], v[246:249], v[166:169]
	v_mfma_f32_16x16x32_bf16 v[114:117], v[90:93], v[234:237], v[114:117]
	v_mfma_f32_16x16x32_bf16 v[130:133], v[90:93], v[238:241], v[130:133]
	v_mfma_f32_16x16x32_bf16 v[154:157], v[90:93], v[242:245], v[154:157]
	v_mfma_f32_16x16x32_bf16 v[170:173], v[90:93], v[246:249], v[170:173]
	v_mfma_f32_16x16x32_bf16 v[118:121], v[94:97], v[234:237], v[118:121]
	v_mfma_f32_16x16x32_bf16 v[134:137], v[94:97], v[238:241], v[134:137]
	v_mfma_f32_16x16x32_bf16 v[158:161], v[94:97], v[242:245], v[158:161]
	v_mfma_f32_16x16x32_bf16 v[174:177], v[94:97], v[246:249], v[174:177]
	ds_read_b128 v[234:237], v103 offset:49152
	ds_read_b128 v[238:241], v103 offset:51200
	ds_read_b128 v[242:245], v103 offset:53248
	ds_read_b128 v[246:249], v103 offset:55296
	ds_read_b128 v[82:85], v105 offset:32768
	ds_read_b128 v[86:89], v105 offset:34816
	ds_read_b128 v[90:93], v105 offset:36864
	ds_read_b128 v[94:97], v105 offset:38912
	s_waitcnt lgkmcnt(8)
	v_mfma_f32_16x16x32_bf16 v[62:65], v[66:69], v[218:221], v[62:65]
	s_add_u32 m0, s4, 0x4800
	v_mfma_f32_16x16x32_bf16 v[46:49], v[66:69], v[222:225], v[46:49]
	global_load_lds_dwordx4 v100, s[28:29]
	v_mfma_f32_16x16x32_bf16 v[30:33], v[66:69], v[226:229], v[30:33]
	v_mfma_f32_16x16x32_bf16 v[14:17], v[66:69], v[230:233], v[14:17]
	v_mfma_f32_16x16x32_bf16 v[58:61], v[70:73], v[218:221], v[58:61]
	s_add_u32 m0, s4, 0x4c00
	v_mfma_f32_16x16x32_bf16 v[42:45], v[70:73], v[222:225], v[42:45]
	global_load_lds_dwordx4 v101, s[28:29]
	v_mfma_f32_16x16x32_bf16 v[26:29], v[70:73], v[226:229], v[26:29]
	v_mfma_f32_16x16x32_bf16 v[10:13], v[70:73], v[230:233], v[10:13]
	v_mfma_f32_16x16x32_bf16 v[54:57], v[74:77], v[218:221], v[54:57]
	v_mfma_f32_16x16x32_bf16 v[38:41], v[74:77], v[222:225], v[38:41]
	v_mfma_f32_16x16x32_bf16 v[22:25], v[74:77], v[226:229], v[22:25]
	v_mfma_f32_16x16x32_bf16 v[6:9], v[74:77], v[230:233], v[6:9]
	v_mfma_f32_16x16x32_bf16 v[50:53], v[78:81], v[218:221], v[50:53]
	v_mfma_f32_16x16x32_bf16 v[34:37], v[78:81], v[222:225], v[34:37]
	v_mfma_f32_16x16x32_bf16 v[18:21], v[78:81], v[226:229], v[18:21]
	v_mfma_f32_16x16x32_bf16 v[2:5], v[78:81], v[230:233], v[2:5]
	s_waitcnt lgkmcnt(0)
	s_waitcnt vmcnt(8)
	s_barrier
	ds_read_b128 v[218:221], v102 offset:0
	ds_read_b128 v[222:225], v102 offset:2048
	ds_read_b128 v[226:229], v102 offset:4096
	ds_read_b128 v[230:233], v102 offset:6144
	v_mfma_f32_16x16x32_bf16 v[62:65], v[82:85], v[234:237], v[62:65]
	s_add_u32 m0, s4, 0xc000
	v_mfma_f32_16x16x32_bf16 v[46:49], v[82:85], v[238:241], v[46:49]
	global_load_lds_dwordx4 v98, s[6:7]
	v_mfma_f32_16x16x32_bf16 v[30:33], v[82:85], v[242:245], v[30:33]
	v_mfma_f32_16x16x32_bf16 v[14:17], v[82:85], v[246:249], v[14:17]
	v_mfma_f32_16x16x32_bf16 v[58:61], v[86:89], v[234:237], v[58:61]
	s_add_u32 m0, s4, 0xc400
	v_mfma_f32_16x16x32_bf16 v[42:45], v[86:89], v[238:241], v[42:45]
	global_load_lds_dwordx4 v99, s[6:7]
	v_mfma_f32_16x16x32_bf16 v[26:29], v[86:89], v[242:245], v[26:29]
	v_mfma_f32_16x16x32_bf16 v[10:13], v[86:89], v[246:249], v[10:13]
	v_mfma_f32_16x16x32_bf16 v[54:57], v[90:93], v[234:237], v[54:57]
	s_add_u32 m0, s4, 0xc800
	v_mfma_f32_16x16x32_bf16 v[38:41], v[90:93], v[238:241], v[38:41]
	global_load_lds_dwordx4 v100, s[6:7]
	v_mfma_f32_16x16x32_bf16 v[22:25], v[90:93], v[242:245], v[22:25]
	v_mfma_f32_16x16x32_bf16 v[6:9], v[90:93], v[246:249], v[6:9]
	v_mfma_f32_16x16x32_bf16 v[50:53], v[94:97], v[234:237], v[50:53]
	s_add_u32 m0, s4, 0xcc00
	v_mfma_f32_16x16x32_bf16 v[34:37], v[94:97], v[238:241], v[34:37]
	global_load_lds_dwordx4 v101, s[6:7]
	v_mfma_f32_16x16x32_bf16 v[18:21], v[94:97], v[242:245], v[18:21]
	v_mfma_f32_16x16x32_bf16 v[2:5], v[94:97], v[246:249], v[2:5]
	v_add_u32_e32 v98, 0x80, v98
	v_add_u32_e32 v99, 0x80, v99
	v_add_u32_e32 v100, 0x80, v100
	v_add_u32_e32 v101, 0x80, v101
	ds_read_b128 v[234:237], v103 offset:0
	ds_read_b128 v[238:241], v103 offset:2048
	ds_read_b128 v[242:245], v103 offset:4096
	ds_read_b128 v[246:249], v103 offset:6144
	s_waitcnt lgkmcnt(4)
	v_mfma_f32_16x16x32_bf16 v[106:109], v[66:69], v[218:221], v[106:109]
	s_add_u32 m0, s4, 0x8000
	v_mfma_f32_16x16x32_bf16 v[122:125], v[66:69], v[222:225], v[122:125]
	global_load_lds_dwordx4 v98, s[48:49]
	v_mfma_f32_16x16x32_bf16 v[138:141], v[66:69], v[226:229], v[138:141]
	v_mfma_f32_16x16x32_bf16 v[162:165], v[66:69], v[230:233], v[162:165]
	v_mfma_f32_16x16x32_bf16 v[110:113], v[70:73], v[218:221], v[110:113]
	s_add_u32 m0, s4, 0x8400
	v_mfma_f32_16x16x32_bf16 v[126:129], v[70:73], v[222:225], v[126:129]
	global_load_lds_dwordx4 v99, s[48:49]
	v_mfma_f32_16x16x32_bf16 v[142:145], v[70:73], v[226:229], v[142:145]
	v_mfma_f32_16x16x32_bf16 v[166:169], v[70:73], v[230:233], v[166:169]
	v_mfma_f32_16x16x32_bf16 v[114:117], v[74:77], v[218:221], v[114:117]
	s_add_u32 m0, s4, 0x8800
	v_mfma_f32_16x16x32_bf16 v[130:133], v[74:77], v[222:225], v[130:133]
	global_load_lds_dwordx4 v100, s[48:49]
	v_mfma_f32_16x16x32_bf16 v[154:157], v[74:77], v[226:229], v[154:157]
	v_mfma_f32_16x16x32_bf16 v[170:173], v[74:77], v[230:233], v[170:173]
	v_mfma_f32_16x16x32_bf16 v[118:121], v[78:81], v[218:221], v[118:121]
	s_add_u32 m0, s4, 0x8c00
	v_mfma_f32_16x16x32_bf16 v[134:137], v[78:81], v[222:225], v[134:137]
	global_load_lds_dwordx4 v101, s[48:49]
	v_mfma_f32_16x16x32_bf16 v[158:161], v[78:81], v[226:229], v[158:161]
	v_mfma_f32_16x16x32_bf16 v[174:177], v[78:81], v[230:233], v[174:177]
	s_waitcnt lgkmcnt(0)
	s_waitcnt vmcnt(8)
	s_barrier
	ds_read_b128 v[218:221], v102 offset:16384
	ds_read_b128 v[222:225], v102 offset:18432
	ds_read_b128 v[226:229], v102 offset:20480
	ds_read_b128 v[230:233], v102 offset:22528
	ds_read_b128 v[66:69], v250 offset:49152
	ds_read_b128 v[70:73], v250 offset:51200
	ds_read_b128 v[74:77], v250 offset:53248
	ds_read_b128 v[78:81], v250 offset:55296
	v_mfma_f32_16x16x32_bf16 v[106:109], v[82:85], v[234:237], v[106:109]
	s_add_u32 m0, s4, 0x0
	v_mfma_f32_16x16x32_bf16 v[122:125], v[82:85], v[238:241], v[122:125]
	global_load_lds_dwordx4 v98, s[28:29]
	v_mfma_f32_16x16x32_bf16 v[138:141], v[82:85], v[242:245], v[138:141]
	v_mfma_f32_16x16x32_bf16 v[162:165], v[82:85], v[246:249], v[162:165]
	v_mfma_f32_16x16x32_bf16 v[110:113], v[86:89], v[234:237], v[110:113]
	s_add_u32 m0, s4, 0x400
	v_mfma_f32_16x16x32_bf16 v[126:129], v[86:89], v[238:241], v[126:129]
	global_load_lds_dwordx4 v99, s[28:29]
	v_mfma_f32_16x16x32_bf16 v[142:145], v[86:89], v[242:245], v[142:145]
	v_mfma_f32_16x16x32_bf16 v[166:169], v[86:89], v[246:249], v[166:169]
	v_mfma_f32_16x16x32_bf16 v[114:117], v[90:93], v[234:237], v[114:117]
	v_mfma_f32_16x16x32_bf16 v[130:133], v[90:93], v[238:241], v[130:133]
	v_mfma_f32_16x16x32_bf16 v[154:157], v[90:93], v[242:245], v[154:157]
	v_mfma_f32_16x16x32_bf16 v[170:173], v[90:93], v[246:249], v[170:173]
	v_mfma_f32_16x16x32_bf16 v[118:121], v[94:97], v[234:237], v[118:121]
	v_mfma_f32_16x16x32_bf16 v[134:137], v[94:97], v[238:241], v[134:137]
	v_mfma_f32_16x16x32_bf16 v[158:161], v[94:97], v[242:245], v[158:161]
	v_mfma_f32_16x16x32_bf16 v[174:177], v[94:97], v[246:249], v[174:177]
	ds_read_b128 v[234:237], v103 offset:16384
	ds_read_b128 v[238:241], v103 offset:18432
	ds_read_b128 v[242:245], v103 offset:20480
	ds_read_b128 v[246:249], v103 offset:22528
	ds_read_b128 v[82:85], v251 offset:49152
	ds_read_b128 v[86:89], v251 offset:51200
	ds_read_b128 v[90:93], v251 offset:53248
	ds_read_b128 v[94:97], v251 offset:55296
	s_waitcnt lgkmcnt(8)
	v_mfma_f32_16x16x32_bf16 v[62:65], v[66:69], v[218:221], v[62:65]
	s_add_u32 m0, s4, 0x800
	v_mfma_f32_16x16x32_bf16 v[46:49], v[66:69], v[222:225], v[46:49]
	global_load_lds_dwordx4 v100, s[28:29]
	v_mfma_f32_16x16x32_bf16 v[30:33], v[66:69], v[226:229], v[30:33]
	v_mfma_f32_16x16x32_bf16 v[14:17], v[66:69], v[230:233], v[14:17]
	v_mfma_f32_16x16x32_bf16 v[58:61], v[70:73], v[218:221], v[58:61]
	s_add_u32 m0, s4, 0xc00
	v_mfma_f32_16x16x32_bf16 v[42:45], v[70:73], v[222:225], v[42:45]
	global_load_lds_dwordx4 v101, s[28:29]
	v_mfma_f32_16x16x32_bf16 v[26:29], v[70:73], v[226:229], v[26:29]
	v_mfma_f32_16x16x32_bf16 v[10:13], v[70:73], v[230:233], v[10:13]
	v_mfma_f32_16x16x32_bf16 v[54:57], v[74:77], v[218:221], v[54:57]
	v_mfma_f32_16x16x32_bf16 v[38:41], v[74:77], v[222:225], v[38:41]
	v_mfma_f32_16x16x32_bf16 v[22:25], v[74:77], v[226:229], v[22:25]
	v_mfma_f32_16x16x32_bf16 v[6:9], v[74:77], v[230:233], v[6:9]
	v_mfma_f32_16x16x32_bf16 v[50:53], v[78:81], v[218:221], v[50:53]
	v_mfma_f32_16x16x32_bf16 v[34:37], v[78:81], v[222:225], v[34:37]
	v_mfma_f32_16x16x32_bf16 v[18:21], v[78:81], v[226:229], v[18:21]
	v_mfma_f32_16x16x32_bf16 v[2:5], v[78:81], v[230:233], v[2:5]
	s_waitcnt lgkmcnt(0)
	s_waitcnt vmcnt(8)
	s_barrier
	ds_read_b128 v[218:221], v102 offset:49152
	ds_read_b128 v[222:225], v102 offset:51200
	ds_read_b128 v[226:229], v102 offset:53248
	ds_read_b128 v[230:233], v102 offset:55296
	v_mfma_f32_16x16x32_bf16 v[62:65], v[82:85], v[234:237], v[62:65]
	s_add_u32 m0, s4, 0x4000
	v_mfma_f32_16x16x32_bf16 v[46:49], v[82:85], v[238:241], v[46:49]
	global_load_lds_dwordx4 v98, s[6:7]
	v_mfma_f32_16x16x32_bf16 v[30:33], v[82:85], v[242:245], v[30:33]
	v_mfma_f32_16x16x32_bf16 v[14:17], v[82:85], v[246:249], v[14:17]
	v_mfma_f32_16x16x32_bf16 v[58:61], v[86:89], v[234:237], v[58:61]
	s_add_u32 m0, s4, 0x4400
	v_mfma_f32_16x16x32_bf16 v[42:45], v[86:89], v[238:241], v[42:45]
	global_load_lds_dwordx4 v99, s[6:7]
	v_mfma_f32_16x16x32_bf16 v[26:29], v[86:89], v[242:245], v[26:29]
	v_mfma_f32_16x16x32_bf16 v[10:13], v[86:89], v[246:249], v[10:13]
	v_mfma_f32_16x16x32_bf16 v[54:57], v[90:93], v[234:237], v[54:57]
	s_add_u32 m0, s4, 0x4800
	v_mfma_f32_16x16x32_bf16 v[38:41], v[90:93], v[238:241], v[38:41]
	global_load_lds_dwordx4 v100, s[6:7]
	v_mfma_f32_16x16x32_bf16 v[22:25], v[90:93], v[242:245], v[22:25]
	v_mfma_f32_16x16x32_bf16 v[6:9], v[90:93], v[246:249], v[6:9]
	v_mfma_f32_16x16x32_bf16 v[50:53], v[94:97], v[234:237], v[50:53]
	s_add_u32 m0, s4, 0x4c00
	v_mfma_f32_16x16x32_bf16 v[34:37], v[94:97], v[238:241], v[34:37]
	global_load_lds_dwordx4 v101, s[6:7]
	v_mfma_f32_16x16x32_bf16 v[18:21], v[94:97], v[242:245], v[18:21]
	v_mfma_f32_16x16x32_bf16 v[2:5], v[94:97], v[246:249], v[2:5]
	v_add_u32_e32 v98, 0x80, v98
	v_add_u32_e32 v99, 0x80, v99
	v_add_u32_e32 v100, 0x80, v100
	v_add_u32_e32 v101, 0x80, v101
	ds_read_b128 v[234:237], v103 offset:49152
	ds_read_b128 v[238:241], v103 offset:51200
	ds_read_b128 v[242:245], v103 offset:53248
	ds_read_b128 v[246:249], v103 offset:55296
	s_waitcnt lgkmcnt(4)
	v_mfma_f32_16x16x32_bf16 v[106:109], v[66:69], v[218:221], v[106:109]
	s_add_u32 m0, s4, 0x10000
	v_mfma_f32_16x16x32_bf16 v[122:125], v[66:69], v[222:225], v[122:125]
	global_load_lds_dwordx4 v98, s[48:49]
	v_mfma_f32_16x16x32_bf16 v[138:141], v[66:69], v[226:229], v[138:141]
	v_mfma_f32_16x16x32_bf16 v[162:165], v[66:69], v[230:233], v[162:165]
	v_mfma_f32_16x16x32_bf16 v[110:113], v[70:73], v[218:221], v[110:113]
	s_add_u32 m0, s4, 0x10400
	v_mfma_f32_16x16x32_bf16 v[126:129], v[70:73], v[222:225], v[126:129]
	global_load_lds_dwordx4 v99, s[48:49]
	v_mfma_f32_16x16x32_bf16 v[142:145], v[70:73], v[226:229], v[142:145]
	v_mfma_f32_16x16x32_bf16 v[166:169], v[70:73], v[230:233], v[166:169]
	v_mfma_f32_16x16x32_bf16 v[114:117], v[74:77], v[218:221], v[114:117]
	s_add_u32 m0, s4, 0x10800
	v_mfma_f32_16x16x32_bf16 v[130:133], v[74:77], v[222:225], v[130:133]
	global_load_lds_dwordx4 v100, s[48:49]
	v_mfma_f32_16x16x32_bf16 v[154:157], v[74:77], v[226:229], v[154:157]
	v_mfma_f32_16x16x32_bf16 v[170:173], v[74:77], v[230:233], v[170:173]
	v_mfma_f32_16x16x32_bf16 v[118:121], v[78:81], v[218:221], v[118:121]
	s_add_u32 m0, s4, 0x10c00
	v_mfma_f32_16x16x32_bf16 v[134:137], v[78:81], v[222:225], v[134:137]
	global_load_lds_dwordx4 v101, s[48:49]
	v_mfma_f32_16x16x32_bf16 v[158:161], v[78:81], v[226:229], v[158:161]
	v_mfma_f32_16x16x32_bf16 v[174:177], v[78:81], v[230:233], v[174:177]
	s_waitcnt lgkmcnt(0)
	s_waitcnt vmcnt(8)
	s_barrier
	ds_read_b128 v[218:221], v102 offset:0
	ds_read_b128 v[222:225], v102 offset:2048
	ds_read_b128 v[226:229], v102 offset:4096
	ds_read_b128 v[230:233], v102 offset:6144
	ds_read_b128 v[66:69], v104 offset:32768
	ds_read_b128 v[70:73], v104 offset:34816
	ds_read_b128 v[74:77], v104 offset:36864
	ds_read_b128 v[78:81], v104 offset:38912
	v_mfma_f32_16x16x32_bf16 v[106:109], v[82:85], v[234:237], v[106:109]
	s_add_u32 m0, s4, 0xc000
	v_mfma_f32_16x16x32_bf16 v[122:125], v[82:85], v[238:241], v[122:125]
	global_load_lds_dwordx4 v98, s[28:29]
	v_mfma_f32_16x16x32_bf16 v[138:141], v[82:85], v[242:245], v[138:141]
	v_mfma_f32_16x16x32_bf16 v[162:165], v[82:85], v[246:249], v[162:165]
	v_mfma_f32_16x16x32_bf16 v[110:113], v[86:89], v[234:237], v[110:113]
	s_add_u32 m0, s4, 0xc400
	v_mfma_f32_16x16x32_bf16 v[126:129], v[86:89], v[238:241], v[126:129]
	global_load_lds_dwordx4 v99, s[28:29]
	v_mfma_f32_16x16x32_bf16 v[142:145], v[86:89], v[242:245], v[142:145]
	v_mfma_f32_16x16x32_bf16 v[166:169], v[86:89], v[246:249], v[166:169]
	v_mfma_f32_16x16x32_bf16 v[114:117], v[90:93], v[234:237], v[114:117]
	v_mfma_f32_16x16x32_bf16 v[130:133], v[90:93], v[238:241], v[130:133]
	v_mfma_f32_16x16x32_bf16 v[154:157], v[90:93], v[242:245], v[154:157]
	v_mfma_f32_16x16x32_bf16 v[170:173], v[90:93], v[246:249], v[170:173]
	v_mfma_f32_16x16x32_bf16 v[118:121], v[94:97], v[234:237], v[118:121]
	v_mfma_f32_16x16x32_bf16 v[134:137], v[94:97], v[238:241], v[134:137]
	v_mfma_f32_16x16x32_bf16 v[158:161], v[94:97], v[242:245], v[158:161]
	v_mfma_f32_16x16x32_bf16 v[174:177], v[94:97], v[246:249], v[174:177]
	ds_read_b128 v[234:237], v103 offset:0
	ds_read_b128 v[238:241], v103 offset:2048
	ds_read_b128 v[242:245], v103 offset:4096
	ds_read_b128 v[246:249], v103 offset:6144
	ds_read_b128 v[82:85], v105 offset:32768
	ds_read_b128 v[86:89], v105 offset:34816
	ds_read_b128 v[90:93], v105 offset:36864
	ds_read_b128 v[94:97], v105 offset:38912
	s_waitcnt lgkmcnt(8)
	v_mfma_f32_16x16x32_bf16 v[62:65], v[66:69], v[218:221], v[62:65]
	s_add_u32 m0, s4, 0xc800
	v_mfma_f32_16x16x32_bf16 v[46:49], v[66:69], v[222:225], v[46:49]
	global_load_lds_dwordx4 v100, s[28:29]
	v_mfma_f32_16x16x32_bf16 v[30:33], v[66:69], v[226:229], v[30:33]
	v_mfma_f32_16x16x32_bf16 v[14:17], v[66:69], v[230:233], v[14:17]
	v_mfma_f32_16x16x32_bf16 v[58:61], v[70:73], v[218:221], v[58:61]
	s_add_u32 m0, s4, 0xcc00
	v_mfma_f32_16x16x32_bf16 v[42:45], v[70:73], v[222:225], v[42:45]
	global_load_lds_dwordx4 v101, s[28:29]
	v_mfma_f32_16x16x32_bf16 v[26:29], v[70:73], v[226:229], v[26:29]
	v_mfma_f32_16x16x32_bf16 v[10:13], v[70:73], v[230:233], v[10:13]
	v_mfma_f32_16x16x32_bf16 v[54:57], v[74:77], v[218:221], v[54:57]
	v_mfma_f32_16x16x32_bf16 v[38:41], v[74:77], v[222:225], v[38:41]
	v_mfma_f32_16x16x32_bf16 v[22:25], v[74:77], v[226:229], v[22:25]
	v_mfma_f32_16x16x32_bf16 v[6:9], v[74:77], v[230:233], v[6:9]
	v_mfma_f32_16x16x32_bf16 v[50:53], v[78:81], v[218:221], v[50:53]
	v_mfma_f32_16x16x32_bf16 v[34:37], v[78:81], v[222:225], v[34:37]
	v_mfma_f32_16x16x32_bf16 v[18:21], v[78:81], v[226:229], v[18:21]
	v_mfma_f32_16x16x32_bf16 v[2:5], v[78:81], v[230:233], v[2:5]
	s_waitcnt lgkmcnt(0)
	s_waitcnt vmcnt(8)
	s_barrier
	ds_read_b128 v[218:221], v102 offset:16384
	ds_read_b128 v[222:225], v102 offset:18432
	ds_read_b128 v[226:229], v102 offset:20480
	ds_read_b128 v[230:233], v102 offset:22528
	v_mfma_f32_16x16x32_bf16 v[62:65], v[82:85], v[234:237], v[62:65]
	s_add_u32 m0, s4, 0x0
	v_mfma_f32_16x16x32_bf16 v[46:49], v[82:85], v[238:241], v[46:49]
	global_load_lds_dwordx4 v98, s[6:7]
	v_mfma_f32_16x16x32_bf16 v[30:33], v[82:85], v[242:245], v[30:33]
	v_mfma_f32_16x16x32_bf16 v[14:17], v[82:85], v[246:249], v[14:17]
	v_mfma_f32_16x16x32_bf16 v[58:61], v[86:89], v[234:237], v[58:61]
	s_add_u32 m0, s4, 0x400
	v_mfma_f32_16x16x32_bf16 v[42:45], v[86:89], v[238:241], v[42:45]
	global_load_lds_dwordx4 v99, s[6:7]
	v_mfma_f32_16x16x32_bf16 v[26:29], v[86:89], v[242:245], v[26:29]
	v_mfma_f32_16x16x32_bf16 v[10:13], v[86:89], v[246:249], v[10:13]
	v_mfma_f32_16x16x32_bf16 v[54:57], v[90:93], v[234:237], v[54:57]
	s_add_u32 m0, s4, 0x800
	v_mfma_f32_16x16x32_bf16 v[38:41], v[90:93], v[238:241], v[38:41]
	global_load_lds_dwordx4 v100, s[6:7]
	v_mfma_f32_16x16x32_bf16 v[22:25], v[90:93], v[242:245], v[22:25]
	v_mfma_f32_16x16x32_bf16 v[6:9], v[90:93], v[246:249], v[6:9]
	v_mfma_f32_16x16x32_bf16 v[50:53], v[94:97], v[234:237], v[50:53]
	s_add_u32 m0, s4, 0xc00
	v_mfma_f32_16x16x32_bf16 v[34:37], v[94:97], v[238:241], v[34:37]
	global_load_lds_dwordx4 v101, s[6:7]
	v_mfma_f32_16x16x32_bf16 v[18:21], v[94:97], v[242:245], v[18:21]
	v_mfma_f32_16x16x32_bf16 v[2:5], v[94:97], v[246:249], v[2:5]
	v_add_u32_e32 v98, 0x80, v98
	v_add_u32_e32 v99, 0x80, v99
	v_add_u32_e32 v100, 0x80, v100
	v_add_u32_e32 v101, 0x80, v101
	ds_read_b128 v[234:237], v103 offset:16384
	ds_read_b128 v[238:241], v103 offset:18432
	ds_read_b128 v[242:245], v103 offset:20480
	ds_read_b128 v[246:249], v103 offset:22528
	s_waitcnt lgkmcnt(4)
	v_mfma_f32_16x16x32_bf16 v[106:109], v[66:69], v[218:221], v[106:109]
	s_add_u32 m0, s4, 0x8000
	v_mfma_f32_16x16x32_bf16 v[122:125], v[66:69], v[222:225], v[122:125]
	global_load_lds_dwordx4 v98, s[48:49]
	v_mfma_f32_16x16x32_bf16 v[138:141], v[66:69], v[226:229], v[138:141]
	v_mfma_f32_16x16x32_bf16 v[162:165], v[66:69], v[230:233], v[162:165]
	v_mfma_f32_16x16x32_bf16 v[110:113], v[70:73], v[218:221], v[110:113]
	s_add_u32 m0, s4, 0x8400
	v_mfma_f32_16x16x32_bf16 v[126:129], v[70:73], v[222:225], v[126:129]
	global_load_lds_dwordx4 v99, s[48:49]
	v_mfma_f32_16x16x32_bf16 v[142:145], v[70:73], v[226:229], v[142:145]
	v_mfma_f32_16x16x32_bf16 v[166:169], v[70:73], v[230:233], v[166:169]
	v_mfma_f32_16x16x32_bf16 v[114:117], v[74:77], v[218:221], v[114:117]
	s_add_u32 m0, s4, 0x8800
	v_mfma_f32_16x16x32_bf16 v[130:133], v[74:77], v[222:225], v[130:133]
	global_load_lds_dwordx4 v100, s[48:49]
	v_mfma_f32_16x16x32_bf16 v[154:157], v[74:77], v[226:229], v[154:157]
	v_mfma_f32_16x16x32_bf16 v[170:173], v[74:77], v[230:233], v[170:173]
	v_mfma_f32_16x16x32_bf16 v[118:121], v[78:81], v[218:221], v[118:121]
	s_add_u32 m0, s4, 0x8c00
	v_mfma_f32_16x16x32_bf16 v[134:137], v[78:81], v[222:225], v[134:137]
	global_load_lds_dwordx4 v101, s[48:49]
	v_mfma_f32_16x16x32_bf16 v[158:161], v[78:81], v[226:229], v[158:161]
	v_mfma_f32_16x16x32_bf16 v[174:177], v[78:81], v[230:233], v[174:177]
	s_waitcnt lgkmcnt(0)
	s_waitcnt vmcnt(8)
	s_barrier
	ds_read_b128 v[218:221], v102 offset:49152
	ds_read_b128 v[222:225], v102 offset:51200
	ds_read_b128 v[226:229], v102 offset:53248
	ds_read_b128 v[230:233], v102 offset:55296
	ds_read_b128 v[66:69], v250 offset:49152
	ds_read_b128 v[70:73], v250 offset:51200
	ds_read_b128 v[74:77], v250 offset:53248
	ds_read_b128 v[78:81], v250 offset:55296
	v_mfma_f32_16x16x32_bf16 v[106:109], v[82:85], v[234:237], v[106:109]
	s_add_u32 m0, s4, 0x4000
	v_mfma_f32_16x16x32_bf16 v[122:125], v[82:85], v[238:241], v[122:125]
	global_load_lds_dwordx4 v98, s[28:29]
	v_mfma_f32_16x16x32_bf16 v[138:141], v[82:85], v[242:245], v[138:141]
	v_mfma_f32_16x16x32_bf16 v[162:165], v[82:85], v[246:249], v[162:165]
	v_mfma_f32_16x16x32_bf16 v[110:113], v[86:89], v[234:237], v[110:113]
	s_add_u32 m0, s4, 0x4400
	v_mfma_f32_16x16x32_bf16 v[126:129], v[86:89], v[238:241], v[126:129]
	global_load_lds_dwordx4 v99, s[28:29]
	v_mfma_f32_16x16x32_bf16 v[142:145], v[86:89], v[242:245], v[142:145]
	v_mfma_f32_16x16x32_bf16 v[166:169], v[86:89], v[246:249], v[166:169]
	v_mfma_f32_16x16x32_bf16 v[114:117], v[90:93], v[234:237], v[114:117]
	v_mfma_f32_16x16x32_bf16 v[130:133], v[90:93], v[238:241], v[130:133]
	v_mfma_f32_16x16x32_bf16 v[154:157], v[90:93], v[242:245], v[154:157]
	v_mfma_f32_16x16x32_bf16 v[170:173], v[90:93], v[246:249], v[170:173]
	v_mfma_f32_16x16x32_bf16 v[118:121], v[94:97], v[234:237], v[118:121]
	v_mfma_f32_16x16x32_bf16 v[134:137], v[94:97], v[238:241], v[134:137]
	v_mfma_f32_16x16x32_bf16 v[158:161], v[94:97], v[242:245], v[158:161]
	v_mfma_f32_16x16x32_bf16 v[174:177], v[94:97], v[246:249], v[174:177]
	ds_read_b128 v[234:237], v103 offset:49152
	ds_read_b128 v[238:241], v103 offset:51200
	ds_read_b128 v[242:245], v103 offset:53248
	ds_read_b128 v[246:249], v103 offset:55296
	ds_read_b128 v[82:85], v251 offset:49152
	ds_read_b128 v[86:89], v251 offset:51200
	ds_read_b128 v[90:93], v251 offset:53248
	ds_read_b128 v[94:97], v251 offset:55296
	s_waitcnt lgkmcnt(8)
	v_mfma_f32_16x16x32_bf16 v[62:65], v[66:69], v[218:221], v[62:65]
	s_add_u32 m0, s4, 0x4800
	v_mfma_f32_16x16x32_bf16 v[46:49], v[66:69], v[222:225], v[46:49]
	global_load_lds_dwordx4 v100, s[28:29]
	v_mfma_f32_16x16x32_bf16 v[30:33], v[66:69], v[226:229], v[30:33]
	v_mfma_f32_16x16x32_bf16 v[14:17], v[66:69], v[230:233], v[14:17]
	v_mfma_f32_16x16x32_bf16 v[58:61], v[70:73], v[218:221], v[58:61]
	s_add_u32 m0, s4, 0x4c00
	v_mfma_f32_16x16x32_bf16 v[42:45], v[70:73], v[222:225], v[42:45]
	global_load_lds_dwordx4 v101, s[28:29]
	v_mfma_f32_16x16x32_bf16 v[26:29], v[70:73], v[226:229], v[26:29]
	v_mfma_f32_16x16x32_bf16 v[10:13], v[70:73], v[230:233], v[10:13]
	v_mfma_f32_16x16x32_bf16 v[54:57], v[74:77], v[218:221], v[54:57]
	v_mfma_f32_16x16x32_bf16 v[38:41], v[74:77], v[222:225], v[38:41]
	v_mfma_f32_16x16x32_bf16 v[22:25], v[74:77], v[226:229], v[22:25]
	v_mfma_f32_16x16x32_bf16 v[6:9], v[74:77], v[230:233], v[6:9]
	v_mfma_f32_16x16x32_bf16 v[50:53], v[78:81], v[218:221], v[50:53]
	v_mfma_f32_16x16x32_bf16 v[34:37], v[78:81], v[222:225], v[34:37]
	v_mfma_f32_16x16x32_bf16 v[18:21], v[78:81], v[226:229], v[18:21]
	v_mfma_f32_16x16x32_bf16 v[2:5], v[78:81], v[230:233], v[2:5]
	s_waitcnt lgkmcnt(0)
	s_waitcnt vmcnt(8)
	s_barrier
	ds_read_b128 v[218:221], v102 offset:0
	ds_read_b128 v[222:225], v102 offset:2048
	ds_read_b128 v[226:229], v102 offset:4096
	ds_read_b128 v[230:233], v102 offset:6144
	v_mfma_f32_16x16x32_bf16 v[62:65], v[82:85], v[234:237], v[62:65]
	s_add_u32 m0, s4, 0xc000
	v_mfma_f32_16x16x32_bf16 v[46:49], v[82:85], v[238:241], v[46:49]
	global_load_lds_dwordx4 v98, s[6:7]
	v_mfma_f32_16x16x32_bf16 v[30:33], v[82:85], v[242:245], v[30:33]
	v_mfma_f32_16x16x32_bf16 v[14:17], v[82:85], v[246:249], v[14:17]
	v_mfma_f32_16x16x32_bf16 v[58:61], v[86:89], v[234:237], v[58:61]
	s_add_u32 m0, s4, 0xc400
	v_mfma_f32_16x16x32_bf16 v[42:45], v[86:89], v[238:241], v[42:45]
	global_load_lds_dwordx4 v99, s[6:7]
	v_mfma_f32_16x16x32_bf16 v[26:29], v[86:89], v[242:245], v[26:29]
	v_mfma_f32_16x16x32_bf16 v[10:13], v[86:89], v[246:249], v[10:13]
	v_mfma_f32_16x16x32_bf16 v[54:57], v[90:93], v[234:237], v[54:57]
	s_add_u32 m0, s4, 0xc800
	v_mfma_f32_16x16x32_bf16 v[38:41], v[90:93], v[238:241], v[38:41]
	global_load_lds_dwordx4 v100, s[6:7]
	v_mfma_f32_16x16x32_bf16 v[22:25], v[90:93], v[242:245], v[22:25]
	v_mfma_f32_16x16x32_bf16 v[6:9], v[90:93], v[246:249], v[6:9]
	v_mfma_f32_16x16x32_bf16 v[50:53], v[94:97], v[234:237], v[50:53]
	s_add_u32 m0, s4, 0xcc00
	v_mfma_f32_16x16x32_bf16 v[34:37], v[94:97], v[238:241], v[34:37]
	global_load_lds_dwordx4 v101, s[6:7]
	v_mfma_f32_16x16x32_bf16 v[18:21], v[94:97], v[242:245], v[18:21]
	v_mfma_f32_16x16x32_bf16 v[2:5], v[94:97], v[246:249], v[2:5]
	v_add_u32_e32 v98, 0x80, v98
	v_add_u32_e32 v99, 0x80, v99
	v_add_u32_e32 v100, 0x80, v100
	v_add_u32_e32 v101, 0x80, v101
	ds_read_b128 v[234:237], v103 offset:0
	ds_read_b128 v[238:241], v103 offset:2048
	ds_read_b128 v[242:245], v103 offset:4096
	ds_read_b128 v[246:249], v103 offset:6144
	s_waitcnt lgkmcnt(4)
	v_mfma_f32_16x16x32_bf16 v[106:109], v[66:69], v[218:221], v[106:109]
	s_add_u32 m0, s4, 0x10000
	v_mfma_f32_16x16x32_bf16 v[122:125], v[66:69], v[222:225], v[122:125]
	global_load_lds_dwordx4 v98, s[48:49]
	v_mfma_f32_16x16x32_bf16 v[138:141], v[66:69], v[226:229], v[138:141]
	v_mfma_f32_16x16x32_bf16 v[162:165], v[66:69], v[230:233], v[162:165]
	v_mfma_f32_16x16x32_bf16 v[110:113], v[70:73], v[218:221], v[110:113]
	s_add_u32 m0, s4, 0x10400
	v_mfma_f32_16x16x32_bf16 v[126:129], v[70:73], v[222:225], v[126:129]
	global_load_lds_dwordx4 v99, s[48:49]
	v_mfma_f32_16x16x32_bf16 v[142:145], v[70:73], v[226:229], v[142:145]
	v_mfma_f32_16x16x32_bf16 v[166:169], v[70:73], v[230:233], v[166:169]
	v_mfma_f32_16x16x32_bf16 v[114:117], v[74:77], v[218:221], v[114:117]
	s_add_u32 m0, s4, 0x10800
	v_mfma_f32_16x16x32_bf16 v[130:133], v[74:77], v[222:225], v[130:133]
	global_load_lds_dwordx4 v100, s[48:49]
	v_mfma_f32_16x16x32_bf16 v[154:157], v[74:77], v[226:229], v[154:157]
	v_mfma_f32_16x16x32_bf16 v[170:173], v[74:77], v[230:233], v[170:173]
	v_mfma_f32_16x16x32_bf16 v[118:121], v[78:81], v[218:221], v[118:121]
	s_add_u32 m0, s4, 0x10c00
	v_mfma_f32_16x16x32_bf16 v[134:137], v[78:81], v[222:225], v[134:137]
	global_load_lds_dwordx4 v101, s[48:49]
	v_mfma_f32_16x16x32_bf16 v[158:161], v[78:81], v[226:229], v[158:161]
	v_mfma_f32_16x16x32_bf16 v[174:177], v[78:81], v[230:233], v[174:177]
	s_waitcnt lgkmcnt(0)
	s_waitcnt vmcnt(8)
	s_barrier
	ds_read_b128 v[218:221], v102 offset:16384
	ds_read_b128 v[222:225], v102 offset:18432
	ds_read_b128 v[226:229], v102 offset:20480
	ds_read_b128 v[230:233], v102 offset:22528
	ds_read_b128 v[66:69], v104 offset:32768
	ds_read_b128 v[70:73], v104 offset:34816
	ds_read_b128 v[74:77], v104 offset:36864
	ds_read_b128 v[78:81], v104 offset:38912
	v_mfma_f32_16x16x32_bf16 v[106:109], v[82:85], v[234:237], v[106:109]
	s_add_u32 m0, s4, 0x0
	v_mfma_f32_16x16x32_bf16 v[122:125], v[82:85], v[238:241], v[122:125]
	global_load_lds_dwordx4 v98, s[28:29]
	v_mfma_f32_16x16x32_bf16 v[138:141], v[82:85], v[242:245], v[138:141]
	v_mfma_f32_16x16x32_bf16 v[162:165], v[82:85], v[246:249], v[162:165]
	v_mfma_f32_16x16x32_bf16 v[110:113], v[86:89], v[234:237], v[110:113]
	s_add_u32 m0, s4, 0x400
	v_mfma_f32_16x16x32_bf16 v[126:129], v[86:89], v[238:241], v[126:129]
	global_load_lds_dwordx4 v99, s[28:29]
	v_mfma_f32_16x16x32_bf16 v[142:145], v[86:89], v[242:245], v[142:145]
	v_mfma_f32_16x16x32_bf16 v[166:169], v[86:89], v[246:249], v[166:169]
	v_mfma_f32_16x16x32_bf16 v[114:117], v[90:93], v[234:237], v[114:117]
	v_mfma_f32_16x16x32_bf16 v[130:133], v[90:93], v[238:241], v[130:133]
	v_mfma_f32_16x16x32_bf16 v[154:157], v[90:93], v[242:245], v[154:157]
	v_mfma_f32_16x16x32_bf16 v[170:173], v[90:93], v[246:249], v[170:173]
	v_mfma_f32_16x16x32_bf16 v[118:121], v[94:97], v[234:237], v[118:121]
	v_mfma_f32_16x16x32_bf16 v[134:137], v[94:97], v[238:241], v[134:137]
	v_mfma_f32_16x16x32_bf16 v[158:161], v[94:97], v[242:245], v[158:161]
	v_mfma_f32_16x16x32_bf16 v[174:177], v[94:97], v[246:249], v[174:177]
	ds_read_b128 v[234:237], v103 offset:16384
	ds_read_b128 v[238:241], v103 offset:18432
	ds_read_b128 v[242:245], v103 offset:20480
	ds_read_b128 v[246:249], v103 offset:22528
	ds_read_b128 v[82:85], v105 offset:32768
	ds_read_b128 v[86:89], v105 offset:34816
	ds_read_b128 v[90:93], v105 offset:36864
	ds_read_b128 v[94:97], v105 offset:38912
	s_waitcnt lgkmcnt(8)
	v_mfma_f32_16x16x32_bf16 v[62:65], v[66:69], v[218:221], v[62:65]
	s_add_u32 m0, s4, 0x800
	v_mfma_f32_16x16x32_bf16 v[46:49], v[66:69], v[222:225], v[46:49]
	global_load_lds_dwordx4 v100, s[28:29]
	v_mfma_f32_16x16x32_bf16 v[30:33], v[66:69], v[226:229], v[30:33]
	v_mfma_f32_16x16x32_bf16 v[14:17], v[66:69], v[230:233], v[14:17]
	v_mfma_f32_16x16x32_bf16 v[58:61], v[70:73], v[218:221], v[58:61]
	s_add_u32 m0, s4, 0xc00
	v_mfma_f32_16x16x32_bf16 v[42:45], v[70:73], v[222:225], v[42:45]
	global_load_lds_dwordx4 v101, s[28:29]
	v_mfma_f32_16x16x32_bf16 v[26:29], v[70:73], v[226:229], v[26:29]
	v_mfma_f32_16x16x32_bf16 v[10:13], v[70:73], v[230:233], v[10:13]
	v_mfma_f32_16x16x32_bf16 v[54:57], v[74:77], v[218:221], v[54:57]
	v_mfma_f32_16x16x32_bf16 v[38:41], v[74:77], v[222:225], v[38:41]
	v_mfma_f32_16x16x32_bf16 v[22:25], v[74:77], v[226:229], v[22:25]
	v_mfma_f32_16x16x32_bf16 v[6:9], v[74:77], v[230:233], v[6:9]
	v_mfma_f32_16x16x32_bf16 v[50:53], v[78:81], v[218:221], v[50:53]
	v_mfma_f32_16x16x32_bf16 v[34:37], v[78:81], v[222:225], v[34:37]
	v_mfma_f32_16x16x32_bf16 v[18:21], v[78:81], v[226:229], v[18:21]
	v_mfma_f32_16x16x32_bf16 v[2:5], v[78:81], v[230:233], v[2:5]
	s_waitcnt lgkmcnt(0)
	s_waitcnt vmcnt(8)
	s_barrier
	ds_read_b128 v[218:221], v102 offset:49152
	ds_read_b128 v[222:225], v102 offset:51200
	ds_read_b128 v[226:229], v102 offset:53248
	ds_read_b128 v[230:233], v102 offset:55296
	v_mfma_f32_16x16x32_bf16 v[62:65], v[82:85], v[234:237], v[62:65]
	s_add_u32 m0, s4, 0x4000
	v_mfma_f32_16x16x32_bf16 v[46:49], v[82:85], v[238:241], v[46:49]
	global_load_lds_dwordx4 v98, s[6:7]
	v_mfma_f32_16x16x32_bf16 v[30:33], v[82:85], v[242:245], v[30:33]
	v_mfma_f32_16x16x32_bf16 v[14:17], v[82:85], v[246:249], v[14:17]
	v_mfma_f32_16x16x32_bf16 v[58:61], v[86:89], v[234:237], v[58:61]
	s_add_u32 m0, s4, 0x4400
	v_mfma_f32_16x16x32_bf16 v[42:45], v[86:89], v[238:241], v[42:45]
	global_load_lds_dwordx4 v99, s[6:7]
	v_mfma_f32_16x16x32_bf16 v[26:29], v[86:89], v[242:245], v[26:29]
	v_mfma_f32_16x16x32_bf16 v[10:13], v[86:89], v[246:249], v[10:13]
	v_mfma_f32_16x16x32_bf16 v[54:57], v[90:93], v[234:237], v[54:57]
	s_add_u32 m0, s4, 0x4800
	v_mfma_f32_16x16x32_bf16 v[38:41], v[90:93], v[238:241], v[38:41]
	global_load_lds_dwordx4 v100, s[6:7]
	v_mfma_f32_16x16x32_bf16 v[22:25], v[90:93], v[242:245], v[22:25]
	v_mfma_f32_16x16x32_bf16 v[6:9], v[90:93], v[246:249], v[6:9]
	v_mfma_f32_16x16x32_bf16 v[50:53], v[94:97], v[234:237], v[50:53]
	s_add_u32 m0, s4, 0x4c00
	v_mfma_f32_16x16x32_bf16 v[34:37], v[94:97], v[238:241], v[34:37]
	global_load_lds_dwordx4 v101, s[6:7]
	v_mfma_f32_16x16x32_bf16 v[18:21], v[94:97], v[242:245], v[18:21]
	v_mfma_f32_16x16x32_bf16 v[2:5], v[94:97], v[246:249], v[2:5]
	v_add_u32_e32 v98, 0x80, v98
	v_add_u32_e32 v99, 0x80, v99
	v_add_u32_e32 v100, 0x80, v100
	v_add_u32_e32 v101, 0x80, v101
	ds_read_b128 v[234:237], v103 offset:49152
	ds_read_b128 v[238:241], v103 offset:51200
	ds_read_b128 v[242:245], v103 offset:53248
	ds_read_b128 v[246:249], v103 offset:55296
	s_waitcnt lgkmcnt(4)
	v_mfma_f32_16x16x32_bf16 v[106:109], v[66:69], v[218:221], v[106:109]
	s_add_u32 m0, s4, 0x8000
	v_mfma_f32_16x16x32_bf16 v[122:125], v[66:69], v[222:225], v[122:125]
	global_load_lds_dwordx4 v98, s[48:49]
	v_mfma_f32_16x16x32_bf16 v[138:141], v[66:69], v[226:229], v[138:141]
	v_mfma_f32_16x16x32_bf16 v[162:165], v[66:69], v[230:233], v[162:165]
	v_mfma_f32_16x16x32_bf16 v[110:113], v[70:73], v[218:221], v[110:113]
	s_add_u32 m0, s4, 0x8400
	v_mfma_f32_16x16x32_bf16 v[126:129], v[70:73], v[222:225], v[126:129]
	global_load_lds_dwordx4 v99, s[48:49]
	v_mfma_f32_16x16x32_bf16 v[142:145], v[70:73], v[226:229], v[142:145]
	v_mfma_f32_16x16x32_bf16 v[166:169], v[70:73], v[230:233], v[166:169]
	v_mfma_f32_16x16x32_bf16 v[114:117], v[74:77], v[218:221], v[114:117]
	s_add_u32 m0, s4, 0x8800
	v_mfma_f32_16x16x32_bf16 v[130:133], v[74:77], v[222:225], v[130:133]
	global_load_lds_dwordx4 v100, s[48:49]
	v_mfma_f32_16x16x32_bf16 v[154:157], v[74:77], v[226:229], v[154:157]
	v_mfma_f32_16x16x32_bf16 v[170:173], v[74:77], v[230:233], v[170:173]
	v_mfma_f32_16x16x32_bf16 v[118:121], v[78:81], v[218:221], v[118:121]
	s_add_u32 m0, s4, 0x8c00
	v_mfma_f32_16x16x32_bf16 v[134:137], v[78:81], v[222:225], v[134:137]
	global_load_lds_dwordx4 v101, s[48:49]
	v_mfma_f32_16x16x32_bf16 v[158:161], v[78:81], v[226:229], v[158:161]
	v_mfma_f32_16x16x32_bf16 v[174:177], v[78:81], v[230:233], v[174:177]
	s_waitcnt lgkmcnt(0)
	s_waitcnt vmcnt(8)
	s_barrier
	ds_read_b128 v[218:221], v102 offset:0
	ds_read_b128 v[222:225], v102 offset:2048
	ds_read_b128 v[226:229], v102 offset:4096
	ds_read_b128 v[230:233], v102 offset:6144
	ds_read_b128 v[66:69], v250 offset:49152
	ds_read_b128 v[70:73], v250 offset:51200
	ds_read_b128 v[74:77], v250 offset:53248
	ds_read_b128 v[78:81], v250 offset:55296
	v_mfma_f32_16x16x32_bf16 v[106:109], v[82:85], v[234:237], v[106:109]
	s_add_u32 m0, s4, 0xc000
	v_mfma_f32_16x16x32_bf16 v[122:125], v[82:85], v[238:241], v[122:125]
	global_load_lds_dwordx4 v98, s[28:29]
	v_mfma_f32_16x16x32_bf16 v[138:141], v[82:85], v[242:245], v[138:141]
	v_mfma_f32_16x16x32_bf16 v[162:165], v[82:85], v[246:249], v[162:165]
	v_mfma_f32_16x16x32_bf16 v[110:113], v[86:89], v[234:237], v[110:113]
	s_add_u32 m0, s4, 0xc400
	v_mfma_f32_16x16x32_bf16 v[126:129], v[86:89], v[238:241], v[126:129]
	global_load_lds_dwordx4 v99, s[28:29]
	v_mfma_f32_16x16x32_bf16 v[142:145], v[86:89], v[242:245], v[142:145]
	v_mfma_f32_16x16x32_bf16 v[166:169], v[86:89], v[246:249], v[166:169]
	v_mfma_f32_16x16x32_bf16 v[114:117], v[90:93], v[234:237], v[114:117]
	v_mfma_f32_16x16x32_bf16 v[130:133], v[90:93], v[238:241], v[130:133]
	v_mfma_f32_16x16x32_bf16 v[154:157], v[90:93], v[242:245], v[154:157]
	v_mfma_f32_16x16x32_bf16 v[170:173], v[90:93], v[246:249], v[170:173]
	v_mfma_f32_16x16x32_bf16 v[118:121], v[94:97], v[234:237], v[118:121]
	v_mfma_f32_16x16x32_bf16 v[134:137], v[94:97], v[238:241], v[134:137]
	v_mfma_f32_16x16x32_bf16 v[158:161], v[94:97], v[242:245], v[158:161]
	v_mfma_f32_16x16x32_bf16 v[174:177], v[94:97], v[246:249], v[174:177]
	ds_read_b128 v[234:237], v103 offset:0
	ds_read_b128 v[238:241], v103 offset:2048
	ds_read_b128 v[242:245], v103 offset:4096
	ds_read_b128 v[246:249], v103 offset:6144
	ds_read_b128 v[82:85], v251 offset:49152
	ds_read_b128 v[86:89], v251 offset:51200
	ds_read_b128 v[90:93], v251 offset:53248
	ds_read_b128 v[94:97], v251 offset:55296
	s_waitcnt lgkmcnt(8)
	v_mfma_f32_16x16x32_bf16 v[62:65], v[66:69], v[218:221], v[62:65]
	s_add_u32 m0, s4, 0xc800
	v_mfma_f32_16x16x32_bf16 v[46:49], v[66:69], v[222:225], v[46:49]
	global_load_lds_dwordx4 v100, s[28:29]
	v_mfma_f32_16x16x32_bf16 v[30:33], v[66:69], v[226:229], v[30:33]
	v_mfma_f32_16x16x32_bf16 v[14:17], v[66:69], v[230:233], v[14:17]
	v_mfma_f32_16x16x32_bf16 v[58:61], v[70:73], v[218:221], v[58:61]
	s_add_u32 m0, s4, 0xcc00
	v_mfma_f32_16x16x32_bf16 v[42:45], v[70:73], v[222:225], v[42:45]
	global_load_lds_dwordx4 v101, s[28:29]
	v_mfma_f32_16x16x32_bf16 v[26:29], v[70:73], v[226:229], v[26:29]
	v_mfma_f32_16x16x32_bf16 v[10:13], v[70:73], v[230:233], v[10:13]
	v_mfma_f32_16x16x32_bf16 v[54:57], v[74:77], v[218:221], v[54:57]
	v_mfma_f32_16x16x32_bf16 v[38:41], v[74:77], v[222:225], v[38:41]
	v_mfma_f32_16x16x32_bf16 v[22:25], v[74:77], v[226:229], v[22:25]
	v_mfma_f32_16x16x32_bf16 v[6:9], v[74:77], v[230:233], v[6:9]
	v_mfma_f32_16x16x32_bf16 v[50:53], v[78:81], v[218:221], v[50:53]
	v_mfma_f32_16x16x32_bf16 v[34:37], v[78:81], v[222:225], v[34:37]
	v_mfma_f32_16x16x32_bf16 v[18:21], v[78:81], v[226:229], v[18:21]
	v_mfma_f32_16x16x32_bf16 v[2:5], v[78:81], v[230:233], v[2:5]
	s_waitcnt lgkmcnt(0)
	s_waitcnt vmcnt(8)
	s_barrier
	ds_read_b128 v[218:221], v102 offset:16384
	ds_read_b128 v[222:225], v102 offset:18432
	ds_read_b128 v[226:229], v102 offset:20480
	ds_read_b128 v[230:233], v102 offset:22528
	v_mfma_f32_16x16x32_bf16 v[62:65], v[82:85], v[234:237], v[62:65]
	s_add_u32 m0, s4, 0x0
	v_mfma_f32_16x16x32_bf16 v[46:49], v[82:85], v[238:241], v[46:49]
	global_load_lds_dwordx4 v98, s[6:7]
	v_mfma_f32_16x16x32_bf16 v[30:33], v[82:85], v[242:245], v[30:33]
	v_mfma_f32_16x16x32_bf16 v[14:17], v[82:85], v[246:249], v[14:17]
	v_mfma_f32_16x16x32_bf16 v[58:61], v[86:89], v[234:237], v[58:61]
	s_add_u32 m0, s4, 0x400
	v_mfma_f32_16x16x32_bf16 v[42:45], v[86:89], v[238:241], v[42:45]
	global_load_lds_dwordx4 v99, s[6:7]
	v_mfma_f32_16x16x32_bf16 v[26:29], v[86:89], v[242:245], v[26:29]
	v_mfma_f32_16x16x32_bf16 v[10:13], v[86:89], v[246:249], v[10:13]
	v_mfma_f32_16x16x32_bf16 v[54:57], v[90:93], v[234:237], v[54:57]
	s_add_u32 m0, s4, 0x800
	v_mfma_f32_16x16x32_bf16 v[38:41], v[90:93], v[238:241], v[38:41]
	global_load_lds_dwordx4 v100, s[6:7]
	v_mfma_f32_16x16x32_bf16 v[22:25], v[90:93], v[242:245], v[22:25]
	v_mfma_f32_16x16x32_bf16 v[6:9], v[90:93], v[246:249], v[6:9]
	v_mfma_f32_16x16x32_bf16 v[50:53], v[94:97], v[234:237], v[50:53]
	s_add_u32 m0, s4, 0xc00
	v_mfma_f32_16x16x32_bf16 v[34:37], v[94:97], v[238:241], v[34:37]
	global_load_lds_dwordx4 v101, s[6:7]
	v_mfma_f32_16x16x32_bf16 v[18:21], v[94:97], v[242:245], v[18:21]
	v_mfma_f32_16x16x32_bf16 v[2:5], v[94:97], v[246:249], v[2:5]
	v_add_u32_e32 v98, 0x80, v98
	v_add_u32_e32 v99, 0x80, v99
	v_add_u32_e32 v100, 0x80, v100
	v_add_u32_e32 v101, 0x80, v101
	ds_read_b128 v[234:237], v103 offset:16384
	ds_read_b128 v[238:241], v103 offset:18432
	ds_read_b128 v[242:245], v103 offset:20480
	ds_read_b128 v[246:249], v103 offset:22528
	s_waitcnt lgkmcnt(4)
	v_mfma_f32_16x16x32_bf16 v[106:109], v[66:69], v[218:221], v[106:109]
	s_add_u32 m0, s4, 0x10000
	v_mfma_f32_16x16x32_bf16 v[122:125], v[66:69], v[222:225], v[122:125]
	global_load_lds_dwordx4 v98, s[48:49]
	v_mfma_f32_16x16x32_bf16 v[138:141], v[66:69], v[226:229], v[138:141]
	v_mfma_f32_16x16x32_bf16 v[162:165], v[66:69], v[230:233], v[162:165]
	v_mfma_f32_16x16x32_bf16 v[110:113], v[70:73], v[218:221], v[110:113]
	s_add_u32 m0, s4, 0x10400
	v_mfma_f32_16x16x32_bf16 v[126:129], v[70:73], v[222:225], v[126:129]
	global_load_lds_dwordx4 v99, s[48:49]
	v_mfma_f32_16x16x32_bf16 v[142:145], v[70:73], v[226:229], v[142:145]
	v_mfma_f32_16x16x32_bf16 v[166:169], v[70:73], v[230:233], v[166:169]
	v_mfma_f32_16x16x32_bf16 v[114:117], v[74:77], v[218:221], v[114:117]
	s_add_u32 m0, s4, 0x10800
	v_mfma_f32_16x16x32_bf16 v[130:133], v[74:77], v[222:225], v[130:133]
	global_load_lds_dwordx4 v100, s[48:49]
	v_mfma_f32_16x16x32_bf16 v[154:157], v[74:77], v[226:229], v[154:157]
	v_mfma_f32_16x16x32_bf16 v[170:173], v[74:77], v[230:233], v[170:173]
	v_mfma_f32_16x16x32_bf16 v[118:121], v[78:81], v[218:221], v[118:121]
	s_add_u32 m0, s4, 0x10c00
	v_mfma_f32_16x16x32_bf16 v[134:137], v[78:81], v[222:225], v[134:137]
	global_load_lds_dwordx4 v101, s[48:49]
	v_mfma_f32_16x16x32_bf16 v[158:161], v[78:81], v[226:229], v[158:161]
	v_mfma_f32_16x16x32_bf16 v[174:177], v[78:81], v[230:233], v[174:177]
	s_waitcnt lgkmcnt(0)
	s_waitcnt vmcnt(8)
	s_barrier
	ds_read_b128 v[218:221], v102 offset:49152
	ds_read_b128 v[222:225], v102 offset:51200
	ds_read_b128 v[226:229], v102 offset:53248
	ds_read_b128 v[230:233], v102 offset:55296
	ds_read_b128 v[66:69], v104 offset:32768
	ds_read_b128 v[70:73], v104 offset:34816
	ds_read_b128 v[74:77], v104 offset:36864
	ds_read_b128 v[78:81], v104 offset:38912
	v_mfma_f32_16x16x32_bf16 v[106:109], v[82:85], v[234:237], v[106:109]
	s_add_u32 m0, s4, 0x4000
	v_mfma_f32_16x16x32_bf16 v[122:125], v[82:85], v[238:241], v[122:125]
	global_load_lds_dwordx4 v98, s[28:29]
	v_mfma_f32_16x16x32_bf16 v[138:141], v[82:85], v[242:245], v[138:141]
	v_mfma_f32_16x16x32_bf16 v[162:165], v[82:85], v[246:249], v[162:165]
	v_mfma_f32_16x16x32_bf16 v[110:113], v[86:89], v[234:237], v[110:113]
	s_add_u32 m0, s4, 0x4400
	v_mfma_f32_16x16x32_bf16 v[126:129], v[86:89], v[238:241], v[126:129]
	global_load_lds_dwordx4 v99, s[28:29]
	v_mfma_f32_16x16x32_bf16 v[142:145], v[86:89], v[242:245], v[142:145]
	v_mfma_f32_16x16x32_bf16 v[166:169], v[86:89], v[246:249], v[166:169]
	v_mfma_f32_16x16x32_bf16 v[114:117], v[90:93], v[234:237], v[114:117]
	v_mfma_f32_16x16x32_bf16 v[130:133], v[90:93], v[238:241], v[130:133]
	v_mfma_f32_16x16x32_bf16 v[154:157], v[90:93], v[242:245], v[154:157]
	v_mfma_f32_16x16x32_bf16 v[170:173], v[90:93], v[246:249], v[170:173]
	v_mfma_f32_16x16x32_bf16 v[118:121], v[94:97], v[234:237], v[118:121]
	v_mfma_f32_16x16x32_bf16 v[134:137], v[94:97], v[238:241], v[134:137]
	v_mfma_f32_16x16x32_bf16 v[158:161], v[94:97], v[242:245], v[158:161]
	v_mfma_f32_16x16x32_bf16 v[174:177], v[94:97], v[246:249], v[174:177]
	ds_read_b128 v[234:237], v103 offset:49152
	ds_read_b128 v[238:241], v103 offset:51200
	ds_read_b128 v[242:245], v103 offset:53248
	ds_read_b128 v[246:249], v103 offset:55296
	ds_read_b128 v[82:85], v105 offset:32768
	ds_read_b128 v[86:89], v105 offset:34816
	ds_read_b128 v[90:93], v105 offset:36864
	ds_read_b128 v[94:97], v105 offset:38912
	s_waitcnt lgkmcnt(8)
	v_mfma_f32_16x16x32_bf16 v[62:65], v[66:69], v[218:221], v[62:65]
	s_add_u32 m0, s4, 0x4800
	v_mfma_f32_16x16x32_bf16 v[46:49], v[66:69], v[222:225], v[46:49]
	global_load_lds_dwordx4 v100, s[28:29]
	v_mfma_f32_16x16x32_bf16 v[30:33], v[66:69], v[226:229], v[30:33]
	v_mfma_f32_16x16x32_bf16 v[14:17], v[66:69], v[230:233], v[14:17]
	v_mfma_f32_16x16x32_bf16 v[58:61], v[70:73], v[218:221], v[58:61]
	s_add_u32 m0, s4, 0x4c00
	v_mfma_f32_16x16x32_bf16 v[42:45], v[70:73], v[222:225], v[42:45]
	global_load_lds_dwordx4 v101, s[28:29]
	v_mfma_f32_16x16x32_bf16 v[26:29], v[70:73], v[226:229], v[26:29]
	v_mfma_f32_16x16x32_bf16 v[10:13], v[70:73], v[230:233], v[10:13]
	v_mfma_f32_16x16x32_bf16 v[54:57], v[74:77], v[218:221], v[54:57]
	v_mfma_f32_16x16x32_bf16 v[38:41], v[74:77], v[222:225], v[38:41]
	v_mfma_f32_16x16x32_bf16 v[22:25], v[74:77], v[226:229], v[22:25]
	v_mfma_f32_16x16x32_bf16 v[6:9], v[74:77], v[230:233], v[6:9]
	v_mfma_f32_16x16x32_bf16 v[50:53], v[78:81], v[218:221], v[50:53]
	v_mfma_f32_16x16x32_bf16 v[34:37], v[78:81], v[222:225], v[34:37]
	v_mfma_f32_16x16x32_bf16 v[18:21], v[78:81], v[226:229], v[18:21]
	v_mfma_f32_16x16x32_bf16 v[2:5], v[78:81], v[230:233], v[2:5]
	s_waitcnt lgkmcnt(0)
	s_waitcnt vmcnt(8)
	s_barrier
	ds_read_b128 v[218:221], v102 offset:0
	ds_read_b128 v[222:225], v102 offset:2048
	ds_read_b128 v[226:229], v102 offset:4096
	ds_read_b128 v[230:233], v102 offset:6144
	v_mfma_f32_16x16x32_bf16 v[62:65], v[82:85], v[234:237], v[62:65]
	s_add_u32 m0, s4, 0xc000
	v_mfma_f32_16x16x32_bf16 v[46:49], v[82:85], v[238:241], v[46:49]
	global_load_lds_dwordx4 v98, s[6:7]
	v_mfma_f32_16x16x32_bf16 v[30:33], v[82:85], v[242:245], v[30:33]
	v_mfma_f32_16x16x32_bf16 v[14:17], v[82:85], v[246:249], v[14:17]
	v_mfma_f32_16x16x32_bf16 v[58:61], v[86:89], v[234:237], v[58:61]
	s_add_u32 m0, s4, 0xc400
	v_mfma_f32_16x16x32_bf16 v[42:45], v[86:89], v[238:241], v[42:45]
	global_load_lds_dwordx4 v99, s[6:7]
	v_mfma_f32_16x16x32_bf16 v[26:29], v[86:89], v[242:245], v[26:29]
	v_mfma_f32_16x16x32_bf16 v[10:13], v[86:89], v[246:249], v[10:13]
	v_mfma_f32_16x16x32_bf16 v[54:57], v[90:93], v[234:237], v[54:57]
	s_add_u32 m0, s4, 0xc800
	v_mfma_f32_16x16x32_bf16 v[38:41], v[90:93], v[238:241], v[38:41]
	global_load_lds_dwordx4 v100, s[6:7]
	v_mfma_f32_16x16x32_bf16 v[22:25], v[90:93], v[242:245], v[22:25]
	v_mfma_f32_16x16x32_bf16 v[6:9], v[90:93], v[246:249], v[6:9]
	v_mfma_f32_16x16x32_bf16 v[50:53], v[94:97], v[234:237], v[50:53]
	s_add_u32 m0, s4, 0xcc00
	v_mfma_f32_16x16x32_bf16 v[34:37], v[94:97], v[238:241], v[34:37]
	global_load_lds_dwordx4 v101, s[6:7]
	v_mfma_f32_16x16x32_bf16 v[18:21], v[94:97], v[242:245], v[18:21]
	v_mfma_f32_16x16x32_bf16 v[2:5], v[94:97], v[246:249], v[2:5]
	v_add_u32_e32 v98, 0x80, v98
	v_add_u32_e32 v99, 0x80, v99
	v_add_u32_e32 v100, 0x80, v100
	v_add_u32_e32 v101, 0x80, v101
	ds_read_b128 v[234:237], v103 offset:0
	ds_read_b128 v[238:241], v103 offset:2048
	ds_read_b128 v[242:245], v103 offset:4096
	ds_read_b128 v[246:249], v103 offset:6144
	s_waitcnt lgkmcnt(4)
	v_mfma_f32_16x16x32_bf16 v[106:109], v[66:69], v[218:221], v[106:109]
	s_add_u32 m0, s4, 0x8000
	v_mfma_f32_16x16x32_bf16 v[122:125], v[66:69], v[222:225], v[122:125]
	global_load_lds_dwordx4 v98, s[48:49]
	v_mfma_f32_16x16x32_bf16 v[138:141], v[66:69], v[226:229], v[138:141]
	v_mfma_f32_16x16x32_bf16 v[162:165], v[66:69], v[230:233], v[162:165]
	v_mfma_f32_16x16x32_bf16 v[110:113], v[70:73], v[218:221], v[110:113]
	s_add_u32 m0, s4, 0x8400
	v_mfma_f32_16x16x32_bf16 v[126:129], v[70:73], v[222:225], v[126:129]
	global_load_lds_dwordx4 v99, s[48:49]
	v_mfma_f32_16x16x32_bf16 v[142:145], v[70:73], v[226:229], v[142:145]
	v_mfma_f32_16x16x32_bf16 v[166:169], v[70:73], v[230:233], v[166:169]
	v_mfma_f32_16x16x32_bf16 v[114:117], v[74:77], v[218:221], v[114:117]
	s_add_u32 m0, s4, 0x8800
	v_mfma_f32_16x16x32_bf16 v[130:133], v[74:77], v[222:225], v[130:133]
	global_load_lds_dwordx4 v100, s[48:49]
	v_mfma_f32_16x16x32_bf16 v[154:157], v[74:77], v[226:229], v[154:157]
	v_mfma_f32_16x16x32_bf16 v[170:173], v[74:77], v[230:233], v[170:173]
	v_mfma_f32_16x16x32_bf16 v[118:121], v[78:81], v[218:221], v[118:121]
	s_add_u32 m0, s4, 0x8c00
	v_mfma_f32_16x16x32_bf16 v[134:137], v[78:81], v[222:225], v[134:137]
	global_load_lds_dwordx4 v101, s[48:49]
	v_mfma_f32_16x16x32_bf16 v[158:161], v[78:81], v[226:229], v[158:161]
	v_mfma_f32_16x16x32_bf16 v[174:177], v[78:81], v[230:233], v[174:177]
	s_waitcnt lgkmcnt(0)
	s_waitcnt vmcnt(8)
	s_barrier
	ds_read_b128 v[218:221], v102 offset:16384
	ds_read_b128 v[222:225], v102 offset:18432
	ds_read_b128 v[226:229], v102 offset:20480
	ds_read_b128 v[230:233], v102 offset:22528
	ds_read_b128 v[66:69], v250 offset:49152
	ds_read_b128 v[70:73], v250 offset:51200
	ds_read_b128 v[74:77], v250 offset:53248
	ds_read_b128 v[78:81], v250 offset:55296
	v_mfma_f32_16x16x32_bf16 v[106:109], v[82:85], v[234:237], v[106:109]
	s_add_u32 m0, s4, 0x0
	v_mfma_f32_16x16x32_bf16 v[122:125], v[82:85], v[238:241], v[122:125]
	global_load_lds_dwordx4 v98, s[28:29]
	v_mfma_f32_16x16x32_bf16 v[138:141], v[82:85], v[242:245], v[138:141]
	v_mfma_f32_16x16x32_bf16 v[162:165], v[82:85], v[246:249], v[162:165]
	v_mfma_f32_16x16x32_bf16 v[110:113], v[86:89], v[234:237], v[110:113]
	s_add_u32 m0, s4, 0x400
	v_mfma_f32_16x16x32_bf16 v[126:129], v[86:89], v[238:241], v[126:129]
	global_load_lds_dwordx4 v99, s[28:29]
	v_mfma_f32_16x16x32_bf16 v[142:145], v[86:89], v[242:245], v[142:145]
	v_mfma_f32_16x16x32_bf16 v[166:169], v[86:89], v[246:249], v[166:169]
	v_mfma_f32_16x16x32_bf16 v[114:117], v[90:93], v[234:237], v[114:117]
	v_mfma_f32_16x16x32_bf16 v[130:133], v[90:93], v[238:241], v[130:133]
	v_mfma_f32_16x16x32_bf16 v[154:157], v[90:93], v[242:245], v[154:157]
	v_mfma_f32_16x16x32_bf16 v[170:173], v[90:93], v[246:249], v[170:173]
	v_mfma_f32_16x16x32_bf16 v[118:121], v[94:97], v[234:237], v[118:121]
	v_mfma_f32_16x16x32_bf16 v[134:137], v[94:97], v[238:241], v[134:137]
	v_mfma_f32_16x16x32_bf16 v[158:161], v[94:97], v[242:245], v[158:161]
	v_mfma_f32_16x16x32_bf16 v[174:177], v[94:97], v[246:249], v[174:177]
	ds_read_b128 v[234:237], v103 offset:16384
	ds_read_b128 v[238:241], v103 offset:18432
	ds_read_b128 v[242:245], v103 offset:20480
	ds_read_b128 v[246:249], v103 offset:22528
	ds_read_b128 v[82:85], v251 offset:49152
	ds_read_b128 v[86:89], v251 offset:51200
	ds_read_b128 v[90:93], v251 offset:53248
	ds_read_b128 v[94:97], v251 offset:55296
	s_waitcnt lgkmcnt(8)
	v_mfma_f32_16x16x32_bf16 v[62:65], v[66:69], v[218:221], v[62:65]
	s_add_u32 m0, s4, 0x800
	v_mfma_f32_16x16x32_bf16 v[46:49], v[66:69], v[222:225], v[46:49]
	global_load_lds_dwordx4 v100, s[28:29]
	v_mfma_f32_16x16x32_bf16 v[30:33], v[66:69], v[226:229], v[30:33]
	v_mfma_f32_16x16x32_bf16 v[14:17], v[66:69], v[230:233], v[14:17]
	v_mfma_f32_16x16x32_bf16 v[58:61], v[70:73], v[218:221], v[58:61]
	s_add_u32 m0, s4, 0xc00
	v_mfma_f32_16x16x32_bf16 v[42:45], v[70:73], v[222:225], v[42:45]
	global_load_lds_dwordx4 v101, s[28:29]
	v_mfma_f32_16x16x32_bf16 v[26:29], v[70:73], v[226:229], v[26:29]
	v_mfma_f32_16x16x32_bf16 v[10:13], v[70:73], v[230:233], v[10:13]
	v_mfma_f32_16x16x32_bf16 v[54:57], v[74:77], v[218:221], v[54:57]
	v_mfma_f32_16x16x32_bf16 v[38:41], v[74:77], v[222:225], v[38:41]
	v_mfma_f32_16x16x32_bf16 v[22:25], v[74:77], v[226:229], v[22:25]
	v_mfma_f32_16x16x32_bf16 v[6:9], v[74:77], v[230:233], v[6:9]
	v_mfma_f32_16x16x32_bf16 v[50:53], v[78:81], v[218:221], v[50:53]
	v_mfma_f32_16x16x32_bf16 v[34:37], v[78:81], v[222:225], v[34:37]
	v_mfma_f32_16x16x32_bf16 v[18:21], v[78:81], v[226:229], v[18:21]
	v_mfma_f32_16x16x32_bf16 v[2:5], v[78:81], v[230:233], v[2:5]
	s_waitcnt lgkmcnt(0)
	s_waitcnt vmcnt(8)
	s_barrier
	ds_read_b128 v[218:221], v102 offset:49152
	ds_read_b128 v[222:225], v102 offset:51200
	ds_read_b128 v[226:229], v102 offset:53248
	ds_read_b128 v[230:233], v102 offset:55296
	v_mfma_f32_16x16x32_bf16 v[62:65], v[82:85], v[234:237], v[62:65]
	s_add_u32 m0, s4, 0x4000
	v_mfma_f32_16x16x32_bf16 v[46:49], v[82:85], v[238:241], v[46:49]
	global_load_lds_dwordx4 v98, s[6:7]
	v_mfma_f32_16x16x32_bf16 v[30:33], v[82:85], v[242:245], v[30:33]
	v_mfma_f32_16x16x32_bf16 v[14:17], v[82:85], v[246:249], v[14:17]
	v_mfma_f32_16x16x32_bf16 v[58:61], v[86:89], v[234:237], v[58:61]
	s_add_u32 m0, s4, 0x4400
	v_mfma_f32_16x16x32_bf16 v[42:45], v[86:89], v[238:241], v[42:45]
	global_load_lds_dwordx4 v99, s[6:7]
	v_mfma_f32_16x16x32_bf16 v[26:29], v[86:89], v[242:245], v[26:29]
	v_mfma_f32_16x16x32_bf16 v[10:13], v[86:89], v[246:249], v[10:13]
	v_mfma_f32_16x16x32_bf16 v[54:57], v[90:93], v[234:237], v[54:57]
	s_add_u32 m0, s4, 0x4800
	v_mfma_f32_16x16x32_bf16 v[38:41], v[90:93], v[238:241], v[38:41]
	global_load_lds_dwordx4 v100, s[6:7]
	v_mfma_f32_16x16x32_bf16 v[22:25], v[90:93], v[242:245], v[22:25]
	v_mfma_f32_16x16x32_bf16 v[6:9], v[90:93], v[246:249], v[6:9]
	v_mfma_f32_16x16x32_bf16 v[50:53], v[94:97], v[234:237], v[50:53]
	s_add_u32 m0, s4, 0x4c00
	v_mfma_f32_16x16x32_bf16 v[34:37], v[94:97], v[238:241], v[34:37]
	global_load_lds_dwordx4 v101, s[6:7]
	v_mfma_f32_16x16x32_bf16 v[18:21], v[94:97], v[242:245], v[18:21]
	v_mfma_f32_16x16x32_bf16 v[2:5], v[94:97], v[246:249], v[2:5]
	v_add_u32_e32 v98, 0x80, v98
	v_add_u32_e32 v99, 0x80, v99
	v_add_u32_e32 v100, 0x80, v100
	v_add_u32_e32 v101, 0x80, v101
	ds_read_b128 v[234:237], v103 offset:49152
	ds_read_b128 v[238:241], v103 offset:51200
	ds_read_b128 v[242:245], v103 offset:53248
	ds_read_b128 v[246:249], v103 offset:55296
	s_waitcnt lgkmcnt(4)
	v_mfma_f32_16x16x32_bf16 v[106:109], v[66:69], v[218:221], v[106:109]
	s_add_u32 m0, s4, 0x10000
	v_mfma_f32_16x16x32_bf16 v[122:125], v[66:69], v[222:225], v[122:125]
	global_load_lds_dwordx4 v98, s[48:49]
	v_mfma_f32_16x16x32_bf16 v[138:141], v[66:69], v[226:229], v[138:141]
	v_mfma_f32_16x16x32_bf16 v[162:165], v[66:69], v[230:233], v[162:165]
	v_mfma_f32_16x16x32_bf16 v[110:113], v[70:73], v[218:221], v[110:113]
	s_add_u32 m0, s4, 0x10400
	v_mfma_f32_16x16x32_bf16 v[126:129], v[70:73], v[222:225], v[126:129]
	global_load_lds_dwordx4 v99, s[48:49]
	v_mfma_f32_16x16x32_bf16 v[142:145], v[70:73], v[226:229], v[142:145]
	v_mfma_f32_16x16x32_bf16 v[166:169], v[70:73], v[230:233], v[166:169]
	v_mfma_f32_16x16x32_bf16 v[114:117], v[74:77], v[218:221], v[114:117]
	s_add_u32 m0, s4, 0x10800
	v_mfma_f32_16x16x32_bf16 v[130:133], v[74:77], v[222:225], v[130:133]
	global_load_lds_dwordx4 v100, s[48:49]
	v_mfma_f32_16x16x32_bf16 v[154:157], v[74:77], v[226:229], v[154:157]
	v_mfma_f32_16x16x32_bf16 v[170:173], v[74:77], v[230:233], v[170:173]
	v_mfma_f32_16x16x32_bf16 v[118:121], v[78:81], v[218:221], v[118:121]
	s_add_u32 m0, s4, 0x10c00
	v_mfma_f32_16x16x32_bf16 v[134:137], v[78:81], v[222:225], v[134:137]
	global_load_lds_dwordx4 v101, s[48:49]
	v_mfma_f32_16x16x32_bf16 v[158:161], v[78:81], v[226:229], v[158:161]
	v_mfma_f32_16x16x32_bf16 v[174:177], v[78:81], v[230:233], v[174:177]
	s_waitcnt lgkmcnt(0)
	s_waitcnt vmcnt(8)
	s_barrier
	ds_read_b128 v[218:221], v102 offset:0
	ds_read_b128 v[222:225], v102 offset:2048
	ds_read_b128 v[226:229], v102 offset:4096
	ds_read_b128 v[230:233], v102 offset:6144
	ds_read_b128 v[66:69], v104 offset:32768
	ds_read_b128 v[70:73], v104 offset:34816
	ds_read_b128 v[74:77], v104 offset:36864
	ds_read_b128 v[78:81], v104 offset:38912
	v_mfma_f32_16x16x32_bf16 v[106:109], v[82:85], v[234:237], v[106:109]
	s_add_u32 m0, s4, 0xc000
	v_mfma_f32_16x16x32_bf16 v[122:125], v[82:85], v[238:241], v[122:125]
	global_load_lds_dwordx4 v98, s[28:29]
	v_mfma_f32_16x16x32_bf16 v[138:141], v[82:85], v[242:245], v[138:141]
	v_mfma_f32_16x16x32_bf16 v[162:165], v[82:85], v[246:249], v[162:165]
	v_mfma_f32_16x16x32_bf16 v[110:113], v[86:89], v[234:237], v[110:113]
	s_add_u32 m0, s4, 0xc400
	v_mfma_f32_16x16x32_bf16 v[126:129], v[86:89], v[238:241], v[126:129]
	global_load_lds_dwordx4 v99, s[28:29]
	v_mfma_f32_16x16x32_bf16 v[142:145], v[86:89], v[242:245], v[142:145]
	v_mfma_f32_16x16x32_bf16 v[166:169], v[86:89], v[246:249], v[166:169]
	v_mfma_f32_16x16x32_bf16 v[114:117], v[90:93], v[234:237], v[114:117]
	v_mfma_f32_16x16x32_bf16 v[130:133], v[90:93], v[238:241], v[130:133]
	v_mfma_f32_16x16x32_bf16 v[154:157], v[90:93], v[242:245], v[154:157]
	v_mfma_f32_16x16x32_bf16 v[170:173], v[90:93], v[246:249], v[170:173]
	v_mfma_f32_16x16x32_bf16 v[118:121], v[94:97], v[234:237], v[118:121]
	v_mfma_f32_16x16x32_bf16 v[134:137], v[94:97], v[238:241], v[134:137]
	v_mfma_f32_16x16x32_bf16 v[158:161], v[94:97], v[242:245], v[158:161]
	v_mfma_f32_16x16x32_bf16 v[174:177], v[94:97], v[246:249], v[174:177]
	ds_read_b128 v[234:237], v103 offset:0
	ds_read_b128 v[238:241], v103 offset:2048
	ds_read_b128 v[242:245], v103 offset:4096
	ds_read_b128 v[246:249], v103 offset:6144
	ds_read_b128 v[82:85], v105 offset:32768
	ds_read_b128 v[86:89], v105 offset:34816
	ds_read_b128 v[90:93], v105 offset:36864
	ds_read_b128 v[94:97], v105 offset:38912
	s_waitcnt lgkmcnt(8)
	v_mfma_f32_16x16x32_bf16 v[62:65], v[66:69], v[218:221], v[62:65]
	s_add_u32 m0, s4, 0xc800
	v_mfma_f32_16x16x32_bf16 v[46:49], v[66:69], v[222:225], v[46:49]
	global_load_lds_dwordx4 v100, s[28:29]
	v_mfma_f32_16x16x32_bf16 v[30:33], v[66:69], v[226:229], v[30:33]
	v_mfma_f32_16x16x32_bf16 v[14:17], v[66:69], v[230:233], v[14:17]
	v_mfma_f32_16x16x32_bf16 v[58:61], v[70:73], v[218:221], v[58:61]
	s_add_u32 m0, s4, 0xcc00
	v_mfma_f32_16x16x32_bf16 v[42:45], v[70:73], v[222:225], v[42:45]
	global_load_lds_dwordx4 v101, s[28:29]
	v_mfma_f32_16x16x32_bf16 v[26:29], v[70:73], v[226:229], v[26:29]
	v_mfma_f32_16x16x32_bf16 v[10:13], v[70:73], v[230:233], v[10:13]
	v_mfma_f32_16x16x32_bf16 v[54:57], v[74:77], v[218:221], v[54:57]
	v_mfma_f32_16x16x32_bf16 v[38:41], v[74:77], v[222:225], v[38:41]
	v_mfma_f32_16x16x32_bf16 v[22:25], v[74:77], v[226:229], v[22:25]
	v_mfma_f32_16x16x32_bf16 v[6:9], v[74:77], v[230:233], v[6:9]
	v_mfma_f32_16x16x32_bf16 v[50:53], v[78:81], v[218:221], v[50:53]
	v_mfma_f32_16x16x32_bf16 v[34:37], v[78:81], v[222:225], v[34:37]
	v_mfma_f32_16x16x32_bf16 v[18:21], v[78:81], v[226:229], v[18:21]
	v_mfma_f32_16x16x32_bf16 v[2:5], v[78:81], v[230:233], v[2:5]
	s_waitcnt lgkmcnt(0)
	s_waitcnt vmcnt(8)
	s_barrier
	ds_read_b128 v[218:221], v102 offset:16384
	ds_read_b128 v[222:225], v102 offset:18432
	ds_read_b128 v[226:229], v102 offset:20480
	ds_read_b128 v[230:233], v102 offset:22528
	v_mfma_f32_16x16x32_bf16 v[62:65], v[82:85], v[234:237], v[62:65]
	s_add_u32 m0, s4, 0x0
	v_mfma_f32_16x16x32_bf16 v[46:49], v[82:85], v[238:241], v[46:49]
	global_load_lds_dwordx4 v98, s[6:7]
	v_mfma_f32_16x16x32_bf16 v[30:33], v[82:85], v[242:245], v[30:33]
	v_mfma_f32_16x16x32_bf16 v[14:17], v[82:85], v[246:249], v[14:17]
	v_mfma_f32_16x16x32_bf16 v[58:61], v[86:89], v[234:237], v[58:61]
	s_add_u32 m0, s4, 0x400
	v_mfma_f32_16x16x32_bf16 v[42:45], v[86:89], v[238:241], v[42:45]
	global_load_lds_dwordx4 v99, s[6:7]
	v_mfma_f32_16x16x32_bf16 v[26:29], v[86:89], v[242:245], v[26:29]
	v_mfma_f32_16x16x32_bf16 v[10:13], v[86:89], v[246:249], v[10:13]
	v_mfma_f32_16x16x32_bf16 v[54:57], v[90:93], v[234:237], v[54:57]
	s_add_u32 m0, s4, 0x800
	v_mfma_f32_16x16x32_bf16 v[38:41], v[90:93], v[238:241], v[38:41]
	global_load_lds_dwordx4 v100, s[6:7]
	v_mfma_f32_16x16x32_bf16 v[22:25], v[90:93], v[242:245], v[22:25]
	v_mfma_f32_16x16x32_bf16 v[6:9], v[90:93], v[246:249], v[6:9]
	v_mfma_f32_16x16x32_bf16 v[50:53], v[94:97], v[234:237], v[50:53]
	s_add_u32 m0, s4, 0xc00
	v_mfma_f32_16x16x32_bf16 v[34:37], v[94:97], v[238:241], v[34:37]
	global_load_lds_dwordx4 v101, s[6:7]
	v_mfma_f32_16x16x32_bf16 v[18:21], v[94:97], v[242:245], v[18:21]
	v_mfma_f32_16x16x32_bf16 v[2:5], v[94:97], v[246:249], v[2:5]
	v_add_u32_e32 v98, 0x80, v98
	v_add_u32_e32 v99, 0x80, v99
	v_add_u32_e32 v100, 0x80, v100
	v_add_u32_e32 v101, 0x80, v101
	ds_read_b128 v[234:237], v103 offset:16384
	ds_read_b128 v[238:241], v103 offset:18432
	ds_read_b128 v[242:245], v103 offset:20480
	ds_read_b128 v[246:249], v103 offset:22528
	s_waitcnt lgkmcnt(4)
	v_mfma_f32_16x16x32_bf16 v[106:109], v[66:69], v[218:221], v[106:109]
	s_add_u32 m0, s4, 0x8000
	v_mfma_f32_16x16x32_bf16 v[122:125], v[66:69], v[222:225], v[122:125]
	global_load_lds_dwordx4 v98, s[48:49]
	v_mfma_f32_16x16x32_bf16 v[138:141], v[66:69], v[226:229], v[138:141]
	v_mfma_f32_16x16x32_bf16 v[162:165], v[66:69], v[230:233], v[162:165]
	v_mfma_f32_16x16x32_bf16 v[110:113], v[70:73], v[218:221], v[110:113]
	s_add_u32 m0, s4, 0x8400
	v_mfma_f32_16x16x32_bf16 v[126:129], v[70:73], v[222:225], v[126:129]
	global_load_lds_dwordx4 v99, s[48:49]
	v_mfma_f32_16x16x32_bf16 v[142:145], v[70:73], v[226:229], v[142:145]
	v_mfma_f32_16x16x32_bf16 v[166:169], v[70:73], v[230:233], v[166:169]
	v_mfma_f32_16x16x32_bf16 v[114:117], v[74:77], v[218:221], v[114:117]
	s_add_u32 m0, s4, 0x8800
	v_mfma_f32_16x16x32_bf16 v[130:133], v[74:77], v[222:225], v[130:133]
	global_load_lds_dwordx4 v100, s[48:49]
	v_mfma_f32_16x16x32_bf16 v[154:157], v[74:77], v[226:229], v[154:157]
	v_mfma_f32_16x16x32_bf16 v[170:173], v[74:77], v[230:233], v[170:173]
	v_mfma_f32_16x16x32_bf16 v[118:121], v[78:81], v[218:221], v[118:121]
	s_add_u32 m0, s4, 0x8c00
	v_mfma_f32_16x16x32_bf16 v[134:137], v[78:81], v[222:225], v[134:137]
	global_load_lds_dwordx4 v101, s[48:49]
	v_mfma_f32_16x16x32_bf16 v[158:161], v[78:81], v[226:229], v[158:161]
	v_mfma_f32_16x16x32_bf16 v[174:177], v[78:81], v[230:233], v[174:177]
	s_waitcnt lgkmcnt(0)
	s_waitcnt vmcnt(8)
	s_barrier
	ds_read_b128 v[218:221], v102 offset:49152
	ds_read_b128 v[222:225], v102 offset:51200
	ds_read_b128 v[226:229], v102 offset:53248
	ds_read_b128 v[230:233], v102 offset:55296
	ds_read_b128 v[66:69], v250 offset:49152
	ds_read_b128 v[70:73], v250 offset:51200
	ds_read_b128 v[74:77], v250 offset:53248
	ds_read_b128 v[78:81], v250 offset:55296
	v_mfma_f32_16x16x32_bf16 v[106:109], v[82:85], v[234:237], v[106:109]
	s_add_u32 m0, s4, 0x4000
	v_mfma_f32_16x16x32_bf16 v[122:125], v[82:85], v[238:241], v[122:125]
	global_load_lds_dwordx4 v98, s[28:29]
	v_mfma_f32_16x16x32_bf16 v[138:141], v[82:85], v[242:245], v[138:141]
	v_mfma_f32_16x16x32_bf16 v[162:165], v[82:85], v[246:249], v[162:165]
	v_mfma_f32_16x16x32_bf16 v[110:113], v[86:89], v[234:237], v[110:113]
	s_add_u32 m0, s4, 0x4400
	v_mfma_f32_16x16x32_bf16 v[126:129], v[86:89], v[238:241], v[126:129]
	global_load_lds_dwordx4 v99, s[28:29]
	v_mfma_f32_16x16x32_bf16 v[142:145], v[86:89], v[242:245], v[142:145]
	v_mfma_f32_16x16x32_bf16 v[166:169], v[86:89], v[246:249], v[166:169]
	v_mfma_f32_16x16x32_bf16 v[114:117], v[90:93], v[234:237], v[114:117]
	v_mfma_f32_16x16x32_bf16 v[130:133], v[90:93], v[238:241], v[130:133]
	v_mfma_f32_16x16x32_bf16 v[154:157], v[90:93], v[242:245], v[154:157]
	v_mfma_f32_16x16x32_bf16 v[170:173], v[90:93], v[246:249], v[170:173]
	v_mfma_f32_16x16x32_bf16 v[118:121], v[94:97], v[234:237], v[118:121]
	v_mfma_f32_16x16x32_bf16 v[134:137], v[94:97], v[238:241], v[134:137]
	v_mfma_f32_16x16x32_bf16 v[158:161], v[94:97], v[242:245], v[158:161]
	v_mfma_f32_16x16x32_bf16 v[174:177], v[94:97], v[246:249], v[174:177]
	ds_read_b128 v[234:237], v103 offset:49152
	ds_read_b128 v[238:241], v103 offset:51200
	ds_read_b128 v[242:245], v103 offset:53248
	ds_read_b128 v[246:249], v103 offset:55296
	ds_read_b128 v[82:85], v251 offset:49152
	ds_read_b128 v[86:89], v251 offset:51200
	ds_read_b128 v[90:93], v251 offset:53248
	ds_read_b128 v[94:97], v251 offset:55296
	s_waitcnt lgkmcnt(8)
	v_mfma_f32_16x16x32_bf16 v[62:65], v[66:69], v[218:221], v[62:65]
	s_add_u32 m0, s4, 0x4800
	v_mfma_f32_16x16x32_bf16 v[46:49], v[66:69], v[222:225], v[46:49]
	global_load_lds_dwordx4 v100, s[28:29]
	v_mfma_f32_16x16x32_bf16 v[30:33], v[66:69], v[226:229], v[30:33]
	v_mfma_f32_16x16x32_bf16 v[14:17], v[66:69], v[230:233], v[14:17]
	v_mfma_f32_16x16x32_bf16 v[58:61], v[70:73], v[218:221], v[58:61]
	s_add_u32 m0, s4, 0x4c00
	v_mfma_f32_16x16x32_bf16 v[42:45], v[70:73], v[222:225], v[42:45]
	global_load_lds_dwordx4 v101, s[28:29]
	v_mfma_f32_16x16x32_bf16 v[26:29], v[70:73], v[226:229], v[26:29]
	v_mfma_f32_16x16x32_bf16 v[10:13], v[70:73], v[230:233], v[10:13]
	v_mfma_f32_16x16x32_bf16 v[54:57], v[74:77], v[218:221], v[54:57]
	v_mfma_f32_16x16x32_bf16 v[38:41], v[74:77], v[222:225], v[38:41]
	v_mfma_f32_16x16x32_bf16 v[22:25], v[74:77], v[226:229], v[22:25]
	v_mfma_f32_16x16x32_bf16 v[6:9], v[74:77], v[230:233], v[6:9]
	v_mfma_f32_16x16x32_bf16 v[50:53], v[78:81], v[218:221], v[50:53]
	v_mfma_f32_16x16x32_bf16 v[34:37], v[78:81], v[222:225], v[34:37]
	v_mfma_f32_16x16x32_bf16 v[18:21], v[78:81], v[226:229], v[18:21]
	v_mfma_f32_16x16x32_bf16 v[2:5], v[78:81], v[230:233], v[2:5]
	s_waitcnt lgkmcnt(0)
	s_waitcnt vmcnt(8)
	s_barrier
	ds_read_b128 v[218:221], v102 offset:0
	ds_read_b128 v[222:225], v102 offset:2048
	ds_read_b128 v[226:229], v102 offset:4096
	ds_read_b128 v[230:233], v102 offset:6144
	v_mfma_f32_16x16x32_bf16 v[62:65], v[82:85], v[234:237], v[62:65]
	s_add_u32 m0, s4, 0xc000
	v_mfma_f32_16x16x32_bf16 v[46:49], v[82:85], v[238:241], v[46:49]
	global_load_lds_dwordx4 v98, s[6:7]
	v_mfma_f32_16x16x32_bf16 v[30:33], v[82:85], v[242:245], v[30:33]
	v_mfma_f32_16x16x32_bf16 v[14:17], v[82:85], v[246:249], v[14:17]
	v_mfma_f32_16x16x32_bf16 v[58:61], v[86:89], v[234:237], v[58:61]
	s_add_u32 m0, s4, 0xc400
	v_mfma_f32_16x16x32_bf16 v[42:45], v[86:89], v[238:241], v[42:45]
	global_load_lds_dwordx4 v99, s[6:7]
	v_mfma_f32_16x16x32_bf16 v[26:29], v[86:89], v[242:245], v[26:29]
	v_mfma_f32_16x16x32_bf16 v[10:13], v[86:89], v[246:249], v[10:13]
	v_mfma_f32_16x16x32_bf16 v[54:57], v[90:93], v[234:237], v[54:57]
	s_add_u32 m0, s4, 0xc800
	v_mfma_f32_16x16x32_bf16 v[38:41], v[90:93], v[238:241], v[38:41]
	global_load_lds_dwordx4 v100, s[6:7]
	v_mfma_f32_16x16x32_bf16 v[22:25], v[90:93], v[242:245], v[22:25]
	v_mfma_f32_16x16x32_bf16 v[6:9], v[90:93], v[246:249], v[6:9]
	v_mfma_f32_16x16x32_bf16 v[50:53], v[94:97], v[234:237], v[50:53]
	s_add_u32 m0, s4, 0xcc00
	v_mfma_f32_16x16x32_bf16 v[34:37], v[94:97], v[238:241], v[34:37]
	global_load_lds_dwordx4 v101, s[6:7]
	v_mfma_f32_16x16x32_bf16 v[18:21], v[94:97], v[242:245], v[18:21]
	v_mfma_f32_16x16x32_bf16 v[2:5], v[94:97], v[246:249], v[2:5]
	v_add_u32_e32 v98, 0x80, v98
	v_add_u32_e32 v99, 0x80, v99
	v_add_u32_e32 v100, 0x80, v100
	v_add_u32_e32 v101, 0x80, v101
	ds_read_b128 v[234:237], v103 offset:0
	ds_read_b128 v[238:241], v103 offset:2048
	ds_read_b128 v[242:245], v103 offset:4096
	ds_read_b128 v[246:249], v103 offset:6144
	s_waitcnt lgkmcnt(4)
	v_mfma_f32_16x16x32_bf16 v[106:109], v[66:69], v[218:221], v[106:109]
	s_add_u32 m0, s4, 0x10000
	v_mfma_f32_16x16x32_bf16 v[122:125], v[66:69], v[222:225], v[122:125]
	global_load_lds_dwordx4 v98, s[48:49]
	v_mfma_f32_16x16x32_bf16 v[138:141], v[66:69], v[226:229], v[138:141]
	v_mfma_f32_16x16x32_bf16 v[162:165], v[66:69], v[230:233], v[162:165]
	v_mfma_f32_16x16x32_bf16 v[110:113], v[70:73], v[218:221], v[110:113]
	s_add_u32 m0, s4, 0x10400
	v_mfma_f32_16x16x32_bf16 v[126:129], v[70:73], v[222:225], v[126:129]
	global_load_lds_dwordx4 v99, s[48:49]
	v_mfma_f32_16x16x32_bf16 v[142:145], v[70:73], v[226:229], v[142:145]
	v_mfma_f32_16x16x32_bf16 v[166:169], v[70:73], v[230:233], v[166:169]
	v_mfma_f32_16x16x32_bf16 v[114:117], v[74:77], v[218:221], v[114:117]
	s_add_u32 m0, s4, 0x10800
	v_mfma_f32_16x16x32_bf16 v[130:133], v[74:77], v[222:225], v[130:133]
	global_load_lds_dwordx4 v100, s[48:49]
	v_mfma_f32_16x16x32_bf16 v[154:157], v[74:77], v[226:229], v[154:157]
	v_mfma_f32_16x16x32_bf16 v[170:173], v[74:77], v[230:233], v[170:173]
	v_mfma_f32_16x16x32_bf16 v[118:121], v[78:81], v[218:221], v[118:121]
	s_add_u32 m0, s4, 0x10c00
	v_mfma_f32_16x16x32_bf16 v[134:137], v[78:81], v[222:225], v[134:137]
	global_load_lds_dwordx4 v101, s[48:49]
	v_mfma_f32_16x16x32_bf16 v[158:161], v[78:81], v[226:229], v[158:161]
	v_mfma_f32_16x16x32_bf16 v[174:177], v[78:81], v[230:233], v[174:177]
	s_waitcnt lgkmcnt(0)
	s_waitcnt vmcnt(8)
	s_barrier
	ds_read_b128 v[218:221], v102 offset:16384
	ds_read_b128 v[222:225], v102 offset:18432
	ds_read_b128 v[226:229], v102 offset:20480
	ds_read_b128 v[230:233], v102 offset:22528
	ds_read_b128 v[66:69], v104 offset:32768
	ds_read_b128 v[70:73], v104 offset:34816
	ds_read_b128 v[74:77], v104 offset:36864
	ds_read_b128 v[78:81], v104 offset:38912
	v_mfma_f32_16x16x32_bf16 v[106:109], v[82:85], v[234:237], v[106:109]
	s_add_u32 m0, s4, 0x0
	v_mfma_f32_16x16x32_bf16 v[122:125], v[82:85], v[238:241], v[122:125]
	global_load_lds_dwordx4 v98, s[28:29]
	v_mfma_f32_16x16x32_bf16 v[138:141], v[82:85], v[242:245], v[138:141]
	v_mfma_f32_16x16x32_bf16 v[162:165], v[82:85], v[246:249], v[162:165]
	v_mfma_f32_16x16x32_bf16 v[110:113], v[86:89], v[234:237], v[110:113]
	s_add_u32 m0, s4, 0x400
	v_mfma_f32_16x16x32_bf16 v[126:129], v[86:89], v[238:241], v[126:129]
	global_load_lds_dwordx4 v99, s[28:29]
	v_mfma_f32_16x16x32_bf16 v[142:145], v[86:89], v[242:245], v[142:145]
	v_mfma_f32_16x16x32_bf16 v[166:169], v[86:89], v[246:249], v[166:169]
	v_mfma_f32_16x16x32_bf16 v[114:117], v[90:93], v[234:237], v[114:117]
	v_mfma_f32_16x16x32_bf16 v[130:133], v[90:93], v[238:241], v[130:133]
	v_mfma_f32_16x16x32_bf16 v[154:157], v[90:93], v[242:245], v[154:157]
	v_mfma_f32_16x16x32_bf16 v[170:173], v[90:93], v[246:249], v[170:173]
	v_mfma_f32_16x16x32_bf16 v[118:121], v[94:97], v[234:237], v[118:121]
	v_mfma_f32_16x16x32_bf16 v[134:137], v[94:97], v[238:241], v[134:137]
	v_mfma_f32_16x16x32_bf16 v[158:161], v[94:97], v[242:245], v[158:161]
	v_mfma_f32_16x16x32_bf16 v[174:177], v[94:97], v[246:249], v[174:177]
	ds_read_b128 v[234:237], v103 offset:16384
	ds_read_b128 v[238:241], v103 offset:18432
	ds_read_b128 v[242:245], v103 offset:20480
	ds_read_b128 v[246:249], v103 offset:22528
	ds_read_b128 v[82:85], v105 offset:32768
	ds_read_b128 v[86:89], v105 offset:34816
	ds_read_b128 v[90:93], v105 offset:36864
	ds_read_b128 v[94:97], v105 offset:38912
	s_waitcnt lgkmcnt(8)
	v_mfma_f32_16x16x32_bf16 v[62:65], v[66:69], v[218:221], v[62:65]
	s_add_u32 m0, s4, 0x800
	v_mfma_f32_16x16x32_bf16 v[46:49], v[66:69], v[222:225], v[46:49]
	global_load_lds_dwordx4 v100, s[28:29]
	v_mfma_f32_16x16x32_bf16 v[30:33], v[66:69], v[226:229], v[30:33]
	v_mfma_f32_16x16x32_bf16 v[14:17], v[66:69], v[230:233], v[14:17]
	v_mfma_f32_16x16x32_bf16 v[58:61], v[70:73], v[218:221], v[58:61]
	s_add_u32 m0, s4, 0xc00
	v_mfma_f32_16x16x32_bf16 v[42:45], v[70:73], v[222:225], v[42:45]
	global_load_lds_dwordx4 v101, s[28:29]
	v_mfma_f32_16x16x32_bf16 v[26:29], v[70:73], v[226:229], v[26:29]
	v_mfma_f32_16x16x32_bf16 v[10:13], v[70:73], v[230:233], v[10:13]
	v_mfma_f32_16x16x32_bf16 v[54:57], v[74:77], v[218:221], v[54:57]
	v_mfma_f32_16x16x32_bf16 v[38:41], v[74:77], v[222:225], v[38:41]
	v_mfma_f32_16x16x32_bf16 v[22:25], v[74:77], v[226:229], v[22:25]
	v_mfma_f32_16x16x32_bf16 v[6:9], v[74:77], v[230:233], v[6:9]
	v_mfma_f32_16x16x32_bf16 v[50:53], v[78:81], v[218:221], v[50:53]
	v_mfma_f32_16x16x32_bf16 v[34:37], v[78:81], v[222:225], v[34:37]
	v_mfma_f32_16x16x32_bf16 v[18:21], v[78:81], v[226:229], v[18:21]
	v_mfma_f32_16x16x32_bf16 v[2:5], v[78:81], v[230:233], v[2:5]
	s_waitcnt lgkmcnt(0)
	s_waitcnt vmcnt(8)
	s_barrier
	ds_read_b128 v[218:221], v102 offset:49152
	ds_read_b128 v[222:225], v102 offset:51200
	ds_read_b128 v[226:229], v102 offset:53248
	ds_read_b128 v[230:233], v102 offset:55296
	v_mfma_f32_16x16x32_bf16 v[62:65], v[82:85], v[234:237], v[62:65]
	s_add_u32 m0, s4, 0x4000
	v_mfma_f32_16x16x32_bf16 v[46:49], v[82:85], v[238:241], v[46:49]
	global_load_lds_dwordx4 v98, s[6:7]
	v_mfma_f32_16x16x32_bf16 v[30:33], v[82:85], v[242:245], v[30:33]
	v_mfma_f32_16x16x32_bf16 v[14:17], v[82:85], v[246:249], v[14:17]
	v_mfma_f32_16x16x32_bf16 v[58:61], v[86:89], v[234:237], v[58:61]
	s_add_u32 m0, s4, 0x4400
	v_mfma_f32_16x16x32_bf16 v[42:45], v[86:89], v[238:241], v[42:45]
	global_load_lds_dwordx4 v99, s[6:7]
	v_mfma_f32_16x16x32_bf16 v[26:29], v[86:89], v[242:245], v[26:29]
	v_mfma_f32_16x16x32_bf16 v[10:13], v[86:89], v[246:249], v[10:13]
	v_mfma_f32_16x16x32_bf16 v[54:57], v[90:93], v[234:237], v[54:57]
	s_add_u32 m0, s4, 0x4800
	v_mfma_f32_16x16x32_bf16 v[38:41], v[90:93], v[238:241], v[38:41]
	global_load_lds_dwordx4 v100, s[6:7]
	v_mfma_f32_16x16x32_bf16 v[22:25], v[90:93], v[242:245], v[22:25]
	v_mfma_f32_16x16x32_bf16 v[6:9], v[90:93], v[246:249], v[6:9]
	v_mfma_f32_16x16x32_bf16 v[50:53], v[94:97], v[234:237], v[50:53]
	s_add_u32 m0, s4, 0x4c00
	v_mfma_f32_16x16x32_bf16 v[34:37], v[94:97], v[238:241], v[34:37]
	global_load_lds_dwordx4 v101, s[6:7]
	v_mfma_f32_16x16x32_bf16 v[18:21], v[94:97], v[242:245], v[18:21]
	v_mfma_f32_16x16x32_bf16 v[2:5], v[94:97], v[246:249], v[2:5]
	v_add_u32_e32 v98, 0x80, v98
	v_add_u32_e32 v99, 0x80, v99
	v_add_u32_e32 v100, 0x80, v100
	v_add_u32_e32 v101, 0x80, v101
	ds_read_b128 v[234:237], v103 offset:49152
	ds_read_b128 v[238:241], v103 offset:51200
	ds_read_b128 v[242:245], v103 offset:53248
	ds_read_b128 v[246:249], v103 offset:55296
	s_waitcnt lgkmcnt(4)
	v_mfma_f32_16x16x32_bf16 v[106:109], v[66:69], v[218:221], v[106:109]
	s_add_u32 m0, s4, 0x8000
	v_mfma_f32_16x16x32_bf16 v[122:125], v[66:69], v[222:225], v[122:125]
	global_load_lds_dwordx4 v98, s[48:49]
	v_mfma_f32_16x16x32_bf16 v[138:141], v[66:69], v[226:229], v[138:141]
	v_mfma_f32_16x16x32_bf16 v[162:165], v[66:69], v[230:233], v[162:165]
	v_mfma_f32_16x16x32_bf16 v[110:113], v[70:73], v[218:221], v[110:113]
	s_add_u32 m0, s4, 0x8400
	v_mfma_f32_16x16x32_bf16 v[126:129], v[70:73], v[222:225], v[126:129]
	global_load_lds_dwordx4 v99, s[48:49]
	v_mfma_f32_16x16x32_bf16 v[142:145], v[70:73], v[226:229], v[142:145]
	v_mfma_f32_16x16x32_bf16 v[166:169], v[70:73], v[230:233], v[166:169]
	v_mfma_f32_16x16x32_bf16 v[114:117], v[74:77], v[218:221], v[114:117]
	s_add_u32 m0, s4, 0x8800
	v_mfma_f32_16x16x32_bf16 v[130:133], v[74:77], v[222:225], v[130:133]
	global_load_lds_dwordx4 v100, s[48:49]
	v_mfma_f32_16x16x32_bf16 v[154:157], v[74:77], v[226:229], v[154:157]
	v_mfma_f32_16x16x32_bf16 v[170:173], v[74:77], v[230:233], v[170:173]
	v_mfma_f32_16x16x32_bf16 v[118:121], v[78:81], v[218:221], v[118:121]
	s_add_u32 m0, s4, 0x8c00
	v_mfma_f32_16x16x32_bf16 v[134:137], v[78:81], v[222:225], v[134:137]
	global_load_lds_dwordx4 v101, s[48:49]
	v_mfma_f32_16x16x32_bf16 v[158:161], v[78:81], v[226:229], v[158:161]
	v_mfma_f32_16x16x32_bf16 v[174:177], v[78:81], v[230:233], v[174:177]
	s_waitcnt lgkmcnt(0)
	s_waitcnt vmcnt(8)
	s_barrier
	ds_read_b128 v[218:221], v102 offset:0
	ds_read_b128 v[222:225], v102 offset:2048
	ds_read_b128 v[226:229], v102 offset:4096
	ds_read_b128 v[230:233], v102 offset:6144
	ds_read_b128 v[66:69], v250 offset:49152
	ds_read_b128 v[70:73], v250 offset:51200
	ds_read_b128 v[74:77], v250 offset:53248
	ds_read_b128 v[78:81], v250 offset:55296
	v_mfma_f32_16x16x32_bf16 v[106:109], v[82:85], v[234:237], v[106:109]
	s_add_u32 m0, s4, 0xc000
	v_mfma_f32_16x16x32_bf16 v[122:125], v[82:85], v[238:241], v[122:125]
	global_load_lds_dwordx4 v98, s[28:29]
	v_mfma_f32_16x16x32_bf16 v[138:141], v[82:85], v[242:245], v[138:141]
	v_mfma_f32_16x16x32_bf16 v[162:165], v[82:85], v[246:249], v[162:165]
	v_mfma_f32_16x16x32_bf16 v[110:113], v[86:89], v[234:237], v[110:113]
	s_add_u32 m0, s4, 0xc400
	v_mfma_f32_16x16x32_bf16 v[126:129], v[86:89], v[238:241], v[126:129]
	global_load_lds_dwordx4 v99, s[28:29]
	v_mfma_f32_16x16x32_bf16 v[142:145], v[86:89], v[242:245], v[142:145]
	v_mfma_f32_16x16x32_bf16 v[166:169], v[86:89], v[246:249], v[166:169]
	v_mfma_f32_16x16x32_bf16 v[114:117], v[90:93], v[234:237], v[114:117]
	v_mfma_f32_16x16x32_bf16 v[130:133], v[90:93], v[238:241], v[130:133]
	v_mfma_f32_16x16x32_bf16 v[154:157], v[90:93], v[242:245], v[154:157]
	v_mfma_f32_16x16x32_bf16 v[170:173], v[90:93], v[246:249], v[170:173]
	v_mfma_f32_16x16x32_bf16 v[118:121], v[94:97], v[234:237], v[118:121]
	v_mfma_f32_16x16x32_bf16 v[134:137], v[94:97], v[238:241], v[134:137]
	v_mfma_f32_16x16x32_bf16 v[158:161], v[94:97], v[242:245], v[158:161]
	v_mfma_f32_16x16x32_bf16 v[174:177], v[94:97], v[246:249], v[174:177]
	ds_read_b128 v[234:237], v103 offset:0
	ds_read_b128 v[238:241], v103 offset:2048
	ds_read_b128 v[242:245], v103 offset:4096
	ds_read_b128 v[246:249], v103 offset:6144
	ds_read_b128 v[82:85], v251 offset:49152
	ds_read_b128 v[86:89], v251 offset:51200
	ds_read_b128 v[90:93], v251 offset:53248
	ds_read_b128 v[94:97], v251 offset:55296
	s_waitcnt lgkmcnt(8)
	v_mfma_f32_16x16x32_bf16 v[62:65], v[66:69], v[218:221], v[62:65]
	s_add_u32 m0, s4, 0xc800
	v_mfma_f32_16x16x32_bf16 v[46:49], v[66:69], v[222:225], v[46:49]
	global_load_lds_dwordx4 v100, s[28:29]
	v_mfma_f32_16x16x32_bf16 v[30:33], v[66:69], v[226:229], v[30:33]
	v_mfma_f32_16x16x32_bf16 v[14:17], v[66:69], v[230:233], v[14:17]
	v_mfma_f32_16x16x32_bf16 v[58:61], v[70:73], v[218:221], v[58:61]
	s_add_u32 m0, s4, 0xcc00
	v_mfma_f32_16x16x32_bf16 v[42:45], v[70:73], v[222:225], v[42:45]
	global_load_lds_dwordx4 v101, s[28:29]
	v_mfma_f32_16x16x32_bf16 v[26:29], v[70:73], v[226:229], v[26:29]
	v_mfma_f32_16x16x32_bf16 v[10:13], v[70:73], v[230:233], v[10:13]
	v_mfma_f32_16x16x32_bf16 v[54:57], v[74:77], v[218:221], v[54:57]
	v_mfma_f32_16x16x32_bf16 v[38:41], v[74:77], v[222:225], v[38:41]
	v_mfma_f32_16x16x32_bf16 v[22:25], v[74:77], v[226:229], v[22:25]
	v_mfma_f32_16x16x32_bf16 v[6:9], v[74:77], v[230:233], v[6:9]
	v_mfma_f32_16x16x32_bf16 v[50:53], v[78:81], v[218:221], v[50:53]
	v_mfma_f32_16x16x32_bf16 v[34:37], v[78:81], v[222:225], v[34:37]
	v_mfma_f32_16x16x32_bf16 v[18:21], v[78:81], v[226:229], v[18:21]
	v_mfma_f32_16x16x32_bf16 v[2:5], v[78:81], v[230:233], v[2:5]
	s_waitcnt lgkmcnt(0)
	s_waitcnt vmcnt(8)
	s_barrier
	ds_read_b128 v[218:221], v102 offset:16384
	ds_read_b128 v[222:225], v102 offset:18432
	ds_read_b128 v[226:229], v102 offset:20480
	ds_read_b128 v[230:233], v102 offset:22528
	v_mfma_f32_16x16x32_bf16 v[62:65], v[82:85], v[234:237], v[62:65]
	s_add_u32 m0, s4, 0x0
	v_mfma_f32_16x16x32_bf16 v[46:49], v[82:85], v[238:241], v[46:49]
	global_load_lds_dwordx4 v98, s[6:7]
	v_mfma_f32_16x16x32_bf16 v[30:33], v[82:85], v[242:245], v[30:33]
	v_mfma_f32_16x16x32_bf16 v[14:17], v[82:85], v[246:249], v[14:17]
	v_mfma_f32_16x16x32_bf16 v[58:61], v[86:89], v[234:237], v[58:61]
	s_add_u32 m0, s4, 0x400
	v_mfma_f32_16x16x32_bf16 v[42:45], v[86:89], v[238:241], v[42:45]
	global_load_lds_dwordx4 v99, s[6:7]
	v_mfma_f32_16x16x32_bf16 v[26:29], v[86:89], v[242:245], v[26:29]
	v_mfma_f32_16x16x32_bf16 v[10:13], v[86:89], v[246:249], v[10:13]
	v_mfma_f32_16x16x32_bf16 v[54:57], v[90:93], v[234:237], v[54:57]
	s_add_u32 m0, s4, 0x800
	v_mfma_f32_16x16x32_bf16 v[38:41], v[90:93], v[238:241], v[38:41]
	global_load_lds_dwordx4 v100, s[6:7]
	v_mfma_f32_16x16x32_bf16 v[22:25], v[90:93], v[242:245], v[22:25]
	v_mfma_f32_16x16x32_bf16 v[6:9], v[90:93], v[246:249], v[6:9]
	v_mfma_f32_16x16x32_bf16 v[50:53], v[94:97], v[234:237], v[50:53]
	s_add_u32 m0, s4, 0xc00
	v_mfma_f32_16x16x32_bf16 v[34:37], v[94:97], v[238:241], v[34:37]
	global_load_lds_dwordx4 v101, s[6:7]
	v_mfma_f32_16x16x32_bf16 v[18:21], v[94:97], v[242:245], v[18:21]
	v_mfma_f32_16x16x32_bf16 v[2:5], v[94:97], v[246:249], v[2:5]
	v_add_u32_e32 v98, 0x80, v98
	v_add_u32_e32 v99, 0x80, v99
	v_add_u32_e32 v100, 0x80, v100
	v_add_u32_e32 v101, 0x80, v101
	ds_read_b128 v[234:237], v103 offset:16384
	ds_read_b128 v[238:241], v103 offset:18432
	ds_read_b128 v[242:245], v103 offset:20480
	ds_read_b128 v[246:249], v103 offset:22528
	s_waitcnt lgkmcnt(4)
	v_mfma_f32_16x16x32_bf16 v[106:109], v[66:69], v[218:221], v[106:109]
	v_mfma_f32_16x16x32_bf16 v[122:125], v[66:69], v[222:225], v[122:125]
	v_mfma_f32_16x16x32_bf16 v[138:141], v[66:69], v[226:229], v[138:141]
	v_mfma_f32_16x16x32_bf16 v[162:165], v[66:69], v[230:233], v[162:165]
	v_mfma_f32_16x16x32_bf16 v[110:113], v[70:73], v[218:221], v[110:113]
	v_mfma_f32_16x16x32_bf16 v[126:129], v[70:73], v[222:225], v[126:129]
	v_mfma_f32_16x16x32_bf16 v[142:145], v[70:73], v[226:229], v[142:145]
	v_mfma_f32_16x16x32_bf16 v[166:169], v[70:73], v[230:233], v[166:169]
	v_mfma_f32_16x16x32_bf16 v[114:117], v[74:77], v[218:221], v[114:117]
	v_mfma_f32_16x16x32_bf16 v[130:133], v[74:77], v[222:225], v[130:133]
	v_mfma_f32_16x16x32_bf16 v[154:157], v[74:77], v[226:229], v[154:157]
	v_mfma_f32_16x16x32_bf16 v[170:173], v[74:77], v[230:233], v[170:173]
	v_mfma_f32_16x16x32_bf16 v[118:121], v[78:81], v[218:221], v[118:121]
	v_mfma_f32_16x16x32_bf16 v[134:137], v[78:81], v[222:225], v[134:137]
	v_mfma_f32_16x16x32_bf16 v[158:161], v[78:81], v[226:229], v[158:161]
	v_mfma_f32_16x16x32_bf16 v[174:177], v[78:81], v[230:233], v[174:177]
	s_waitcnt lgkmcnt(0)
	s_waitcnt vmcnt(4)
	s_barrier
	ds_read_b128 v[218:221], v102 offset:49152
	ds_read_b128 v[222:225], v102 offset:51200
	ds_read_b128 v[226:229], v102 offset:53248
	ds_read_b128 v[230:233], v102 offset:55296
	ds_read_b128 v[66:69], v104 offset:32768
	ds_read_b128 v[70:73], v104 offset:34816
	ds_read_b128 v[74:77], v104 offset:36864
	ds_read_b128 v[78:81], v104 offset:38912
	v_mfma_f32_16x16x32_bf16 v[106:109], v[82:85], v[234:237], v[106:109]
	v_mfma_f32_16x16x32_bf16 v[122:125], v[82:85], v[238:241], v[122:125]
	v_mfma_f32_16x16x32_bf16 v[138:141], v[82:85], v[242:245], v[138:141]
	v_mfma_f32_16x16x32_bf16 v[162:165], v[82:85], v[246:249], v[162:165]
	v_mfma_f32_16x16x32_bf16 v[110:113], v[86:89], v[234:237], v[110:113]
	v_mfma_f32_16x16x32_bf16 v[126:129], v[86:89], v[238:241], v[126:129]
	v_mfma_f32_16x16x32_bf16 v[142:145], v[86:89], v[242:245], v[142:145]
	v_mfma_f32_16x16x32_bf16 v[166:169], v[86:89], v[246:249], v[166:169]
	v_mfma_f32_16x16x32_bf16 v[114:117], v[90:93], v[234:237], v[114:117]
	v_mfma_f32_16x16x32_bf16 v[130:133], v[90:93], v[238:241], v[130:133]
	v_mfma_f32_16x16x32_bf16 v[154:157], v[90:93], v[242:245], v[154:157]
	v_mfma_f32_16x16x32_bf16 v[170:173], v[90:93], v[246:249], v[170:173]
	v_mfma_f32_16x16x32_bf16 v[118:121], v[94:97], v[234:237], v[118:121]
	v_mfma_f32_16x16x32_bf16 v[134:137], v[94:97], v[238:241], v[134:137]
	v_mfma_f32_16x16x32_bf16 v[158:161], v[94:97], v[242:245], v[158:161]
	v_mfma_f32_16x16x32_bf16 v[174:177], v[94:97], v[246:249], v[174:177]
	ds_read_b128 v[234:237], v103 offset:49152
	ds_read_b128 v[238:241], v103 offset:51200
	ds_read_b128 v[242:245], v103 offset:53248
	ds_read_b128 v[246:249], v103 offset:55296
	ds_read_b128 v[82:85], v105 offset:32768
	ds_read_b128 v[86:89], v105 offset:34816
	ds_read_b128 v[90:93], v105 offset:36864
	ds_read_b128 v[94:97], v105 offset:38912
	s_waitcnt lgkmcnt(8)
	v_mfma_f32_16x16x32_bf16 v[62:65], v[66:69], v[218:221], v[62:65]
	v_mfma_f32_16x16x32_bf16 v[46:49], v[66:69], v[222:225], v[46:49]
	v_mfma_f32_16x16x32_bf16 v[30:33], v[66:69], v[226:229], v[30:33]
	v_mfma_f32_16x16x32_bf16 v[14:17], v[66:69], v[230:233], v[14:17]
	v_mfma_f32_16x16x32_bf16 v[58:61], v[70:73], v[218:221], v[58:61]
	v_mfma_f32_16x16x32_bf16 v[42:45], v[70:73], v[222:225], v[42:45]
	v_mfma_f32_16x16x32_bf16 v[26:29], v[70:73], v[226:229], v[26:29]
	v_mfma_f32_16x16x32_bf16 v[10:13], v[70:73], v[230:233], v[10:13]
	v_mfma_f32_16x16x32_bf16 v[54:57], v[74:77], v[218:221], v[54:57]
	v_mfma_f32_16x16x32_bf16 v[38:41], v[74:77], v[222:225], v[38:41]
	v_mfma_f32_16x16x32_bf16 v[22:25], v[74:77], v[226:229], v[22:25]
	v_mfma_f32_16x16x32_bf16 v[6:9], v[74:77], v[230:233], v[6:9]
	v_mfma_f32_16x16x32_bf16 v[50:53], v[78:81], v[218:221], v[50:53]
	v_mfma_f32_16x16x32_bf16 v[34:37], v[78:81], v[222:225], v[34:37]
	v_mfma_f32_16x16x32_bf16 v[18:21], v[78:81], v[226:229], v[18:21]
	v_mfma_f32_16x16x32_bf16 v[2:5], v[78:81], v[230:233], v[2:5]
	s_waitcnt lgkmcnt(0)
	s_waitcnt vmcnt(0)
	s_barrier
	ds_read_b128 v[218:221], v102 offset:0
	ds_read_b128 v[222:225], v102 offset:2048
	ds_read_b128 v[226:229], v102 offset:4096
	ds_read_b128 v[230:233], v102 offset:6144
	v_mfma_f32_16x16x32_bf16 v[62:65], v[82:85], v[234:237], v[62:65]
	v_mfma_f32_16x16x32_bf16 v[46:49], v[82:85], v[238:241], v[46:49]
	v_mfma_f32_16x16x32_bf16 v[30:33], v[82:85], v[242:245], v[30:33]
	v_mfma_f32_16x16x32_bf16 v[14:17], v[82:85], v[246:249], v[14:17]
	v_mfma_f32_16x16x32_bf16 v[58:61], v[86:89], v[234:237], v[58:61]
	v_mfma_f32_16x16x32_bf16 v[42:45], v[86:89], v[238:241], v[42:45]
	v_mfma_f32_16x16x32_bf16 v[26:29], v[86:89], v[242:245], v[26:29]
	v_mfma_f32_16x16x32_bf16 v[10:13], v[86:89], v[246:249], v[10:13]
	v_mfma_f32_16x16x32_bf16 v[54:57], v[90:93], v[234:237], v[54:57]
	v_mfma_f32_16x16x32_bf16 v[38:41], v[90:93], v[238:241], v[38:41]
	v_mfma_f32_16x16x32_bf16 v[22:25], v[90:93], v[242:245], v[22:25]
	v_mfma_f32_16x16x32_bf16 v[6:9], v[90:93], v[246:249], v[6:9]
	v_mfma_f32_16x16x32_bf16 v[50:53], v[94:97], v[234:237], v[50:53]
	v_mfma_f32_16x16x32_bf16 v[34:37], v[94:97], v[238:241], v[34:37]
	v_mfma_f32_16x16x32_bf16 v[18:21], v[94:97], v[242:245], v[18:21]
	v_mfma_f32_16x16x32_bf16 v[2:5], v[94:97], v[246:249], v[2:5]
	ds_read_b128 v[234:237], v103 offset:0
	ds_read_b128 v[238:241], v103 offset:2048
	ds_read_b128 v[242:245], v103 offset:4096
	ds_read_b128 v[246:249], v103 offset:6144
	s_waitcnt lgkmcnt(4)
	v_mfma_f32_16x16x32_bf16 v[106:109], v[66:69], v[218:221], v[106:109]
	v_mfma_f32_16x16x32_bf16 v[122:125], v[66:69], v[222:225], v[122:125]
	v_mfma_f32_16x16x32_bf16 v[138:141], v[66:69], v[226:229], v[138:141]
	v_mfma_f32_16x16x32_bf16 v[162:165], v[66:69], v[230:233], v[162:165]
	v_mfma_f32_16x16x32_bf16 v[110:113], v[70:73], v[218:221], v[110:113]
	v_mfma_f32_16x16x32_bf16 v[126:129], v[70:73], v[222:225], v[126:129]
	v_mfma_f32_16x16x32_bf16 v[142:145], v[70:73], v[226:229], v[142:145]
	v_mfma_f32_16x16x32_bf16 v[166:169], v[70:73], v[230:233], v[166:169]
	v_mfma_f32_16x16x32_bf16 v[114:117], v[74:77], v[218:221], v[114:117]
	v_mfma_f32_16x16x32_bf16 v[130:133], v[74:77], v[222:225], v[130:133]
	v_mfma_f32_16x16x32_bf16 v[154:157], v[74:77], v[226:229], v[154:157]
	v_mfma_f32_16x16x32_bf16 v[170:173], v[74:77], v[230:233], v[170:173]
	v_mfma_f32_16x16x32_bf16 v[118:121], v[78:81], v[218:221], v[118:121]
	v_mfma_f32_16x16x32_bf16 v[134:137], v[78:81], v[222:225], v[134:137]
	v_mfma_f32_16x16x32_bf16 v[158:161], v[78:81], v[226:229], v[158:161]
	v_mfma_f32_16x16x32_bf16 v[174:177], v[78:81], v[230:233], v[174:177]
	s_waitcnt lgkmcnt(0)
	v_mfma_f32_16x16x32_bf16 v[106:109], v[82:85], v[234:237], v[106:109]
	v_mfma_f32_16x16x32_bf16 v[122:125], v[82:85], v[238:241], v[122:125]
	v_mfma_f32_16x16x32_bf16 v[138:141], v[82:85], v[242:245], v[138:141]
	v_mfma_f32_16x16x32_bf16 v[162:165], v[82:85], v[246:249], v[162:165]
	v_mfma_f32_16x16x32_bf16 v[110:113], v[86:89], v[234:237], v[110:113]
	v_mfma_f32_16x16x32_bf16 v[126:129], v[86:89], v[238:241], v[126:129]
	v_mfma_f32_16x16x32_bf16 v[142:145], v[86:89], v[242:245], v[142:145]
	v_mfma_f32_16x16x32_bf16 v[166:169], v[86:89], v[246:249], v[166:169]
	v_mfma_f32_16x16x32_bf16 v[114:117], v[90:93], v[234:237], v[114:117]
	v_mfma_f32_16x16x32_bf16 v[130:133], v[90:93], v[238:241], v[130:133]
	v_mfma_f32_16x16x32_bf16 v[154:157], v[90:93], v[242:245], v[154:157]
	v_mfma_f32_16x16x32_bf16 v[170:173], v[90:93], v[246:249], v[170:173]
	v_mfma_f32_16x16x32_bf16 v[118:121], v[94:97], v[234:237], v[118:121]
	v_mfma_f32_16x16x32_bf16 v[134:137], v[94:97], v[238:241], v[134:137]
	v_mfma_f32_16x16x32_bf16 v[158:161], v[94:97], v[242:245], v[158:161]
	v_mfma_f32_16x16x32_bf16 v[174:177], v[94:97], v[246:249], v[174:177]
	s_nop 7
	s_barrier
	s_and_b32 s5, s100, 0xff
	s_cmp_lt_u32 s5, 4
	s_cbranch_scc0 .Lpk_sw_nopf
	s_add_i32 s5, s5, 1
	s_lshl_b32 s5, s5, 6
	v_readlane_b32 s6, v254, 7
	s_add_i32 s5, s5, s6
	s_mul_hi_u32 s6, s5, 0x924924a
	s_mul_i32 s7, s6, 28
	s_sub_u32 s5, s5, s7
	s_mul_hi_u32 s7, s5, 0x24924925
	s_mul_i32 s28, s7, 7
	s_sub_u32 s5, s5, s28
	s_and_b32 s28, s6, 3
	s_mul_i32 s28, s28, 7
	s_add_i32 s28, s28, s5
	s_lshl_b32 s48, s28, 18
	s_add_u32 s48, s12, s48
	s_addc_u32 s49, s13, 0
	s_lshr_b32 s6, s6, 2
	s_lshl_b32 s6, s6, 3
	v_readlane_b32 s5, v254, 6
	s_or_b32 s6, s6, s5
	s_lshl_b32 s6, s6, 3
	s_lshl_b32 s7, s7, 1
	s_add_i32 s6, s6, s7
	s_lshl_b32 s6, s6, 18
	s_add_u32 s28, s94, s6
	s_addc_u32 s29, s95, 0
	v_add_u32_e32 v98, 0xfffff800, v98
	v_add_u32_e32 v99, 0xfffff800, v99
	v_add_u32_e32 v100, 0xfffff800, v100
	v_add_u32_e32 v101, 0xfffff800, v101
	s_add_u32 m0, s4, 0xc000
	s_nop 0
	global_load_lds_dwordx4 v98, s[28:29]
	s_add_u32 m0, s4, 0xc400
	s_nop 0
	global_load_lds_dwordx4 v99, s[28:29]
	s_add_u32 m0, s4, 0xc800
	s_nop 0
	global_load_lds_dwordx4 v100, s[28:29]
	s_add_u32 m0, s4, 0xcc00
	s_nop 0
	global_load_lds_dwordx4 v101, s[28:29]
	s_add_u32 m0, s4, 0x10000
	s_nop 0
	global_load_lds_dwordx4 v98, s[48:49]
	s_add_u32 m0, s4, 0x10400
	s_nop 0
	global_load_lds_dwordx4 v99, s[48:49]
	s_add_u32 m0, s4, 0x10800
	s_nop 0
	global_load_lds_dwordx4 v100, s[48:49]
	s_add_u32 m0, s4, 0x10c00
	s_nop 0
	global_load_lds_dwordx4 v101, s[48:49]
	s_or_b32 s100, s100, 0x1000
	s_branch .Lpk_sw_end

.Lpk_tt_pf:
	s_and_b32 s100, s100, 0xffffefff
	s_add_u32 m0, s4, 0x0
	s_nop 0
	global_load_lds_dwordx4 v98, s[6:7]
	s_add_u32 m0, s4, 0x400
	s_nop 0
	global_load_lds_dwordx4 v99, s[6:7]
	s_add_u32 m0, s4, 0x800
	s_nop 0
	global_load_lds_dwordx4 v100, s[6:7]
	s_add_u32 m0, s4, 0xc00
	s_nop 0
	global_load_lds_dwordx4 v101, s[6:7]
	v_add_u32_e32 v98, 0x80, v98
	v_add_u32_e32 v99, 0x80, v99
	v_add_u32_e32 v100, 0x80, v100
	v_add_u32_e32 v101, 0x80, v101
	s_add_u32 m0, s4, 0x8000
	s_nop 0
	global_load_lds_dwordx4 v98, s[48:49]
	s_add_u32 m0, s4, 0x8400
	s_nop 0
	global_load_lds_dwordx4 v99, s[48:49]
	s_add_u32 m0, s4, 0x8800
	s_nop 0
	global_load_lds_dwordx4 v100, s[48:49]
	s_add_u32 m0, s4, 0x8c00
	s_nop 0
	global_load_lds_dwordx4 v101, s[48:49]
	s_add_u32 m0, s4, 0x4000
	s_nop 0
	global_load_lds_dwordx4 v98, s[28:29]
	s_add_u32 m0, s4, 0x4400
	s_nop 0
	global_load_lds_dwordx4 v99, s[28:29]
	s_add_u32 m0, s4, 0x4800
	s_nop 0
	global_load_lds_dwordx4 v100, s[28:29]
	s_add_u32 m0, s4, 0x4c00
	s_nop 0
	global_load_lds_dwordx4 v101, s[28:29]
	v_mov_b32_e32 v62, 0
	v_mov_b32_e32 v106, 0
	v_mov_b32_e32 v63, 0
	v_mov_b32_e32 v107, 0
	v_mov_b32_e32 v64, 0
	v_mov_b32_e32 v108, 0
	v_mov_b32_e32 v65, 0
	v_mov_b32_e32 v109, 0
	v_mov_b32_e32 v58, 0
	v_mov_b32_e32 v110, 0
	v_mov_b32_e32 v59, 0
	v_mov_b32_e32 v111, 0
	v_mov_b32_e32 v60, 0
	v_mov_b32_e32 v112, 0
	v_mov_b32_e32 v61, 0
	v_mov_b32_e32 v113, 0
	v_mov_b32_e32 v54, 0
	v_mov_b32_e32 v114, 0
	v_mov_b32_e32 v55, 0
	v_mov_b32_e32 v115, 0
	v_mov_b32_e32 v56, 0
	v_mov_b32_e32 v116, 0
	v_mov_b32_e32 v57, 0
	v_mov_b32_e32 v117, 0
	v_mov_b32_e32 v50, 0
	v_mov_b32_e32 v118, 0
	v_mov_b32_e32 v51, 0
	v_mov_b32_e32 v119, 0
	v_mov_b32_e32 v52, 0
	v_mov_b32_e32 v120, 0
	v_mov_b32_e32 v53, 0
	v_mov_b32_e32 v121, 0
	v_mov_b32_e32 v46, 0
	v_mov_b32_e32 v122, 0
	v_mov_b32_e32 v47, 0
	v_mov_b32_e32 v123, 0
	v_mov_b32_e32 v48, 0
	v_mov_b32_e32 v124, 0
	v_mov_b32_e32 v49, 0
	v_mov_b32_e32 v125, 0
	v_mov_b32_e32 v42, 0
	v_mov_b32_e32 v126, 0
	v_mov_b32_e32 v43, 0
	v_mov_b32_e32 v127, 0
	v_mov_b32_e32 v44, 0
	v_mov_b32_e32 v128, 0
	v_mov_b32_e32 v45, 0
	v_mov_b32_e32 v129, 0
	v_mov_b32_e32 v38, 0
	v_mov_b32_e32 v130, 0
	v_mov_b32_e32 v39, 0
	v_mov_b32_e32 v131, 0
	v_mov_b32_e32 v40, 0
	v_mov_b32_e32 v132, 0
	v_mov_b32_e32 v41, 0
	v_mov_b32_e32 v133, 0
	v_mov_b32_e32 v34, 0
	v_mov_b32_e32 v134, 0
	v_mov_b32_e32 v35, 0
	v_mov_b32_e32 v135, 0
	v_mov_b32_e32 v36, 0
	v_mov_b32_e32 v136, 0
	v_mov_b32_e32 v37, 0
	v_mov_b32_e32 v137, 0
	v_mov_b32_e32 v30, 0
	v_mov_b32_e32 v138, 0
	v_mov_b32_e32 v31, 0
	v_mov_b32_e32 v139, 0
	v_mov_b32_e32 v32, 0
	v_mov_b32_e32 v140, 0
	v_mov_b32_e32 v33, 0
	v_mov_b32_e32 v141, 0
	v_mov_b32_e32 v26, 0
	v_mov_b32_e32 v142, 0
	v_mov_b32_e32 v27, 0
	v_mov_b32_e32 v143, 0
	v_mov_b32_e32 v28, 0
	v_mov_b32_e32 v144, 0
	v_mov_b32_e32 v29, 0
	v_mov_b32_e32 v145, 0
	v_mov_b32_e32 v22, 0
	v_mov_b32_e32 v154, 0
	v_mov_b32_e32 v23, 0
	v_mov_b32_e32 v155, 0
	v_mov_b32_e32 v24, 0
	v_mov_b32_e32 v156, 0
	v_mov_b32_e32 v25, 0
	v_mov_b32_e32 v157, 0
	v_mov_b32_e32 v18, 0
	v_mov_b32_e32 v158, 0
	v_mov_b32_e32 v19, 0
	v_mov_b32_e32 v159, 0
	v_mov_b32_e32 v20, 0
	v_mov_b32_e32 v160, 0
	v_mov_b32_e32 v21, 0
	v_mov_b32_e32 v161, 0
	v_mov_b32_e32 v14, 0
	v_mov_b32_e32 v162, 0
	v_mov_b32_e32 v15, 0
	v_mov_b32_e32 v163, 0
	v_mov_b32_e32 v16, 0
	v_mov_b32_e32 v164, 0
	v_mov_b32_e32 v17, 0
	v_mov_b32_e32 v165, 0
	v_mov_b32_e32 v10, 0
	v_mov_b32_e32 v166, 0
	v_mov_b32_e32 v11, 0
	v_mov_b32_e32 v167, 0
	v_mov_b32_e32 v12, 0
	v_mov_b32_e32 v168, 0
	v_mov_b32_e32 v13, 0
	v_mov_b32_e32 v169, 0
	v_mov_b32_e32 v6, 0
	v_mov_b32_e32 v170, 0
	v_mov_b32_e32 v7, 0
	v_mov_b32_e32 v171, 0
	v_mov_b32_e32 v8, 0
	v_mov_b32_e32 v172, 0
	v_mov_b32_e32 v9, 0
	v_mov_b32_e32 v173, 0
	v_mov_b32_e32 v2, 0
	v_mov_b32_e32 v174, 0
	v_mov_b32_e32 v3, 0
	v_mov_b32_e32 v175, 0
	v_mov_b32_e32 v4, 0
	v_mov_b32_e32 v176, 0
	v_mov_b32_e32 v5, 0
	v_mov_b32_e32 v177, 0
	s_waitcnt vmcnt(12)
	s_barrier
	ds_read_b128 v[218:221], v102 offset:49152
	ds_read_b128 v[222:225], v102 offset:51200
	ds_read_b128 v[226:229], v102 offset:53248
	ds_read_b128 v[230:233], v102 offset:55296
	ds_read_b128 v[66:69], v250 offset:49152
	ds_read_b128 v[70:73], v250 offset:51200
	ds_read_b128 v[74:77], v250 offset:53248
	ds_read_b128 v[78:81], v250 offset:55296
	ds_read_b128 v[234:237], v103 offset:49152
	ds_read_b128 v[238:241], v103 offset:51200
	ds_read_b128 v[242:245], v103 offset:53248
	ds_read_b128 v[246:249], v103 offset:55296
	ds_read_b128 v[82:85], v251 offset:49152
	ds_read_b128 v[86:89], v251 offset:51200
	ds_read_b128 v[90:93], v251 offset:53248
	ds_read_b128 v[94:97], v251 offset:55296
	s_waitcnt lgkmcnt(8)
	v_mfma_f32_16x16x32_bf16 v[62:65], v[218:221], v[66:69], v[62:65]
	v_mfma_f32_16x16x32_bf16 v[46:49], v[222:225], v[66:69], v[46:49]
	v_mfma_f32_16x16x32_bf16 v[30:33], v[226:229], v[66:69], v[30:33]
	v_mfma_f32_16x16x32_bf16 v[14:17], v[230:233], v[66:69], v[14:17]
	v_mfma_f32_16x16x32_bf16 v[58:61], v[218:221], v[70:73], v[58:61]
	v_mfma_f32_16x16x32_bf16 v[42:45], v[222:225], v[70:73], v[42:45]
	v_mfma_f32_16x16x32_bf16 v[26:29], v[226:229], v[70:73], v[26:29]
	v_mfma_f32_16x16x32_bf16 v[10:13], v[230:233], v[70:73], v[10:13]
	v_mfma_f32_16x16x32_bf16 v[54:57], v[218:221], v[74:77], v[54:57]
	v_mfma_f32_16x16x32_bf16 v[38:41], v[222:225], v[74:77], v[38:41]
	v_mfma_f32_16x16x32_bf16 v[22:25], v[226:229], v[74:77], v[22:25]
	v_mfma_f32_16x16x32_bf16 v[6:9], v[230:233], v[74:77], v[6:9]
	v_mfma_f32_16x16x32_bf16 v[50:53], v[218:221], v[78:81], v[50:53]
	v_mfma_f32_16x16x32_bf16 v[34:37], v[222:225], v[78:81], v[34:37]
	v_mfma_f32_16x16x32_bf16 v[18:21], v[226:229], v[78:81], v[18:21]
	v_mfma_f32_16x16x32_bf16 v[2:5], v[230:233], v[78:81], v[2:5]
	s_waitcnt lgkmcnt(0)
	s_waitcnt vmcnt(8)
	s_barrier
	ds_read_b128 v[218:221], v102 offset:0
	ds_read_b128 v[222:225], v102 offset:2048
	ds_read_b128 v[226:229], v102 offset:4096
	ds_read_b128 v[230:233], v102 offset:6144
	v_mfma_f32_16x16x32_bf16 v[62:65], v[234:237], v[82:85], v[62:65]
	s_add_u32 m0, s4, 0xc000
	v_mfma_f32_16x16x32_bf16 v[46:49], v[238:241], v[82:85], v[46:49]
	global_load_lds_dwordx4 v98, s[6:7]
	v_mfma_f32_16x16x32_bf16 v[30:33], v[242:245], v[82:85], v[30:33]
	v_mfma_f32_16x16x32_bf16 v[14:17], v[246:249], v[82:85], v[14:17]
	v_mfma_f32_16x16x32_bf16 v[58:61], v[234:237], v[86:89], v[58:61]
	s_add_u32 m0, s4, 0xc400
	v_mfma_f32_16x16x32_bf16 v[42:45], v[238:241], v[86:89], v[42:45]
	global_load_lds_dwordx4 v99, s[6:7]
	v_mfma_f32_16x16x32_bf16 v[26:29], v[242:245], v[86:89], v[26:29]
	v_mfma_f32_16x16x32_bf16 v[10:13], v[246:249], v[86:89], v[10:13]
	v_mfma_f32_16x16x32_bf16 v[54:57], v[234:237], v[90:93], v[54:57]
	s_add_u32 m0, s4, 0xc800
	v_mfma_f32_16x16x32_bf16 v[38:41], v[238:241], v[90:93], v[38:41]
	global_load_lds_dwordx4 v100, s[6:7]
	v_mfma_f32_16x16x32_bf16 v[22:25], v[242:245], v[90:93], v[22:25]
	v_mfma_f32_16x16x32_bf16 v[6:9], v[246:249], v[90:93], v[6:9]
	v_mfma_f32_16x16x32_bf16 v[50:53], v[234:237], v[94:97], v[50:53]
	s_add_u32 m0, s4, 0xcc00
	v_mfma_f32_16x16x32_bf16 v[34:37], v[238:241], v[94:97], v[34:37]
	global_load_lds_dwordx4 v101, s[6:7]
	v_mfma_f32_16x16x32_bf16 v[18:21], v[242:245], v[94:97], v[18:21]
	v_mfma_f32_16x16x32_bf16 v[2:5], v[246:249], v[94:97], v[2:5]
	v_add_u32_e32 v98, 0x80, v98
	v_add_u32_e32 v99, 0x80, v99
	v_add_u32_e32 v100, 0x80, v100
	v_add_u32_e32 v101, 0x80, v101
	ds_read_b128 v[234:237], v103 offset:0
	ds_read_b128 v[238:241], v103 offset:2048
	ds_read_b128 v[242:245], v103 offset:4096
	ds_read_b128 v[246:249], v103 offset:6144
	s_waitcnt lgkmcnt(4)
	v_mfma_f32_16x16x32_bf16 v[106:109], v[218:221], v[66:69], v[106:109]
	s_add_u32 m0, s4, 0x10000
	v_mfma_f32_16x16x32_bf16 v[122:125], v[222:225], v[66:69], v[122:125]
	global_load_lds_dwordx4 v98, s[48:49]
	v_mfma_f32_16x16x32_bf16 v[138:141], v[226:229], v[66:69], v[138:141]
	v_mfma_f32_16x16x32_bf16 v[162:165], v[230:233], v[66:69], v[162:165]
	v_mfma_f32_16x16x32_bf16 v[110:113], v[218:221], v[70:73], v[110:113]
	s_add_u32 m0, s4, 0x10400
	v_mfma_f32_16x16x32_bf16 v[126:129], v[222:225], v[70:73], v[126:129]
	global_load_lds_dwordx4 v99, s[48:49]
	v_mfma_f32_16x16x32_bf16 v[142:145], v[226:229], v[70:73], v[142:145]
	v_mfma_f32_16x16x32_bf16 v[166:169], v[230:233], v[70:73], v[166:169]
	v_mfma_f32_16x16x32_bf16 v[114:117], v[218:221], v[74:77], v[114:117]
	s_add_u32 m0, s4, 0x10800
	v_mfma_f32_16x16x32_bf16 v[130:133], v[222:225], v[74:77], v[130:133]
	global_load_lds_dwordx4 v100, s[48:49]
	v_mfma_f32_16x16x32_bf16 v[154:157], v[226:229], v[74:77], v[154:157]
	v_mfma_f32_16x16x32_bf16 v[170:173], v[230:233], v[74:77], v[170:173]
	v_mfma_f32_16x16x32_bf16 v[118:121], v[218:221], v[78:81], v[118:121]
	s_add_u32 m0, s4, 0x10c00
	v_mfma_f32_16x16x32_bf16 v[134:137], v[222:225], v[78:81], v[134:137]
	global_load_lds_dwordx4 v101, s[48:49]
	v_mfma_f32_16x16x32_bf16 v[158:161], v[226:229], v[78:81], v[158:161]
	v_mfma_f32_16x16x32_bf16 v[174:177], v[230:233], v[78:81], v[174:177]
	s_waitcnt lgkmcnt(0)
	s_waitcnt vmcnt(8)
	s_barrier
	ds_read_b128 v[218:221], v102 offset:16384
	ds_read_b128 v[222:225], v102 offset:18432
	ds_read_b128 v[226:229], v102 offset:20480
	ds_read_b128 v[230:233], v102 offset:22528
	ds_read_b128 v[66:69], v104 offset:32768
	ds_read_b128 v[70:73], v104 offset:34816
	ds_read_b128 v[74:77], v104 offset:36864
	ds_read_b128 v[78:81], v104 offset:38912
	v_mfma_f32_16x16x32_bf16 v[106:109], v[234:237], v[82:85], v[106:109]
	s_add_u32 m0, s4, 0x0
	v_mfma_f32_16x16x32_bf16 v[122:125], v[238:241], v[82:85], v[122:125]
	global_load_lds_dwordx4 v98, s[28:29]
	v_mfma_f32_16x16x32_bf16 v[138:141], v[242:245], v[82:85], v[138:141]
	v_mfma_f32_16x16x32_bf16 v[162:165], v[246:249], v[82:85], v[162:165]
	v_mfma_f32_16x16x32_bf16 v[110:113], v[234:237], v[86:89], v[110:113]
	s_add_u32 m0, s4, 0x400
	v_mfma_f32_16x16x32_bf16 v[126:129], v[238:241], v[86:89], v[126:129]
	global_load_lds_dwordx4 v99, s[28:29]
	v_mfma_f32_16x16x32_bf16 v[142:145], v[242:245], v[86:89], v[142:145]
	v_mfma_f32_16x16x32_bf16 v[166:169], v[246:249], v[86:89], v[166:169]
	v_mfma_f32_16x16x32_bf16 v[114:117], v[234:237], v[90:93], v[114:117]
	v_mfma_f32_16x16x32_bf16 v[130:133], v[238:241], v[90:93], v[130:133]
	v_mfma_f32_16x16x32_bf16 v[154:157], v[242:245], v[90:93], v[154:157]
	v_mfma_f32_16x16x32_bf16 v[170:173], v[246:249], v[90:93], v[170:173]
	v_mfma_f32_16x16x32_bf16 v[118:121], v[234:237], v[94:97], v[118:121]
	v_mfma_f32_16x16x32_bf16 v[134:137], v[238:241], v[94:97], v[134:137]
	v_mfma_f32_16x16x32_bf16 v[158:161], v[242:245], v[94:97], v[158:161]
	v_mfma_f32_16x16x32_bf16 v[174:177], v[246:249], v[94:97], v[174:177]
	ds_read_b128 v[234:237], v103 offset:16384
	ds_read_b128 v[238:241], v103 offset:18432
	ds_read_b128 v[242:245], v103 offset:20480
	ds_read_b128 v[246:249], v103 offset:22528
	ds_read_b128 v[82:85], v105 offset:32768
	ds_read_b128 v[86:89], v105 offset:34816
	ds_read_b128 v[90:93], v105 offset:36864
	ds_read_b128 v[94:97], v105 offset:38912
	s_waitcnt lgkmcnt(8)
	v_mfma_f32_16x16x32_bf16 v[62:65], v[218:221], v[66:69], v[62:65]
	s_add_u32 m0, s4, 0x800
	v_mfma_f32_16x16x32_bf16 v[46:49], v[222:225], v[66:69], v[46:49]
	global_load_lds_dwordx4 v100, s[28:29]
	v_mfma_f32_16x16x32_bf16 v[30:33], v[226:229], v[66:69], v[30:33]
	v_mfma_f32_16x16x32_bf16 v[14:17], v[230:233], v[66:69], v[14:17]
	v_mfma_f32_16x16x32_bf16 v[58:61], v[218:221], v[70:73], v[58:61]
	s_add_u32 m0, s4, 0xc00
	v_mfma_f32_16x16x32_bf16 v[42:45], v[222:225], v[70:73], v[42:45]
	global_load_lds_dwordx4 v101, s[28:29]
	v_mfma_f32_16x16x32_bf16 v[26:29], v[226:229], v[70:73], v[26:29]
	v_mfma_f32_16x16x32_bf16 v[10:13], v[230:233], v[70:73], v[10:13]
	v_mfma_f32_16x16x32_bf16 v[54:57], v[218:221], v[74:77], v[54:57]
	v_mfma_f32_16x16x32_bf16 v[38:41], v[222:225], v[74:77], v[38:41]
	v_mfma_f32_16x16x32_bf16 v[22:25], v[226:229], v[74:77], v[22:25]
	v_mfma_f32_16x16x32_bf16 v[6:9], v[230:233], v[74:77], v[6:9]
	v_mfma_f32_16x16x32_bf16 v[50:53], v[218:221], v[78:81], v[50:53]
	v_mfma_f32_16x16x32_bf16 v[34:37], v[222:225], v[78:81], v[34:37]
	v_mfma_f32_16x16x32_bf16 v[18:21], v[226:229], v[78:81], v[18:21]
	v_mfma_f32_16x16x32_bf16 v[2:5], v[230:233], v[78:81], v[2:5]
	s_waitcnt lgkmcnt(0)
	s_waitcnt vmcnt(8)
	s_barrier
	ds_read_b128 v[218:221], v102 offset:49152
	ds_read_b128 v[222:225], v102 offset:51200
	ds_read_b128 v[226:229], v102 offset:53248
	ds_read_b128 v[230:233], v102 offset:55296
	v_mfma_f32_16x16x32_bf16 v[62:65], v[234:237], v[82:85], v[62:65]
	s_add_u32 m0, s4, 0x4000
	v_mfma_f32_16x16x32_bf16 v[46:49], v[238:241], v[82:85], v[46:49]
	global_load_lds_dwordx4 v98, s[6:7]
	v_mfma_f32_16x16x32_bf16 v[30:33], v[242:245], v[82:85], v[30:33]
	v_mfma_f32_16x16x32_bf16 v[14:17], v[246:249], v[82:85], v[14:17]
	v_mfma_f32_16x16x32_bf16 v[58:61], v[234:237], v[86:89], v[58:61]
	s_add_u32 m0, s4, 0x4400
	v_mfma_f32_16x16x32_bf16 v[42:45], v[238:241], v[86:89], v[42:45]
	global_load_lds_dwordx4 v99, s[6:7]
	v_mfma_f32_16x16x32_bf16 v[26:29], v[242:245], v[86:89], v[26:29]
	v_mfma_f32_16x16x32_bf16 v[10:13], v[246:249], v[86:89], v[10:13]
	v_mfma_f32_16x16x32_bf16 v[54:57], v[234:237], v[90:93], v[54:57]
	s_add_u32 m0, s4, 0x4800
	v_mfma_f32_16x16x32_bf16 v[38:41], v[238:241], v[90:93], v[38:41]
	global_load_lds_dwordx4 v100, s[6:7]
	v_mfma_f32_16x16x32_bf16 v[22:25], v[242:245], v[90:93], v[22:25]
	v_mfma_f32_16x16x32_bf16 v[6:9], v[246:249], v[90:93], v[6:9]
	v_mfma_f32_16x16x32_bf16 v[50:53], v[234:237], v[94:97], v[50:53]
	s_add_u32 m0, s4, 0x4c00
	v_mfma_f32_16x16x32_bf16 v[34:37], v[238:241], v[94:97], v[34:37]
	global_load_lds_dwordx4 v101, s[6:7]
	v_mfma_f32_16x16x32_bf16 v[18:21], v[242:245], v[94:97], v[18:21]
	v_mfma_f32_16x16x32_bf16 v[2:5], v[246:249], v[94:97], v[2:5]
	v_add_u32_e32 v98, 0x80, v98
	v_add_u32_e32 v99, 0x80, v99
	v_add_u32_e32 v100, 0x80, v100
	v_add_u32_e32 v101, 0x80, v101
	ds_read_b128 v[234:237], v103 offset:49152
	ds_read_b128 v[238:241], v103 offset:51200
	ds_read_b128 v[242:245], v103 offset:53248
	ds_read_b128 v[246:249], v103 offset:55296
	s_waitcnt lgkmcnt(4)
	v_mfma_f32_16x16x32_bf16 v[106:109], v[218:221], v[66:69], v[106:109]
	s_add_u32 m0, s4, 0x8000
	v_mfma_f32_16x16x32_bf16 v[122:125], v[222:225], v[66:69], v[122:125]
	global_load_lds_dwordx4 v98, s[48:49]
	v_mfma_f32_16x16x32_bf16 v[138:141], v[226:229], v[66:69], v[138:141]
	v_mfma_f32_16x16x32_bf16 v[162:165], v[230:233], v[66:69], v[162:165]
	v_mfma_f32_16x16x32_bf16 v[110:113], v[218:221], v[70:73], v[110:113]
	s_add_u32 m0, s4, 0x8400
	v_mfma_f32_16x16x32_bf16 v[126:129], v[222:225], v[70:73], v[126:129]
	global_load_lds_dwordx4 v99, s[48:49]
	v_mfma_f32_16x16x32_bf16 v[142:145], v[226:229], v[70:73], v[142:145]
	v_mfma_f32_16x16x32_bf16 v[166:169], v[230:233], v[70:73], v[166:169]
	v_mfma_f32_16x16x32_bf16 v[114:117], v[218:221], v[74:77], v[114:117]
	s_add_u32 m0, s4, 0x8800
	v_mfma_f32_16x16x32_bf16 v[130:133], v[222:225], v[74:77], v[130:133]
	global_load_lds_dwordx4 v100, s[48:49]
	v_mfma_f32_16x16x32_bf16 v[154:157], v[226:229], v[74:77], v[154:157]
	v_mfma_f32_16x16x32_bf16 v[170:173], v[230:233], v[74:77], v[170:173]
	v_mfma_f32_16x16x32_bf16 v[118:121], v[218:221], v[78:81], v[118:121]
	s_add_u32 m0, s4, 0x8c00
	v_mfma_f32_16x16x32_bf16 v[134:137], v[222:225], v[78:81], v[134:137]
	global_load_lds_dwordx4 v101, s[48:49]
	v_mfma_f32_16x16x32_bf16 v[158:161], v[226:229], v[78:81], v[158:161]
	v_mfma_f32_16x16x32_bf16 v[174:177], v[230:233], v[78:81], v[174:177]
	s_waitcnt lgkmcnt(0)
	s_waitcnt vmcnt(8)
	s_barrier
	ds_read_b128 v[218:221], v102 offset:0
	ds_read_b128 v[222:225], v102 offset:2048
	ds_read_b128 v[226:229], v102 offset:4096
	ds_read_b128 v[230:233], v102 offset:6144
	ds_read_b128 v[66:69], v250 offset:49152
	ds_read_b128 v[70:73], v250 offset:51200
	ds_read_b128 v[74:77], v250 offset:53248
	ds_read_b128 v[78:81], v250 offset:55296
	v_mfma_f32_16x16x32_bf16 v[106:109], v[234:237], v[82:85], v[106:109]
	s_add_u32 m0, s4, 0xc000
	v_mfma_f32_16x16x32_bf16 v[122:125], v[238:241], v[82:85], v[122:125]
	global_load_lds_dwordx4 v98, s[28:29]
	v_mfma_f32_16x16x32_bf16 v[138:141], v[242:245], v[82:85], v[138:141]
	v_mfma_f32_16x16x32_bf16 v[162:165], v[246:249], v[82:85], v[162:165]
	v_mfma_f32_16x16x32_bf16 v[110:113], v[234:237], v[86:89], v[110:113]
	s_add_u32 m0, s4, 0xc400
	v_mfma_f32_16x16x32_bf16 v[126:129], v[238:241], v[86:89], v[126:129]
	global_load_lds_dwordx4 v99, s[28:29]
	v_mfma_f32_16x16x32_bf16 v[142:145], v[242:245], v[86:89], v[142:145]
	v_mfma_f32_16x16x32_bf16 v[166:169], v[246:249], v[86:89], v[166:169]
	v_mfma_f32_16x16x32_bf16 v[114:117], v[234:237], v[90:93], v[114:117]
	v_mfma_f32_16x16x32_bf16 v[130:133], v[238:241], v[90:93], v[130:133]
	v_mfma_f32_16x16x32_bf16 v[154:157], v[242:245], v[90:93], v[154:157]
	v_mfma_f32_16x16x32_bf16 v[170:173], v[246:249], v[90:93], v[170:173]
	v_mfma_f32_16x16x32_bf16 v[118:121], v[234:237], v[94:97], v[118:121]
	v_mfma_f32_16x16x32_bf16 v[134:137], v[238:241], v[94:97], v[134:137]
	v_mfma_f32_16x16x32_bf16 v[158:161], v[242:245], v[94:97], v[158:161]
	v_mfma_f32_16x16x32_bf16 v[174:177], v[246:249], v[94:97], v[174:177]
	ds_read_b128 v[234:237], v103 offset:0
	ds_read_b128 v[238:241], v103 offset:2048
	ds_read_b128 v[242:245], v103 offset:4096
	ds_read_b128 v[246:249], v103 offset:6144
	ds_read_b128 v[82:85], v251 offset:49152
	ds_read_b128 v[86:89], v251 offset:51200
	ds_read_b128 v[90:93], v251 offset:53248
	ds_read_b128 v[94:97], v251 offset:55296
	s_waitcnt lgkmcnt(8)
	v_mfma_f32_16x16x32_bf16 v[62:65], v[218:221], v[66:69], v[62:65]
	s_add_u32 m0, s4, 0xc800
	v_mfma_f32_16x16x32_bf16 v[46:49], v[222:225], v[66:69], v[46:49]
	global_load_lds_dwordx4 v100, s[28:29]
	v_mfma_f32_16x16x32_bf16 v[30:33], v[226:229], v[66:69], v[30:33]
	v_mfma_f32_16x16x32_bf16 v[14:17], v[230:233], v[66:69], v[14:17]
	v_mfma_f32_16x16x32_bf16 v[58:61], v[218:221], v[70:73], v[58:61]
	s_add_u32 m0, s4, 0xcc00
	v_mfma_f32_16x16x32_bf16 v[42:45], v[222:225], v[70:73], v[42:45]
	global_load_lds_dwordx4 v101, s[28:29]
	v_mfma_f32_16x16x32_bf16 v[26:29], v[226:229], v[70:73], v[26:29]
	v_mfma_f32_16x16x32_bf16 v[10:13], v[230:233], v[70:73], v[10:13]
	v_mfma_f32_16x16x32_bf16 v[54:57], v[218:221], v[74:77], v[54:57]
	v_mfma_f32_16x16x32_bf16 v[38:41], v[222:225], v[74:77], v[38:41]
	v_mfma_f32_16x16x32_bf16 v[22:25], v[226:229], v[74:77], v[22:25]
	v_mfma_f32_16x16x32_bf16 v[6:9], v[230:233], v[74:77], v[6:9]
	v_mfma_f32_16x16x32_bf16 v[50:53], v[218:221], v[78:81], v[50:53]
	v_mfma_f32_16x16x32_bf16 v[34:37], v[222:225], v[78:81], v[34:37]
	v_mfma_f32_16x16x32_bf16 v[18:21], v[226:229], v[78:81], v[18:21]
	v_mfma_f32_16x16x32_bf16 v[2:5], v[230:233], v[78:81], v[2:5]
	s_waitcnt lgkmcnt(0)
	s_waitcnt vmcnt(8)
	s_barrier
	ds_read_b128 v[218:221], v102 offset:16384
	ds_read_b128 v[222:225], v102 offset:18432
	ds_read_b128 v[226:229], v102 offset:20480
	ds_read_b128 v[230:233], v102 offset:22528
	v_mfma_f32_16x16x32_bf16 v[62:65], v[234:237], v[82:85], v[62:65]
	s_add_u32 m0, s4, 0x0
	v_mfma_f32_16x16x32_bf16 v[46:49], v[238:241], v[82:85], v[46:49]
	global_load_lds_dwordx4 v98, s[6:7]
	v_mfma_f32_16x16x32_bf16 v[30:33], v[242:245], v[82:85], v[30:33]
	v_mfma_f32_16x16x32_bf16 v[14:17], v[246:249], v[82:85], v[14:17]
	v_mfma_f32_16x16x32_bf16 v[58:61], v[234:237], v[86:89], v[58:61]
	s_add_u32 m0, s4, 0x400
	v_mfma_f32_16x16x32_bf16 v[42:45], v[238:241], v[86:89], v[42:45]
	global_load_lds_dwordx4 v99, s[6:7]
	v_mfma_f32_16x16x32_bf16 v[26:29], v[242:245], v[86:89], v[26:29]
	v_mfma_f32_16x16x32_bf16 v[10:13], v[246:249], v[86:89], v[10:13]
	v_mfma_f32_16x16x32_bf16 v[54:57], v[234:237], v[90:93], v[54:57]
	s_add_u32 m0, s4, 0x800
	v_mfma_f32_16x16x32_bf16 v[38:41], v[238:241], v[90:93], v[38:41]
	global_load_lds_dwordx4 v100, s[6:7]
	v_mfma_f32_16x16x32_bf16 v[22:25], v[242:245], v[90:93], v[22:25]
	v_mfma_f32_16x16x32_bf16 v[6:9], v[246:249], v[90:93], v[6:9]
	v_mfma_f32_16x16x32_bf16 v[50:53], v[234:237], v[94:97], v[50:53]
	s_add_u32 m0, s4, 0xc00
	v_mfma_f32_16x16x32_bf16 v[34:37], v[238:241], v[94:97], v[34:37]
	global_load_lds_dwordx4 v101, s[6:7]
	v_mfma_f32_16x16x32_bf16 v[18:21], v[242:245], v[94:97], v[18:21]
	v_mfma_f32_16x16x32_bf16 v[2:5], v[246:249], v[94:97], v[2:5]
	v_add_u32_e32 v98, 0x80, v98
	v_add_u32_e32 v99, 0x80, v99
	v_add_u32_e32 v100, 0x80, v100
	v_add_u32_e32 v101, 0x80, v101
	ds_read_b128 v[234:237], v103 offset:16384
	ds_read_b128 v[238:241], v103 offset:18432
	ds_read_b128 v[242:245], v103 offset:20480
	ds_read_b128 v[246:249], v103 offset:22528
	s_waitcnt lgkmcnt(4)
	v_mfma_f32_16x16x32_bf16 v[106:109], v[218:221], v[66:69], v[106:109]
	s_add_u32 m0, s4, 0x10000
	v_mfma_f32_16x16x32_bf16 v[122:125], v[222:225], v[66:69], v[122:125]
	global_load_lds_dwordx4 v98, s[48:49]
	v_mfma_f32_16x16x32_bf16 v[138:141], v[226:229], v[66:69], v[138:141]
	v_mfma_f32_16x16x32_bf16 v[162:165], v[230:233], v[66:69], v[162:165]
	v_mfma_f32_16x16x32_bf16 v[110:113], v[218:221], v[70:73], v[110:113]
	s_add_u32 m0, s4, 0x10400
	v_mfma_f32_16x16x32_bf16 v[126:129], v[222:225], v[70:73], v[126:129]
	global_load_lds_dwordx4 v99, s[48:49]
	v_mfma_f32_16x16x32_bf16 v[142:145], v[226:229], v[70:73], v[142:145]
	v_mfma_f32_16x16x32_bf16 v[166:169], v[230:233], v[70:73], v[166:169]
	v_mfma_f32_16x16x32_bf16 v[114:117], v[218:221], v[74:77], v[114:117]
	s_add_u32 m0, s4, 0x10800
	v_mfma_f32_16x16x32_bf16 v[130:133], v[222:225], v[74:77], v[130:133]
	global_load_lds_dwordx4 v100, s[48:49]
	v_mfma_f32_16x16x32_bf16 v[154:157], v[226:229], v[74:77], v[154:157]
	v_mfma_f32_16x16x32_bf16 v[170:173], v[230:233], v[74:77], v[170:173]
	v_mfma_f32_16x16x32_bf16 v[118:121], v[218:221], v[78:81], v[118:121]
	s_add_u32 m0, s4, 0x10c00
	v_mfma_f32_16x16x32_bf16 v[134:137], v[222:225], v[78:81], v[134:137]
	global_load_lds_dwordx4 v101, s[48:49]
	v_mfma_f32_16x16x32_bf16 v[158:161], v[226:229], v[78:81], v[158:161]
	v_mfma_f32_16x16x32_bf16 v[174:177], v[230:233], v[78:81], v[174:177]
	s_waitcnt lgkmcnt(0)
	s_waitcnt vmcnt(8)
	s_barrier
	ds_read_b128 v[218:221], v102 offset:49152
	ds_read_b128 v[222:225], v102 offset:51200
	ds_read_b128 v[226:229], v102 offset:53248
	ds_read_b128 v[230:233], v102 offset:55296
	ds_read_b128 v[66:69], v104 offset:32768
	ds_read_b128 v[70:73], v104 offset:34816
	ds_read_b128 v[74:77], v104 offset:36864
	ds_read_b128 v[78:81], v104 offset:38912
	v_mfma_f32_16x16x32_bf16 v[106:109], v[234:237], v[82:85], v[106:109]
	s_add_u32 m0, s4, 0x4000
	v_mfma_f32_16x16x32_bf16 v[122:125], v[238:241], v[82:85], v[122:125]
	global_load_lds_dwordx4 v98, s[28:29]
	v_mfma_f32_16x16x32_bf16 v[138:141], v[242:245], v[82:85], v[138:141]
	v_mfma_f32_16x16x32_bf16 v[162:165], v[246:249], v[82:85], v[162:165]
	v_mfma_f32_16x16x32_bf16 v[110:113], v[234:237], v[86:89], v[110:113]
	s_add_u32 m0, s4, 0x4400
	v_mfma_f32_16x16x32_bf16 v[126:129], v[238:241], v[86:89], v[126:129]
	global_load_lds_dwordx4 v99, s[28:29]
	v_mfma_f32_16x16x32_bf16 v[142:145], v[242:245], v[86:89], v[142:145]
	v_mfma_f32_16x16x32_bf16 v[166:169], v[246:249], v[86:89], v[166:169]
	v_mfma_f32_16x16x32_bf16 v[114:117], v[234:237], v[90:93], v[114:117]
	v_mfma_f32_16x16x32_bf16 v[130:133], v[238:241], v[90:93], v[130:133]
	v_mfma_f32_16x16x32_bf16 v[154:157], v[242:245], v[90:93], v[154:157]
	v_mfma_f32_16x16x32_bf16 v[170:173], v[246:249], v[90:93], v[170:173]
	v_mfma_f32_16x16x32_bf16 v[118:121], v[234:237], v[94:97], v[118:121]
	v_mfma_f32_16x16x32_bf16 v[134:137], v[238:241], v[94:97], v[134:137]
	v_mfma_f32_16x16x32_bf16 v[158:161], v[242:245], v[94:97], v[158:161]
	v_mfma_f32_16x16x32_bf16 v[174:177], v[246:249], v[94:97], v[174:177]
	ds_read_b128 v[234:237], v103 offset:49152
	ds_read_b128 v[238:241], v103 offset:51200
	ds_read_b128 v[242:245], v103 offset:53248
	ds_read_b128 v[246:249], v103 offset:55296
	ds_read_b128 v[82:85], v105 offset:32768
	ds_read_b128 v[86:89], v105 offset:34816
	ds_read_b128 v[90:93], v105 offset:36864
	ds_read_b128 v[94:97], v105 offset:38912
	s_waitcnt lgkmcnt(8)
	v_mfma_f32_16x16x32_bf16 v[62:65], v[218:221], v[66:69], v[62:65]
	s_add_u32 m0, s4, 0x4800
	v_mfma_f32_16x16x32_bf16 v[46:49], v[222:225], v[66:69], v[46:49]
	global_load_lds_dwordx4 v100, s[28:29]
	v_mfma_f32_16x16x32_bf16 v[30:33], v[226:229], v[66:69], v[30:33]
	v_mfma_f32_16x16x32_bf16 v[14:17], v[230:233], v[66:69], v[14:17]
	v_mfma_f32_16x16x32_bf16 v[58:61], v[218:221], v[70:73], v[58:61]
	s_add_u32 m0, s4, 0x4c00
	v_mfma_f32_16x16x32_bf16 v[42:45], v[222:225], v[70:73], v[42:45]
	global_load_lds_dwordx4 v101, s[28:29]
	v_mfma_f32_16x16x32_bf16 v[26:29], v[226:229], v[70:73], v[26:29]
	v_mfma_f32_16x16x32_bf16 v[10:13], v[230:233], v[70:73], v[10:13]
	v_mfma_f32_16x16x32_bf16 v[54:57], v[218:221], v[74:77], v[54:57]
	v_mfma_f32_16x16x32_bf16 v[38:41], v[222:225], v[74:77], v[38:41]
	v_mfma_f32_16x16x32_bf16 v[22:25], v[226:229], v[74:77], v[22:25]
	v_mfma_f32_16x16x32_bf16 v[6:9], v[230:233], v[74:77], v[6:9]
	v_mfma_f32_16x16x32_bf16 v[50:53], v[218:221], v[78:81], v[50:53]
	v_mfma_f32_16x16x32_bf16 v[34:37], v[222:225], v[78:81], v[34:37]
	v_mfma_f32_16x16x32_bf16 v[18:21], v[226:229], v[78:81], v[18:21]
	v_mfma_f32_16x16x32_bf16 v[2:5], v[230:233], v[78:81], v[2:5]
	s_waitcnt lgkmcnt(0)
	s_waitcnt vmcnt(8)
	s_barrier
	ds_read_b128 v[218:221], v102 offset:0
	ds_read_b128 v[222:225], v102 offset:2048
	ds_read_b128 v[226:229], v102 offset:4096
	ds_read_b128 v[230:233], v102 offset:6144
	v_mfma_f32_16x16x32_bf16 v[62:65], v[234:237], v[82:85], v[62:65]
	s_add_u32 m0, s4, 0xc000
	v_mfma_f32_16x16x32_bf16 v[46:49], v[238:241], v[82:85], v[46:49]
	global_load_lds_dwordx4 v98, s[6:7]
	v_mfma_f32_16x16x32_bf16 v[30:33], v[242:245], v[82:85], v[30:33]
	v_mfma_f32_16x16x32_bf16 v[14:17], v[246:249], v[82:85], v[14:17]
	v_mfma_f32_16x16x32_bf16 v[58:61], v[234:237], v[86:89], v[58:61]
	s_add_u32 m0, s4, 0xc400
	v_mfma_f32_16x16x32_bf16 v[42:45], v[238:241], v[86:89], v[42:45]
	global_load_lds_dwordx4 v99, s[6:7]
	v_mfma_f32_16x16x32_bf16 v[26:29], v[242:245], v[86:89], v[26:29]
	v_mfma_f32_16x16x32_bf16 v[10:13], v[246:249], v[86:89], v[10:13]
	v_mfma_f32_16x16x32_bf16 v[54:57], v[234:237], v[90:93], v[54:57]
	s_add_u32 m0, s4, 0xc800
	v_mfma_f32_16x16x32_bf16 v[38:41], v[238:241], v[90:93], v[38:41]
	global_load_lds_dwordx4 v100, s[6:7]
	v_mfma_f32_16x16x32_bf16 v[22:25], v[242:245], v[90:93], v[22:25]
	v_mfma_f32_16x16x32_bf16 v[6:9], v[246:249], v[90:93], v[6:9]
	v_mfma_f32_16x16x32_bf16 v[50:53], v[234:237], v[94:97], v[50:53]
	s_add_u32 m0, s4, 0xcc00
	v_mfma_f32_16x16x32_bf16 v[34:37], v[238:241], v[94:97], v[34:37]
	global_load_lds_dwordx4 v101, s[6:7]
	v_mfma_f32_16x16x32_bf16 v[18:21], v[242:245], v[94:97], v[18:21]
	v_mfma_f32_16x16x32_bf16 v[2:5], v[246:249], v[94:97], v[2:5]
	v_add_u32_e32 v98, 0x80, v98
	v_add_u32_e32 v99, 0x80, v99
	v_add_u32_e32 v100, 0x80, v100
	v_add_u32_e32 v101, 0x80, v101
	ds_read_b128 v[234:237], v103 offset:0
	ds_read_b128 v[238:241], v103 offset:2048
	ds_read_b128 v[242:245], v103 offset:4096
	ds_read_b128 v[246:249], v103 offset:6144
	s_waitcnt lgkmcnt(4)
	v_mfma_f32_16x16x32_bf16 v[106:109], v[218:221], v[66:69], v[106:109]
	s_add_u32 m0, s4, 0x8000
	v_mfma_f32_16x16x32_bf16 v[122:125], v[222:225], v[66:69], v[122:125]
	global_load_lds_dwordx4 v98, s[48:49]
	v_mfma_f32_16x16x32_bf16 v[138:141], v[226:229], v[66:69], v[138:141]
	v_mfma_f32_16x16x32_bf16 v[162:165], v[230:233], v[66:69], v[162:165]
	v_mfma_f32_16x16x32_bf16 v[110:113], v[218:221], v[70:73], v[110:113]
	s_add_u32 m0, s4, 0x8400
	v_mfma_f32_16x16x32_bf16 v[126:129], v[222:225], v[70:73], v[126:129]
	global_load_lds_dwordx4 v99, s[48:49]
	v_mfma_f32_16x16x32_bf16 v[142:145], v[226:229], v[70:73], v[142:145]
	v_mfma_f32_16x16x32_bf16 v[166:169], v[230:233], v[70:73], v[166:169]
	v_mfma_f32_16x16x32_bf16 v[114:117], v[218:221], v[74:77], v[114:117]
	s_add_u32 m0, s4, 0x8800
	v_mfma_f32_16x16x32_bf16 v[130:133], v[222:225], v[74:77], v[130:133]
	global_load_lds_dwordx4 v100, s[48:49]
	v_mfma_f32_16x16x32_bf16 v[154:157], v[226:229], v[74:77], v[154:157]
	v_mfma_f32_16x16x32_bf16 v[170:173], v[230:233], v[74:77], v[170:173]
	v_mfma_f32_16x16x32_bf16 v[118:121], v[218:221], v[78:81], v[118:121]
	s_add_u32 m0, s4, 0x8c00
	v_mfma_f32_16x16x32_bf16 v[134:137], v[222:225], v[78:81], v[134:137]
	global_load_lds_dwordx4 v101, s[48:49]
	v_mfma_f32_16x16x32_bf16 v[158:161], v[226:229], v[78:81], v[158:161]
	v_mfma_f32_16x16x32_bf16 v[174:177], v[230:233], v[78:81], v[174:177]
	s_waitcnt lgkmcnt(0)
	s_waitcnt vmcnt(8)
	s_barrier
	ds_read_b128 v[218:221], v102 offset:16384
	ds_read_b128 v[222:225], v102 offset:18432
	ds_read_b128 v[226:229], v102 offset:20480
	ds_read_b128 v[230:233], v102 offset:22528
	ds_read_b128 v[66:69], v250 offset:49152
	ds_read_b128 v[70:73], v250 offset:51200
	ds_read_b128 v[74:77], v250 offset:53248
	ds_read_b128 v[78:81], v250 offset:55296
	v_mfma_f32_16x16x32_bf16 v[106:109], v[234:237], v[82:85], v[106:109]
	s_add_u32 m0, s4, 0x0
	v_mfma_f32_16x16x32_bf16 v[122:125], v[238:241], v[82:85], v[122:125]
	global_load_lds_dwordx4 v98, s[28:29]
	v_mfma_f32_16x16x32_bf16 v[138:141], v[242:245], v[82:85], v[138:141]
	v_mfma_f32_16x16x32_bf16 v[162:165], v[246:249], v[82:85], v[162:165]
	v_mfma_f32_16x16x32_bf16 v[110:113], v[234:237], v[86:89], v[110:113]
	s_add_u32 m0, s4, 0x400
	v_mfma_f32_16x16x32_bf16 v[126:129], v[238:241], v[86:89], v[126:129]
	global_load_lds_dwordx4 v99, s[28:29]
	v_mfma_f32_16x16x32_bf16 v[142:145], v[242:245], v[86:89], v[142:145]
	v_mfma_f32_16x16x32_bf16 v[166:169], v[246:249], v[86:89], v[166:169]
	v_mfma_f32_16x16x32_bf16 v[114:117], v[234:237], v[90:93], v[114:117]
	v_mfma_f32_16x16x32_bf16 v[130:133], v[238:241], v[90:93], v[130:133]
	v_mfma_f32_16x16x32_bf16 v[154:157], v[242:245], v[90:93], v[154:157]
	v_mfma_f32_16x16x32_bf16 v[170:173], v[246:249], v[90:93], v[170:173]
	v_mfma_f32_16x16x32_bf16 v[118:121], v[234:237], v[94:97], v[118:121]
	v_mfma_f32_16x16x32_bf16 v[134:137], v[238:241], v[94:97], v[134:137]
	v_mfma_f32_16x16x32_bf16 v[158:161], v[242:245], v[94:97], v[158:161]
	v_mfma_f32_16x16x32_bf16 v[174:177], v[246:249], v[94:97], v[174:177]
	ds_read_b128 v[234:237], v103 offset:16384
	ds_read_b128 v[238:241], v103 offset:18432
	ds_read_b128 v[242:245], v103 offset:20480
	ds_read_b128 v[246:249], v103 offset:22528
	ds_read_b128 v[82:85], v251 offset:49152
	ds_read_b128 v[86:89], v251 offset:51200
	ds_read_b128 v[90:93], v251 offset:53248
	ds_read_b128 v[94:97], v251 offset:55296
	s_waitcnt lgkmcnt(8)
	v_mfma_f32_16x16x32_bf16 v[62:65], v[218:221], v[66:69], v[62:65]
	s_add_u32 m0, s4, 0x800
	v_mfma_f32_16x16x32_bf16 v[46:49], v[222:225], v[66:69], v[46:49]
	global_load_lds_dwordx4 v100, s[28:29]
	v_mfma_f32_16x16x32_bf16 v[30:33], v[226:229], v[66:69], v[30:33]
	v_mfma_f32_16x16x32_bf16 v[14:17], v[230:233], v[66:69], v[14:17]
	v_mfma_f32_16x16x32_bf16 v[58:61], v[218:221], v[70:73], v[58:61]
	s_add_u32 m0, s4, 0xc00
	v_mfma_f32_16x16x32_bf16 v[42:45], v[222:225], v[70:73], v[42:45]
	global_load_lds_dwordx4 v101, s[28:29]
	v_mfma_f32_16x16x32_bf16 v[26:29], v[226:229], v[70:73], v[26:29]
	v_mfma_f32_16x16x32_bf16 v[10:13], v[230:233], v[70:73], v[10:13]
	v_mfma_f32_16x16x32_bf16 v[54:57], v[218:221], v[74:77], v[54:57]
	v_mfma_f32_16x16x32_bf16 v[38:41], v[222:225], v[74:77], v[38:41]
	v_mfma_f32_16x16x32_bf16 v[22:25], v[226:229], v[74:77], v[22:25]
	v_mfma_f32_16x16x32_bf16 v[6:9], v[230:233], v[74:77], v[6:9]
	v_mfma_f32_16x16x32_bf16 v[50:53], v[218:221], v[78:81], v[50:53]
	v_mfma_f32_16x16x32_bf16 v[34:37], v[222:225], v[78:81], v[34:37]
	v_mfma_f32_16x16x32_bf16 v[18:21], v[226:229], v[78:81], v[18:21]
	v_mfma_f32_16x16x32_bf16 v[2:5], v[230:233], v[78:81], v[2:5]
	s_waitcnt lgkmcnt(0)
	s_waitcnt vmcnt(8)
	s_barrier
	ds_read_b128 v[218:221], v102 offset:49152
	ds_read_b128 v[222:225], v102 offset:51200
	ds_read_b128 v[226:229], v102 offset:53248
	ds_read_b128 v[230:233], v102 offset:55296
	v_mfma_f32_16x16x32_bf16 v[62:65], v[234:237], v[82:85], v[62:65]
	s_add_u32 m0, s4, 0x4000
	v_mfma_f32_16x16x32_bf16 v[46:49], v[238:241], v[82:85], v[46:49]
	global_load_lds_dwordx4 v98, s[6:7]
	v_mfma_f32_16x16x32_bf16 v[30:33], v[242:245], v[82:85], v[30:33]
	v_mfma_f32_16x16x32_bf16 v[14:17], v[246:249], v[82:85], v[14:17]
	v_mfma_f32_16x16x32_bf16 v[58:61], v[234:237], v[86:89], v[58:61]
	s_add_u32 m0, s4, 0x4400
	v_mfma_f32_16x16x32_bf16 v[42:45], v[238:241], v[86:89], v[42:45]
	global_load_lds_dwordx4 v99, s[6:7]
	v_mfma_f32_16x16x32_bf16 v[26:29], v[242:245], v[86:89], v[26:29]
	v_mfma_f32_16x16x32_bf16 v[10:13], v[246:249], v[86:89], v[10:13]
	v_mfma_f32_16x16x32_bf16 v[54:57], v[234:237], v[90:93], v[54:57]
	s_add_u32 m0, s4, 0x4800
	v_mfma_f32_16x16x32_bf16 v[38:41], v[238:241], v[90:93], v[38:41]
	global_load_lds_dwordx4 v100, s[6:7]
	v_mfma_f32_16x16x32_bf16 v[22:25], v[242:245], v[90:93], v[22:25]
	v_mfma_f32_16x16x32_bf16 v[6:9], v[246:249], v[90:93], v[6:9]
	v_mfma_f32_16x16x32_bf16 v[50:53], v[234:237], v[94:97], v[50:53]
	s_add_u32 m0, s4, 0x4c00
	v_mfma_f32_16x16x32_bf16 v[34:37], v[238:241], v[94:97], v[34:37]
	global_load_lds_dwordx4 v101, s[6:7]
	v_mfma_f32_16x16x32_bf16 v[18:21], v[242:245], v[94:97], v[18:21]
	v_mfma_f32_16x16x32_bf16 v[2:5], v[246:249], v[94:97], v[2:5]
	v_add_u32_e32 v98, 0x80, v98
	v_add_u32_e32 v99, 0x80, v99
	v_add_u32_e32 v100, 0x80, v100
	v_add_u32_e32 v101, 0x80, v101
	ds_read_b128 v[234:237], v103 offset:49152
	ds_read_b128 v[238:241], v103 offset:51200
	ds_read_b128 v[242:245], v103 offset:53248
	ds_read_b128 v[246:249], v103 offset:55296
	s_waitcnt lgkmcnt(4)
	v_mfma_f32_16x16x32_bf16 v[106:109], v[218:221], v[66:69], v[106:109]
	s_add_u32 m0, s4, 0x10000
	v_mfma_f32_16x16x32_bf16 v[122:125], v[222:225], v[66:69], v[122:125]
	global_load_lds_dwordx4 v98, s[48:49]
	v_mfma_f32_16x16x32_bf16 v[138:141], v[226:229], v[66:69], v[138:141]
	v_mfma_f32_16x16x32_bf16 v[162:165], v[230:233], v[66:69], v[162:165]
	v_mfma_f32_16x16x32_bf16 v[110:113], v[218:221], v[70:73], v[110:113]
	s_add_u32 m0, s4, 0x10400
	v_mfma_f32_16x16x32_bf16 v[126:129], v[222:225], v[70:73], v[126:129]
	global_load_lds_dwordx4 v99, s[48:49]
	v_mfma_f32_16x16x32_bf16 v[142:145], v[226:229], v[70:73], v[142:145]
	v_mfma_f32_16x16x32_bf16 v[166:169], v[230:233], v[70:73], v[166:169]
	v_mfma_f32_16x16x32_bf16 v[114:117], v[218:221], v[74:77], v[114:117]
	s_add_u32 m0, s4, 0x10800
	v_mfma_f32_16x16x32_bf16 v[130:133], v[222:225], v[74:77], v[130:133]
	global_load_lds_dwordx4 v100, s[48:49]
	v_mfma_f32_16x16x32_bf16 v[154:157], v[226:229], v[74:77], v[154:157]
	v_mfma_f32_16x16x32_bf16 v[170:173], v[230:233], v[74:77], v[170:173]
	v_mfma_f32_16x16x32_bf16 v[118:121], v[218:221], v[78:81], v[118:121]
	s_add_u32 m0, s4, 0x10c00
	v_mfma_f32_16x16x32_bf16 v[134:137], v[222:225], v[78:81], v[134:137]
	global_load_lds_dwordx4 v101, s[48:49]
	v_mfma_f32_16x16x32_bf16 v[158:161], v[226:229], v[78:81], v[158:161]
	v_mfma_f32_16x16x32_bf16 v[174:177], v[230:233], v[78:81], v[174:177]
	s_waitcnt lgkmcnt(0)
	s_waitcnt vmcnt(8)
	s_barrier
	ds_read_b128 v[218:221], v102 offset:0
	ds_read_b128 v[222:225], v102 offset:2048
	ds_read_b128 v[226:229], v102 offset:4096
	ds_read_b128 v[230:233], v102 offset:6144
	ds_read_b128 v[66:69], v104 offset:32768
	ds_read_b128 v[70:73], v104 offset:34816
	ds_read_b128 v[74:77], v104 offset:36864
	ds_read_b128 v[78:81], v104 offset:38912
	v_mfma_f32_16x16x32_bf16 v[106:109], v[234:237], v[82:85], v[106:109]
	s_add_u32 m0, s4, 0xc000
	v_mfma_f32_16x16x32_bf16 v[122:125], v[238:241], v[82:85], v[122:125]
	global_load_lds_dwordx4 v98, s[28:29]
	v_mfma_f32_16x16x32_bf16 v[138:141], v[242:245], v[82:85], v[138:141]
	v_mfma_f32_16x16x32_bf16 v[162:165], v[246:249], v[82:85], v[162:165]
	v_mfma_f32_16x16x32_bf16 v[110:113], v[234:237], v[86:89], v[110:113]
	s_add_u32 m0, s4, 0xc400
	v_mfma_f32_16x16x32_bf16 v[126:129], v[238:241], v[86:89], v[126:129]
	global_load_lds_dwordx4 v99, s[28:29]
	v_mfma_f32_16x16x32_bf16 v[142:145], v[242:245], v[86:89], v[142:145]
	v_mfma_f32_16x16x32_bf16 v[166:169], v[246:249], v[86:89], v[166:169]
	v_mfma_f32_16x16x32_bf16 v[114:117], v[234:237], v[90:93], v[114:117]
	v_mfma_f32_16x16x32_bf16 v[130:133], v[238:241], v[90:93], v[130:133]
	v_mfma_f32_16x16x32_bf16 v[154:157], v[242:245], v[90:93], v[154:157]
	v_mfma_f32_16x16x32_bf16 v[170:173], v[246:249], v[90:93], v[170:173]
	v_mfma_f32_16x16x32_bf16 v[118:121], v[234:237], v[94:97], v[118:121]
	v_mfma_f32_16x16x32_bf16 v[134:137], v[238:241], v[94:97], v[134:137]
	v_mfma_f32_16x16x32_bf16 v[158:161], v[242:245], v[94:97], v[158:161]
	v_mfma_f32_16x16x32_bf16 v[174:177], v[246:249], v[94:97], v[174:177]
	ds_read_b128 v[234:237], v103 offset:0
	ds_read_b128 v[238:241], v103 offset:2048
	ds_read_b128 v[242:245], v103 offset:4096
	ds_read_b128 v[246:249], v103 offset:6144
	ds_read_b128 v[82:85], v105 offset:32768
	ds_read_b128 v[86:89], v105 offset:34816
	ds_read_b128 v[90:93], v105 offset:36864
	ds_read_b128 v[94:97], v105 offset:38912
	s_waitcnt lgkmcnt(8)
	v_mfma_f32_16x16x32_bf16 v[62:65], v[218:221], v[66:69], v[62:65]
	s_add_u32 m0, s4, 0xc800
	v_mfma_f32_16x16x32_bf16 v[46:49], v[222:225], v[66:69], v[46:49]
	global_load_lds_dwordx4 v100, s[28:29]
	v_mfma_f32_16x16x32_bf16 v[30:33], v[226:229], v[66:69], v[30:33]
	v_mfma_f32_16x16x32_bf16 v[14:17], v[230:233], v[66:69], v[14:17]
	v_mfma_f32_16x16x32_bf16 v[58:61], v[218:221], v[70:73], v[58:61]
	s_add_u32 m0, s4, 0xcc00
	v_mfma_f32_16x16x32_bf16 v[42:45], v[222:225], v[70:73], v[42:45]
	global_load_lds_dwordx4 v101, s[28:29]
	v_mfma_f32_16x16x32_bf16 v[26:29], v[226:229], v[70:73], v[26:29]
	v_mfma_f32_16x16x32_bf16 v[10:13], v[230:233], v[70:73], v[10:13]
	v_mfma_f32_16x16x32_bf16 v[54:57], v[218:221], v[74:77], v[54:57]
	v_mfma_f32_16x16x32_bf16 v[38:41], v[222:225], v[74:77], v[38:41]
	v_mfma_f32_16x16x32_bf16 v[22:25], v[226:229], v[74:77], v[22:25]
	v_mfma_f32_16x16x32_bf16 v[6:9], v[230:233], v[74:77], v[6:9]
	v_mfma_f32_16x16x32_bf16 v[50:53], v[218:221], v[78:81], v[50:53]
	v_mfma_f32_16x16x32_bf16 v[34:37], v[222:225], v[78:81], v[34:37]
	v_mfma_f32_16x16x32_bf16 v[18:21], v[226:229], v[78:81], v[18:21]
	v_mfma_f32_16x16x32_bf16 v[2:5], v[230:233], v[78:81], v[2:5]
	s_waitcnt lgkmcnt(0)
	s_waitcnt vmcnt(8)
	s_barrier
	ds_read_b128 v[218:221], v102 offset:16384
	ds_read_b128 v[222:225], v102 offset:18432
	ds_read_b128 v[226:229], v102 offset:20480
	ds_read_b128 v[230:233], v102 offset:22528
	v_mfma_f32_16x16x32_bf16 v[62:65], v[234:237], v[82:85], v[62:65]
	s_add_u32 m0, s4, 0x0
	v_mfma_f32_16x16x32_bf16 v[46:49], v[238:241], v[82:85], v[46:49]
	global_load_lds_dwordx4 v98, s[6:7]
	v_mfma_f32_16x16x32_bf16 v[30:33], v[242:245], v[82:85], v[30:33]
	v_mfma_f32_16x16x32_bf16 v[14:17], v[246:249], v[82:85], v[14:17]
	v_mfma_f32_16x16x32_bf16 v[58:61], v[234:237], v[86:89], v[58:61]
	s_add_u32 m0, s4, 0x400
	v_mfma_f32_16x16x32_bf16 v[42:45], v[238:241], v[86:89], v[42:45]
	global_load_lds_dwordx4 v99, s[6:7]
	v_mfma_f32_16x16x32_bf16 v[26:29], v[242:245], v[86:89], v[26:29]
	v_mfma_f32_16x16x32_bf16 v[10:13], v[246:249], v[86:89], v[10:13]
	v_mfma_f32_16x16x32_bf16 v[54:57], v[234:237], v[90:93], v[54:57]
	s_add_u32 m0, s4, 0x800
	v_mfma_f32_16x16x32_bf16 v[38:41], v[238:241], v[90:93], v[38:41]
	global_load_lds_dwordx4 v100, s[6:7]
	v_mfma_f32_16x16x32_bf16 v[22:25], v[242:245], v[90:93], v[22:25]
	v_mfma_f32_16x16x32_bf16 v[6:9], v[246:249], v[90:93], v[6:9]
	v_mfma_f32_16x16x32_bf16 v[50:53], v[234:237], v[94:97], v[50:53]
	s_add_u32 m0, s4, 0xc00
	v_mfma_f32_16x16x32_bf16 v[34:37], v[238:241], v[94:97], v[34:37]
	global_load_lds_dwordx4 v101, s[6:7]
	v_mfma_f32_16x16x32_bf16 v[18:21], v[242:245], v[94:97], v[18:21]
	v_mfma_f32_16x16x32_bf16 v[2:5], v[246:249], v[94:97], v[2:5]
	v_add_u32_e32 v98, 0x80, v98
	v_add_u32_e32 v99, 0x80, v99
	v_add_u32_e32 v100, 0x80, v100
	v_add_u32_e32 v101, 0x80, v101
	ds_read_b128 v[234:237], v103 offset:16384
	ds_read_b128 v[238:241], v103 offset:18432
	ds_read_b128 v[242:245], v103 offset:20480
	ds_read_b128 v[246:249], v103 offset:22528
	s_waitcnt lgkmcnt(4)
	v_mfma_f32_16x16x32_bf16 v[106:109], v[218:221], v[66:69], v[106:109]
	s_add_u32 m0, s4, 0x8000
	v_mfma_f32_16x16x32_bf16 v[122:125], v[222:225], v[66:69], v[122:125]
	global_load_lds_dwordx4 v98, s[48:49]
	v_mfma_f32_16x16x32_bf16 v[138:141], v[226:229], v[66:69], v[138:141]
	v_mfma_f32_16x16x32_bf16 v[162:165], v[230:233], v[66:69], v[162:165]
	v_mfma_f32_16x16x32_bf16 v[110:113], v[218:221], v[70:73], v[110:113]
	s_add_u32 m0, s4, 0x8400
	v_mfma_f32_16x16x32_bf16 v[126:129], v[222:225], v[70:73], v[126:129]
	global_load_lds_dwordx4 v99, s[48:49]
	v_mfma_f32_16x16x32_bf16 v[142:145], v[226:229], v[70:73], v[142:145]
	v_mfma_f32_16x16x32_bf16 v[166:169], v[230:233], v[70:73], v[166:169]
	v_mfma_f32_16x16x32_bf16 v[114:117], v[218:221], v[74:77], v[114:117]
	s_add_u32 m0, s4, 0x8800
	v_mfma_f32_16x16x32_bf16 v[130:133], v[222:225], v[74:77], v[130:133]
	global_load_lds_dwordx4 v100, s[48:49]
	v_mfma_f32_16x16x32_bf16 v[154:157], v[226:229], v[74:77], v[154:157]
	v_mfma_f32_16x16x32_bf16 v[170:173], v[230:233], v[74:77], v[170:173]
	v_mfma_f32_16x16x32_bf16 v[118:121], v[218:221], v[78:81], v[118:121]
	s_add_u32 m0, s4, 0x8c00
	v_mfma_f32_16x16x32_bf16 v[134:137], v[222:225], v[78:81], v[134:137]
	global_load_lds_dwordx4 v101, s[48:49]
	v_mfma_f32_16x16x32_bf16 v[158:161], v[226:229], v[78:81], v[158:161]
	v_mfma_f32_16x16x32_bf16 v[174:177], v[230:233], v[78:81], v[174:177]
	s_waitcnt lgkmcnt(0)
	s_waitcnt vmcnt(8)
	s_barrier
	ds_read_b128 v[218:221], v102 offset:49152
	ds_read_b128 v[222:225], v102 offset:51200
	ds_read_b128 v[226:229], v102 offset:53248
	ds_read_b128 v[230:233], v102 offset:55296
	ds_read_b128 v[66:69], v250 offset:49152
	ds_read_b128 v[70:73], v250 offset:51200
	ds_read_b128 v[74:77], v250 offset:53248
	ds_read_b128 v[78:81], v250 offset:55296
	v_mfma_f32_16x16x32_bf16 v[106:109], v[234:237], v[82:85], v[106:109]
	s_add_u32 m0, s4, 0x4000
	v_mfma_f32_16x16x32_bf16 v[122:125], v[238:241], v[82:85], v[122:125]
	global_load_lds_dwordx4 v98, s[28:29]
	v_mfma_f32_16x16x32_bf16 v[138:141], v[242:245], v[82:85], v[138:141]
	v_mfma_f32_16x16x32_bf16 v[162:165], v[246:249], v[82:85], v[162:165]
	v_mfma_f32_16x16x32_bf16 v[110:113], v[234:237], v[86:89], v[110:113]
	s_add_u32 m0, s4, 0x4400
	v_mfma_f32_16x16x32_bf16 v[126:129], v[238:241], v[86:89], v[126:129]
	global_load_lds_dwordx4 v99, s[28:29]
	v_mfma_f32_16x16x32_bf16 v[142:145], v[242:245], v[86:89], v[142:145]
	v_mfma_f32_16x16x32_bf16 v[166:169], v[246:249], v[86:89], v[166:169]
	v_mfma_f32_16x16x32_bf16 v[114:117], v[234:237], v[90:93], v[114:117]
	v_mfma_f32_16x16x32_bf16 v[130:133], v[238:241], v[90:93], v[130:133]
	v_mfma_f32_16x16x32_bf16 v[154:157], v[242:245], v[90:93], v[154:157]
	v_mfma_f32_16x16x32_bf16 v[170:173], v[246:249], v[90:93], v[170:173]
	v_mfma_f32_16x16x32_bf16 v[118:121], v[234:237], v[94:97], v[118:121]
	v_mfma_f32_16x16x32_bf16 v[134:137], v[238:241], v[94:97], v[134:137]
	v_mfma_f32_16x16x32_bf16 v[158:161], v[242:245], v[94:97], v[158:161]
	v_mfma_f32_16x16x32_bf16 v[174:177], v[246:249], v[94:97], v[174:177]
	ds_read_b128 v[234:237], v103 offset:49152
	ds_read_b128 v[238:241], v103 offset:51200
	ds_read_b128 v[242:245], v103 offset:53248
	ds_read_b128 v[246:249], v103 offset:55296
	ds_read_b128 v[82:85], v251 offset:49152
	ds_read_b128 v[86:89], v251 offset:51200
	ds_read_b128 v[90:93], v251 offset:53248
	ds_read_b128 v[94:97], v251 offset:55296
	s_waitcnt lgkmcnt(8)
	v_mfma_f32_16x16x32_bf16 v[62:65], v[218:221], v[66:69], v[62:65]
	s_add_u32 m0, s4, 0x4800
	v_mfma_f32_16x16x32_bf16 v[46:49], v[222:225], v[66:69], v[46:49]
	global_load_lds_dwordx4 v100, s[28:29]
	v_mfma_f32_16x16x32_bf16 v[30:33], v[226:229], v[66:69], v[30:33]
	v_mfma_f32_16x16x32_bf16 v[14:17], v[230:233], v[66:69], v[14:17]
	v_mfma_f32_16x16x32_bf16 v[58:61], v[218:221], v[70:73], v[58:61]
	s_add_u32 m0, s4, 0x4c00
	v_mfma_f32_16x16x32_bf16 v[42:45], v[222:225], v[70:73], v[42:45]
	global_load_lds_dwordx4 v101, s[28:29]
	v_mfma_f32_16x16x32_bf16 v[26:29], v[226:229], v[70:73], v[26:29]
	v_mfma_f32_16x16x32_bf16 v[10:13], v[230:233], v[70:73], v[10:13]
	v_mfma_f32_16x16x32_bf16 v[54:57], v[218:221], v[74:77], v[54:57]
	v_mfma_f32_16x16x32_bf16 v[38:41], v[222:225], v[74:77], v[38:41]
	v_mfma_f32_16x16x32_bf16 v[22:25], v[226:229], v[74:77], v[22:25]
	v_mfma_f32_16x16x32_bf16 v[6:9], v[230:233], v[74:77], v[6:9]
	v_mfma_f32_16x16x32_bf16 v[50:53], v[218:221], v[78:81], v[50:53]
	v_mfma_f32_16x16x32_bf16 v[34:37], v[222:225], v[78:81], v[34:37]
	v_mfma_f32_16x16x32_bf16 v[18:21], v[226:229], v[78:81], v[18:21]
	v_mfma_f32_16x16x32_bf16 v[2:5], v[230:233], v[78:81], v[2:5]
	s_waitcnt lgkmcnt(0)
	s_waitcnt vmcnt(8)
	s_barrier
	ds_read_b128 v[218:221], v102 offset:0
	ds_read_b128 v[222:225], v102 offset:2048
	ds_read_b128 v[226:229], v102 offset:4096
	ds_read_b128 v[230:233], v102 offset:6144
	v_mfma_f32_16x16x32_bf16 v[62:65], v[234:237], v[82:85], v[62:65]
	s_add_u32 m0, s4, 0xc000
	v_mfma_f32_16x16x32_bf16 v[46:49], v[238:241], v[82:85], v[46:49]
	global_load_lds_dwordx4 v98, s[6:7]
	v_mfma_f32_16x16x32_bf16 v[30:33], v[242:245], v[82:85], v[30:33]
	v_mfma_f32_16x16x32_bf16 v[14:17], v[246:249], v[82:85], v[14:17]
	v_mfma_f32_16x16x32_bf16 v[58:61], v[234:237], v[86:89], v[58:61]
	s_add_u32 m0, s4, 0xc400
	v_mfma_f32_16x16x32_bf16 v[42:45], v[238:241], v[86:89], v[42:45]
	global_load_lds_dwordx4 v99, s[6:7]
	v_mfma_f32_16x16x32_bf16 v[26:29], v[242:245], v[86:89], v[26:29]
	v_mfma_f32_16x16x32_bf16 v[10:13], v[246:249], v[86:89], v[10:13]
	v_mfma_f32_16x16x32_bf16 v[54:57], v[234:237], v[90:93], v[54:57]
	s_add_u32 m0, s4, 0xc800
	v_mfma_f32_16x16x32_bf16 v[38:41], v[238:241], v[90:93], v[38:41]
	global_load_lds_dwordx4 v100, s[6:7]
	v_mfma_f32_16x16x32_bf16 v[22:25], v[242:245], v[90:93], v[22:25]
	v_mfma_f32_16x16x32_bf16 v[6:9], v[246:249], v[90:93], v[6:9]
	v_mfma_f32_16x16x32_bf16 v[50:53], v[234:237], v[94:97], v[50:53]
	s_add_u32 m0, s4, 0xcc00
	v_mfma_f32_16x16x32_bf16 v[34:37], v[238:241], v[94:97], v[34:37]
	global_load_lds_dwordx4 v101, s[6:7]
	v_mfma_f32_16x16x32_bf16 v[18:21], v[242:245], v[94:97], v[18:21]
	v_mfma_f32_16x16x32_bf16 v[2:5], v[246:249], v[94:97], v[2:5]
	v_add_u32_e32 v98, 0x80, v98
	v_add_u32_e32 v99, 0x80, v99
	v_add_u32_e32 v100, 0x80, v100
	v_add_u32_e32 v101, 0x80, v101
	ds_read_b128 v[234:237], v103 offset:0
	ds_read_b128 v[238:241], v103 offset:2048
	ds_read_b128 v[242:245], v103 offset:4096
	ds_read_b128 v[246:249], v103 offset:6144
	s_waitcnt lgkmcnt(4)
	v_mfma_f32_16x16x32_bf16 v[106:109], v[218:221], v[66:69], v[106:109]
	s_add_u32 m0, s4, 0x10000
	v_mfma_f32_16x16x32_bf16 v[122:125], v[222:225], v[66:69], v[122:125]
	global_load_lds_dwordx4 v98, s[48:49]
	v_mfma_f32_16x16x32_bf16 v[138:141], v[226:229], v[66:69], v[138:141]
	v_mfma_f32_16x16x32_bf16 v[162:165], v[230:233], v[66:69], v[162:165]
	v_mfma_f32_16x16x32_bf16 v[110:113], v[218:221], v[70:73], v[110:113]
	s_add_u32 m0, s4, 0x10400
	v_mfma_f32_16x16x32_bf16 v[126:129], v[222:225], v[70:73], v[126:129]
	global_load_lds_dwordx4 v99, s[48:49]
	v_mfma_f32_16x16x32_bf16 v[142:145], v[226:229], v[70:73], v[142:145]
	v_mfma_f32_16x16x32_bf16 v[166:169], v[230:233], v[70:73], v[166:169]
	v_mfma_f32_16x16x32_bf16 v[114:117], v[218:221], v[74:77], v[114:117]
	s_add_u32 m0, s4, 0x10800
	v_mfma_f32_16x16x32_bf16 v[130:133], v[222:225], v[74:77], v[130:133]
	global_load_lds_dwordx4 v100, s[48:49]
	v_mfma_f32_16x16x32_bf16 v[154:157], v[226:229], v[74:77], v[154:157]
	v_mfma_f32_16x16x32_bf16 v[170:173], v[230:233], v[74:77], v[170:173]
	v_mfma_f32_16x16x32_bf16 v[118:121], v[218:221], v[78:81], v[118:121]
	s_add_u32 m0, s4, 0x10c00
	v_mfma_f32_16x16x32_bf16 v[134:137], v[222:225], v[78:81], v[134:137]
	global_load_lds_dwordx4 v101, s[48:49]
	v_mfma_f32_16x16x32_bf16 v[158:161], v[226:229], v[78:81], v[158:161]
	v_mfma_f32_16x16x32_bf16 v[174:177], v[230:233], v[78:81], v[174:177]
	s_waitcnt lgkmcnt(0)
	s_waitcnt vmcnt(8)
	s_barrier
	ds_read_b128 v[218:221], v102 offset:16384
	ds_read_b128 v[222:225], v102 offset:18432
	ds_read_b128 v[226:229], v102 offset:20480
	ds_read_b128 v[230:233], v102 offset:22528
	ds_read_b128 v[66:69], v104 offset:32768
	ds_read_b128 v[70:73], v104 offset:34816
	ds_read_b128 v[74:77], v104 offset:36864
	ds_read_b128 v[78:81], v104 offset:38912
	v_mfma_f32_16x16x32_bf16 v[106:109], v[234:237], v[82:85], v[106:109]
	s_add_u32 m0, s4, 0x0
	v_mfma_f32_16x16x32_bf16 v[122:125], v[238:241], v[82:85], v[122:125]
	global_load_lds_dwordx4 v98, s[28:29]
	v_mfma_f32_16x16x32_bf16 v[138:141], v[242:245], v[82:85], v[138:141]
	v_mfma_f32_16x16x32_bf16 v[162:165], v[246:249], v[82:85], v[162:165]
	v_mfma_f32_16x16x32_bf16 v[110:113], v[234:237], v[86:89], v[110:113]
	s_add_u32 m0, s4, 0x400
	v_mfma_f32_16x16x32_bf16 v[126:129], v[238:241], v[86:89], v[126:129]
	global_load_lds_dwordx4 v99, s[28:29]
	v_mfma_f32_16x16x32_bf16 v[142:145], v[242:245], v[86:89], v[142:145]
	v_mfma_f32_16x16x32_bf16 v[166:169], v[246:249], v[86:89], v[166:169]
	v_mfma_f32_16x16x32_bf16 v[114:117], v[234:237], v[90:93], v[114:117]
	v_mfma_f32_16x16x32_bf16 v[130:133], v[238:241], v[90:93], v[130:133]
	v_mfma_f32_16x16x32_bf16 v[154:157], v[242:245], v[90:93], v[154:157]
	v_mfma_f32_16x16x32_bf16 v[170:173], v[246:249], v[90:93], v[170:173]
	v_mfma_f32_16x16x32_bf16 v[118:121], v[234:237], v[94:97], v[118:121]
	v_mfma_f32_16x16x32_bf16 v[134:137], v[238:241], v[94:97], v[134:137]
	v_mfma_f32_16x16x32_bf16 v[158:161], v[242:245], v[94:97], v[158:161]
	v_mfma_f32_16x16x32_bf16 v[174:177], v[246:249], v[94:97], v[174:177]
	ds_read_b128 v[234:237], v103 offset:16384
	ds_read_b128 v[238:241], v103 offset:18432
	ds_read_b128 v[242:245], v103 offset:20480
	ds_read_b128 v[246:249], v103 offset:22528
	ds_read_b128 v[82:85], v105 offset:32768
	ds_read_b128 v[86:89], v105 offset:34816
	ds_read_b128 v[90:93], v105 offset:36864
	ds_read_b128 v[94:97], v105 offset:38912
	s_waitcnt lgkmcnt(8)
	v_mfma_f32_16x16x32_bf16 v[62:65], v[218:221], v[66:69], v[62:65]
	s_add_u32 m0, s4, 0x800
	v_mfma_f32_16x16x32_bf16 v[46:49], v[222:225], v[66:69], v[46:49]
	global_load_lds_dwordx4 v100, s[28:29]
	v_mfma_f32_16x16x32_bf16 v[30:33], v[226:229], v[66:69], v[30:33]
	v_mfma_f32_16x16x32_bf16 v[14:17], v[230:233], v[66:69], v[14:17]
	v_mfma_f32_16x16x32_bf16 v[58:61], v[218:221], v[70:73], v[58:61]
	s_add_u32 m0, s4, 0xc00
	v_mfma_f32_16x16x32_bf16 v[42:45], v[222:225], v[70:73], v[42:45]
	global_load_lds_dwordx4 v101, s[28:29]
	v_mfma_f32_16x16x32_bf16 v[26:29], v[226:229], v[70:73], v[26:29]
	v_mfma_f32_16x16x32_bf16 v[10:13], v[230:233], v[70:73], v[10:13]
	v_mfma_f32_16x16x32_bf16 v[54:57], v[218:221], v[74:77], v[54:57]
	v_mfma_f32_16x16x32_bf16 v[38:41], v[222:225], v[74:77], v[38:41]
	v_mfma_f32_16x16x32_bf16 v[22:25], v[226:229], v[74:77], v[22:25]
	v_mfma_f32_16x16x32_bf16 v[6:9], v[230:233], v[74:77], v[6:9]
	v_mfma_f32_16x16x32_bf16 v[50:53], v[218:221], v[78:81], v[50:53]
	v_mfma_f32_16x16x32_bf16 v[34:37], v[222:225], v[78:81], v[34:37]
	v_mfma_f32_16x16x32_bf16 v[18:21], v[226:229], v[78:81], v[18:21]
	v_mfma_f32_16x16x32_bf16 v[2:5], v[230:233], v[78:81], v[2:5]
	s_waitcnt lgkmcnt(0)
	s_waitcnt vmcnt(8)
	s_barrier
	ds_read_b128 v[218:221], v102 offset:49152
	ds_read_b128 v[222:225], v102 offset:51200
	ds_read_b128 v[226:229], v102 offset:53248
	ds_read_b128 v[230:233], v102 offset:55296
	v_mfma_f32_16x16x32_bf16 v[62:65], v[234:237], v[82:85], v[62:65]
	s_add_u32 m0, s4, 0x4000
	v_mfma_f32_16x16x32_bf16 v[46:49], v[238:241], v[82:85], v[46:49]
	global_load_lds_dwordx4 v98, s[6:7]
	v_mfma_f32_16x16x32_bf16 v[30:33], v[242:245], v[82:85], v[30:33]
	v_mfma_f32_16x16x32_bf16 v[14:17], v[246:249], v[82:85], v[14:17]
	v_mfma_f32_16x16x32_bf16 v[58:61], v[234:237], v[86:89], v[58:61]
	s_add_u32 m0, s4, 0x4400
	v_mfma_f32_16x16x32_bf16 v[42:45], v[238:241], v[86:89], v[42:45]
	global_load_lds_dwordx4 v99, s[6:7]
	v_mfma_f32_16x16x32_bf16 v[26:29], v[242:245], v[86:89], v[26:29]
	v_mfma_f32_16x16x32_bf16 v[10:13], v[246:249], v[86:89], v[10:13]
	v_mfma_f32_16x16x32_bf16 v[54:57], v[234:237], v[90:93], v[54:57]
	s_add_u32 m0, s4, 0x4800
	v_mfma_f32_16x16x32_bf16 v[38:41], v[238:241], v[90:93], v[38:41]
	global_load_lds_dwordx4 v100, s[6:7]
	v_mfma_f32_16x16x32_bf16 v[22:25], v[242:245], v[90:93], v[22:25]
	v_mfma_f32_16x16x32_bf16 v[6:9], v[246:249], v[90:93], v[6:9]
	v_mfma_f32_16x16x32_bf16 v[50:53], v[234:237], v[94:97], v[50:53]
	s_add_u32 m0, s4, 0x4c00
	v_mfma_f32_16x16x32_bf16 v[34:37], v[238:241], v[94:97], v[34:37]
	global_load_lds_dwordx4 v101, s[6:7]
	v_mfma_f32_16x16x32_bf16 v[18:21], v[242:245], v[94:97], v[18:21]
	v_mfma_f32_16x16x32_bf16 v[2:5], v[246:249], v[94:97], v[2:5]
	v_add_u32_e32 v98, 0x80, v98
	v_add_u32_e32 v99, 0x80, v99
	v_add_u32_e32 v100, 0x80, v100
	v_add_u32_e32 v101, 0x80, v101
	ds_read_b128 v[234:237], v103 offset:49152
	ds_read_b128 v[238:241], v103 offset:51200
	ds_read_b128 v[242:245], v103 offset:53248
	ds_read_b128 v[246:249], v103 offset:55296
	s_waitcnt lgkmcnt(4)
	v_mfma_f32_16x16x32_bf16 v[106:109], v[218:221], v[66:69], v[106:109]
	s_add_u32 m0, s4, 0x8000
	v_mfma_f32_16x16x32_bf16 v[122:125], v[222:225], v[66:69], v[122:125]
	global_load_lds_dwordx4 v98, s[48:49]
	v_mfma_f32_16x16x32_bf16 v[138:141], v[226:229], v[66:69], v[138:141]
	v_mfma_f32_16x16x32_bf16 v[162:165], v[230:233], v[66:69], v[162:165]
	v_mfma_f32_16x16x32_bf16 v[110:113], v[218:221], v[70:73], v[110:113]
	s_add_u32 m0, s4, 0x8400
	v_mfma_f32_16x16x32_bf16 v[126:129], v[222:225], v[70:73], v[126:129]
	global_load_lds_dwordx4 v99, s[48:49]
	v_mfma_f32_16x16x32_bf16 v[142:145], v[226:229], v[70:73], v[142:145]
	v_mfma_f32_16x16x32_bf16 v[166:169], v[230:233], v[70:73], v[166:169]
	v_mfma_f32_16x16x32_bf16 v[114:117], v[218:221], v[74:77], v[114:117]
	s_add_u32 m0, s4, 0x8800
	v_mfma_f32_16x16x32_bf16 v[130:133], v[222:225], v[74:77], v[130:133]
	global_load_lds_dwordx4 v100, s[48:49]
	v_mfma_f32_16x16x32_bf16 v[154:157], v[226:229], v[74:77], v[154:157]
	v_mfma_f32_16x16x32_bf16 v[170:173], v[230:233], v[74:77], v[170:173]
	v_mfma_f32_16x16x32_bf16 v[118:121], v[218:221], v[78:81], v[118:121]
	s_add_u32 m0, s4, 0x8c00
	v_mfma_f32_16x16x32_bf16 v[134:137], v[222:225], v[78:81], v[134:137]
	global_load_lds_dwordx4 v101, s[48:49]
	v_mfma_f32_16x16x32_bf16 v[158:161], v[226:229], v[78:81], v[158:161]
	v_mfma_f32_16x16x32_bf16 v[174:177], v[230:233], v[78:81], v[174:177]
	s_waitcnt lgkmcnt(0)
	s_waitcnt vmcnt(8)
	s_barrier
	ds_read_b128 v[218:221], v102 offset:0
	ds_read_b128 v[222:225], v102 offset:2048
	ds_read_b128 v[226:229], v102 offset:4096
	ds_read_b128 v[230:233], v102 offset:6144
	ds_read_b128 v[66:69], v250 offset:49152
	ds_read_b128 v[70:73], v250 offset:51200
	ds_read_b128 v[74:77], v250 offset:53248
	ds_read_b128 v[78:81], v250 offset:55296
	v_mfma_f32_16x16x32_bf16 v[106:109], v[234:237], v[82:85], v[106:109]
	s_add_u32 m0, s4, 0xc000
	v_mfma_f32_16x16x32_bf16 v[122:125], v[238:241], v[82:85], v[122:125]
	global_load_lds_dwordx4 v98, s[28:29]
	v_mfma_f32_16x16x32_bf16 v[138:141], v[242:245], v[82:85], v[138:141]
	v_mfma_f32_16x16x32_bf16 v[162:165], v[246:249], v[82:85], v[162:165]
	v_mfma_f32_16x16x32_bf16 v[110:113], v[234:237], v[86:89], v[110:113]
	s_add_u32 m0, s4, 0xc400
	v_mfma_f32_16x16x32_bf16 v[126:129], v[238:241], v[86:89], v[126:129]
	global_load_lds_dwordx4 v99, s[28:29]
	v_mfma_f32_16x16x32_bf16 v[142:145], v[242:245], v[86:89], v[142:145]
	v_mfma_f32_16x16x32_bf16 v[166:169], v[246:249], v[86:89], v[166:169]
	v_mfma_f32_16x16x32_bf16 v[114:117], v[234:237], v[90:93], v[114:117]
	v_mfma_f32_16x16x32_bf16 v[130:133], v[238:241], v[90:93], v[130:133]
	v_mfma_f32_16x16x32_bf16 v[154:157], v[242:245], v[90:93], v[154:157]
	v_mfma_f32_16x16x32_bf16 v[170:173], v[246:249], v[90:93], v[170:173]
	v_mfma_f32_16x16x32_bf16 v[118:121], v[234:237], v[94:97], v[118:121]
	v_mfma_f32_16x16x32_bf16 v[134:137], v[238:241], v[94:97], v[134:137]
	v_mfma_f32_16x16x32_bf16 v[158:161], v[242:245], v[94:97], v[158:161]
	v_mfma_f32_16x16x32_bf16 v[174:177], v[246:249], v[94:97], v[174:177]
	ds_read_b128 v[234:237], v103 offset:0
	ds_read_b128 v[238:241], v103 offset:2048
	ds_read_b128 v[242:245], v103 offset:4096
	ds_read_b128 v[246:249], v103 offset:6144
	ds_read_b128 v[82:85], v251 offset:49152
	ds_read_b128 v[86:89], v251 offset:51200
	ds_read_b128 v[90:93], v251 offset:53248
	ds_read_b128 v[94:97], v251 offset:55296
	s_waitcnt lgkmcnt(8)
	v_mfma_f32_16x16x32_bf16 v[62:65], v[218:221], v[66:69], v[62:65]
	s_add_u32 m0, s4, 0xc800
	v_mfma_f32_16x16x32_bf16 v[46:49], v[222:225], v[66:69], v[46:49]
	global_load_lds_dwordx4 v100, s[28:29]
	v_mfma_f32_16x16x32_bf16 v[30:33], v[226:229], v[66:69], v[30:33]
	v_mfma_f32_16x16x32_bf16 v[14:17], v[230:233], v[66:69], v[14:17]
	v_mfma_f32_16x16x32_bf16 v[58:61], v[218:221], v[70:73], v[58:61]
	s_add_u32 m0, s4, 0xcc00
	v_mfma_f32_16x16x32_bf16 v[42:45], v[222:225], v[70:73], v[42:45]
	global_load_lds_dwordx4 v101, s[28:29]
	v_mfma_f32_16x16x32_bf16 v[26:29], v[226:229], v[70:73], v[26:29]
	v_mfma_f32_16x16x32_bf16 v[10:13], v[230:233], v[70:73], v[10:13]
	v_mfma_f32_16x16x32_bf16 v[54:57], v[218:221], v[74:77], v[54:57]
	v_mfma_f32_16x16x32_bf16 v[38:41], v[222:225], v[74:77], v[38:41]
	v_mfma_f32_16x16x32_bf16 v[22:25], v[226:229], v[74:77], v[22:25]
	v_mfma_f32_16x16x32_bf16 v[6:9], v[230:233], v[74:77], v[6:9]
	v_mfma_f32_16x16x32_bf16 v[50:53], v[218:221], v[78:81], v[50:53]
	v_mfma_f32_16x16x32_bf16 v[34:37], v[222:225], v[78:81], v[34:37]
	v_mfma_f32_16x16x32_bf16 v[18:21], v[226:229], v[78:81], v[18:21]
	v_mfma_f32_16x16x32_bf16 v[2:5], v[230:233], v[78:81], v[2:5]
	s_waitcnt lgkmcnt(0)
	s_waitcnt vmcnt(8)
	s_barrier
	ds_read_b128 v[218:221], v102 offset:16384
	ds_read_b128 v[222:225], v102 offset:18432
	ds_read_b128 v[226:229], v102 offset:20480
	ds_read_b128 v[230:233], v102 offset:22528
	v_mfma_f32_16x16x32_bf16 v[62:65], v[234:237], v[82:85], v[62:65]
	s_add_u32 m0, s4, 0x0
	v_mfma_f32_16x16x32_bf16 v[46:49], v[238:241], v[82:85], v[46:49]
	global_load_lds_dwordx4 v98, s[6:7]
	v_mfma_f32_16x16x32_bf16 v[30:33], v[242:245], v[82:85], v[30:33]
	v_mfma_f32_16x16x32_bf16 v[14:17], v[246:249], v[82:85], v[14:17]
	v_mfma_f32_16x16x32_bf16 v[58:61], v[234:237], v[86:89], v[58:61]
	s_add_u32 m0, s4, 0x400
	v_mfma_f32_16x16x32_bf16 v[42:45], v[238:241], v[86:89], v[42:45]
	global_load_lds_dwordx4 v99, s[6:7]
	v_mfma_f32_16x16x32_bf16 v[26:29], v[242:245], v[86:89], v[26:29]
	v_mfma_f32_16x16x32_bf16 v[10:13], v[246:249], v[86:89], v[10:13]
	v_mfma_f32_16x16x32_bf16 v[54:57], v[234:237], v[90:93], v[54:57]
	s_add_u32 m0, s4, 0x800
	v_mfma_f32_16x16x32_bf16 v[38:41], v[238:241], v[90:93], v[38:41]
	global_load_lds_dwordx4 v100, s[6:7]
	v_mfma_f32_16x16x32_bf16 v[22:25], v[242:245], v[90:93], v[22:25]
	v_mfma_f32_16x16x32_bf16 v[6:9], v[246:249], v[90:93], v[6:9]
	v_mfma_f32_16x16x32_bf16 v[50:53], v[234:237], v[94:97], v[50:53]
	s_add_u32 m0, s4, 0xc00
	v_mfma_f32_16x16x32_bf16 v[34:37], v[238:241], v[94:97], v[34:37]
	global_load_lds_dwordx4 v101, s[6:7]
	v_mfma_f32_16x16x32_bf16 v[18:21], v[242:245], v[94:97], v[18:21]
	v_mfma_f32_16x16x32_bf16 v[2:5], v[246:249], v[94:97], v[2:5]
	v_add_u32_e32 v98, 0x80, v98
	v_add_u32_e32 v99, 0x80, v99
	v_add_u32_e32 v100, 0x80, v100
	v_add_u32_e32 v101, 0x80, v101
	ds_read_b128 v[234:237], v103 offset:16384
	ds_read_b128 v[238:241], v103 offset:18432
	ds_read_b128 v[242:245], v103 offset:20480
	ds_read_b128 v[246:249], v103 offset:22528
	s_waitcnt lgkmcnt(4)
	v_mfma_f32_16x16x32_bf16 v[106:109], v[218:221], v[66:69], v[106:109]
	s_add_u32 m0, s4, 0x10000
	v_mfma_f32_16x16x32_bf16 v[122:125], v[222:225], v[66:69], v[122:125]
	global_load_lds_dwordx4 v98, s[48:49]
	v_mfma_f32_16x16x32_bf16 v[138:141], v[226:229], v[66:69], v[138:141]
	v_mfma_f32_16x16x32_bf16 v[162:165], v[230:233], v[66:69], v[162:165]
	v_mfma_f32_16x16x32_bf16 v[110:113], v[218:221], v[70:73], v[110:113]
	s_add_u32 m0, s4, 0x10400
	v_mfma_f32_16x16x32_bf16 v[126:129], v[222:225], v[70:73], v[126:129]
	global_load_lds_dwordx4 v99, s[48:49]
	v_mfma_f32_16x16x32_bf16 v[142:145], v[226:229], v[70:73], v[142:145]
	v_mfma_f32_16x16x32_bf16 v[166:169], v[230:233], v[70:73], v[166:169]
	v_mfma_f32_16x16x32_bf16 v[114:117], v[218:221], v[74:77], v[114:117]
	s_add_u32 m0, s4, 0x10800
	v_mfma_f32_16x16x32_bf16 v[130:133], v[222:225], v[74:77], v[130:133]
	global_load_lds_dwordx4 v100, s[48:49]
	v_mfma_f32_16x16x32_bf16 v[154:157], v[226:229], v[74:77], v[154:157]
	v_mfma_f32_16x16x32_bf16 v[170:173], v[230:233], v[74:77], v[170:173]
	v_mfma_f32_16x16x32_bf16 v[118:121], v[218:221], v[78:81], v[118:121]
	s_add_u32 m0, s4, 0x10c00
	v_mfma_f32_16x16x32_bf16 v[134:137], v[222:225], v[78:81], v[134:137]
	global_load_lds_dwordx4 v101, s[48:49]
	v_mfma_f32_16x16x32_bf16 v[158:161], v[226:229], v[78:81], v[158:161]
	v_mfma_f32_16x16x32_bf16 v[174:177], v[230:233], v[78:81], v[174:177]
	s_waitcnt lgkmcnt(0)
	s_waitcnt vmcnt(8)
	s_barrier
	ds_read_b128 v[218:221], v102 offset:49152
	ds_read_b128 v[222:225], v102 offset:51200
	ds_read_b128 v[226:229], v102 offset:53248
	ds_read_b128 v[230:233], v102 offset:55296
	ds_read_b128 v[66:69], v104 offset:32768
	ds_read_b128 v[70:73], v104 offset:34816
	ds_read_b128 v[74:77], v104 offset:36864
	ds_read_b128 v[78:81], v104 offset:38912
	v_mfma_f32_16x16x32_bf16 v[106:109], v[234:237], v[82:85], v[106:109]
	s_add_u32 m0, s4, 0x4000
	v_mfma_f32_16x16x32_bf16 v[122:125], v[238:241], v[82:85], v[122:125]
	global_load_lds_dwordx4 v98, s[28:29]
	v_mfma_f32_16x16x32_bf16 v[138:141], v[242:245], v[82:85], v[138:141]
	v_mfma_f32_16x16x32_bf16 v[162:165], v[246:249], v[82:85], v[162:165]
	v_mfma_f32_16x16x32_bf16 v[110:113], v[234:237], v[86:89], v[110:113]
	s_add_u32 m0, s4, 0x4400
	v_mfma_f32_16x16x32_bf16 v[126:129], v[238:241], v[86:89], v[126:129]
	global_load_lds_dwordx4 v99, s[28:29]
	v_mfma_f32_16x16x32_bf16 v[142:145], v[242:245], v[86:89], v[142:145]
	v_mfma_f32_16x16x32_bf16 v[166:169], v[246:249], v[86:89], v[166:169]
	v_mfma_f32_16x16x32_bf16 v[114:117], v[234:237], v[90:93], v[114:117]
	v_mfma_f32_16x16x32_bf16 v[130:133], v[238:241], v[90:93], v[130:133]
	v_mfma_f32_16x16x32_bf16 v[154:157], v[242:245], v[90:93], v[154:157]
	v_mfma_f32_16x16x32_bf16 v[170:173], v[246:249], v[90:93], v[170:173]
	v_mfma_f32_16x16x32_bf16 v[118:121], v[234:237], v[94:97], v[118:121]
	v_mfma_f32_16x16x32_bf16 v[134:137], v[238:241], v[94:97], v[134:137]
	v_mfma_f32_16x16x32_bf16 v[158:161], v[242:245], v[94:97], v[158:161]
	v_mfma_f32_16x16x32_bf16 v[174:177], v[246:249], v[94:97], v[174:177]
	ds_read_b128 v[234:237], v103 offset:49152
	ds_read_b128 v[238:241], v103 offset:51200
	ds_read_b128 v[242:245], v103 offset:53248
	ds_read_b128 v[246:249], v103 offset:55296
	ds_read_b128 v[82:85], v105 offset:32768
	ds_read_b128 v[86:89], v105 offset:34816
	ds_read_b128 v[90:93], v105 offset:36864
	ds_read_b128 v[94:97], v105 offset:38912
	s_waitcnt lgkmcnt(8)
	v_mfma_f32_16x16x32_bf16 v[62:65], v[218:221], v[66:69], v[62:65]
	s_add_u32 m0, s4, 0x4800
	v_mfma_f32_16x16x32_bf16 v[46:49], v[222:225], v[66:69], v[46:49]
	global_load_lds_dwordx4 v100, s[28:29]
	v_mfma_f32_16x16x32_bf16 v[30:33], v[226:229], v[66:69], v[30:33]
	v_mfma_f32_16x16x32_bf16 v[14:17], v[230:233], v[66:69], v[14:17]
	v_mfma_f32_16x16x32_bf16 v[58:61], v[218:221], v[70:73], v[58:61]
	s_add_u32 m0, s4, 0x4c00
	v_mfma_f32_16x16x32_bf16 v[42:45], v[222:225], v[70:73], v[42:45]
	global_load_lds_dwordx4 v101, s[28:29]
	v_mfma_f32_16x16x32_bf16 v[26:29], v[226:229], v[70:73], v[26:29]
	v_mfma_f32_16x16x32_bf16 v[10:13], v[230:233], v[70:73], v[10:13]
	v_mfma_f32_16x16x32_bf16 v[54:57], v[218:221], v[74:77], v[54:57]
	v_mfma_f32_16x16x32_bf16 v[38:41], v[222:225], v[74:77], v[38:41]
	v_mfma_f32_16x16x32_bf16 v[22:25], v[226:229], v[74:77], v[22:25]
	v_mfma_f32_16x16x32_bf16 v[6:9], v[230:233], v[74:77], v[6:9]
	v_mfma_f32_16x16x32_bf16 v[50:53], v[218:221], v[78:81], v[50:53]
	v_mfma_f32_16x16x32_bf16 v[34:37], v[222:225], v[78:81], v[34:37]
	v_mfma_f32_16x16x32_bf16 v[18:21], v[226:229], v[78:81], v[18:21]
	v_mfma_f32_16x16x32_bf16 v[2:5], v[230:233], v[78:81], v[2:5]
	s_waitcnt lgkmcnt(0)
	s_waitcnt vmcnt(8)
	s_barrier
	ds_read_b128 v[218:221], v102 offset:0
	ds_read_b128 v[222:225], v102 offset:2048
	ds_read_b128 v[226:229], v102 offset:4096
	ds_read_b128 v[230:233], v102 offset:6144
	v_mfma_f32_16x16x32_bf16 v[62:65], v[234:237], v[82:85], v[62:65]
	s_add_u32 m0, s4, 0xc000
	v_mfma_f32_16x16x32_bf16 v[46:49], v[238:241], v[82:85], v[46:49]
	global_load_lds_dwordx4 v98, s[6:7]
	v_mfma_f32_16x16x32_bf16 v[30:33], v[242:245], v[82:85], v[30:33]
	v_mfma_f32_16x16x32_bf16 v[14:17], v[246:249], v[82:85], v[14:17]
	v_mfma_f32_16x16x32_bf16 v[58:61], v[234:237], v[86:89], v[58:61]
	s_add_u32 m0, s4, 0xc400
	v_mfma_f32_16x16x32_bf16 v[42:45], v[238:241], v[86:89], v[42:45]
	global_load_lds_dwordx4 v99, s[6:7]
	v_mfma_f32_16x16x32_bf16 v[26:29], v[242:245], v[86:89], v[26:29]
	v_mfma_f32_16x16x32_bf16 v[10:13], v[246:249], v[86:89], v[10:13]
	v_mfma_f32_16x16x32_bf16 v[54:57], v[234:237], v[90:93], v[54:57]
	s_add_u32 m0, s4, 0xc800
	v_mfma_f32_16x16x32_bf16 v[38:41], v[238:241], v[90:93], v[38:41]
	global_load_lds_dwordx4 v100, s[6:7]
	v_mfma_f32_16x16x32_bf16 v[22:25], v[242:245], v[90:93], v[22:25]
	v_mfma_f32_16x16x32_bf16 v[6:9], v[246:249], v[90:93], v[6:9]
	v_mfma_f32_16x16x32_bf16 v[50:53], v[234:237], v[94:97], v[50:53]
	s_add_u32 m0, s4, 0xcc00
	v_mfma_f32_16x16x32_bf16 v[34:37], v[238:241], v[94:97], v[34:37]
	global_load_lds_dwordx4 v101, s[6:7]
	v_mfma_f32_16x16x32_bf16 v[18:21], v[242:245], v[94:97], v[18:21]
	v_mfma_f32_16x16x32_bf16 v[2:5], v[246:249], v[94:97], v[2:5]
	v_add_u32_e32 v98, 0x80, v98
	v_add_u32_e32 v99, 0x80, v99
	v_add_u32_e32 v100, 0x80, v100
	v_add_u32_e32 v101, 0x80, v101
	ds_read_b128 v[234:237], v103 offset:0
	ds_read_b128 v[238:241], v103 offset:2048
	ds_read_b128 v[242:245], v103 offset:4096
	ds_read_b128 v[246:249], v103 offset:6144
	s_waitcnt lgkmcnt(4)
	v_mfma_f32_16x16x32_bf16 v[106:109], v[218:221], v[66:69], v[106:109]
	s_add_u32 m0, s4, 0x8000
	v_mfma_f32_16x16x32_bf16 v[122:125], v[222:225], v[66:69], v[122:125]
	global_load_lds_dwordx4 v98, s[48:49]
	v_mfma_f32_16x16x32_bf16 v[138:141], v[226:229], v[66:69], v[138:141]
	v_mfma_f32_16x16x32_bf16 v[162:165], v[230:233], v[66:69], v[162:165]
	v_mfma_f32_16x16x32_bf16 v[110:113], v[218:221], v[70:73], v[110:113]
	s_add_u32 m0, s4, 0x8400
	v_mfma_f32_16x16x32_bf16 v[126:129], v[222:225], v[70:73], v[126:129]
	global_load_lds_dwordx4 v99, s[48:49]
	v_mfma_f32_16x16x32_bf16 v[142:145], v[226:229], v[70:73], v[142:145]
	v_mfma_f32_16x16x32_bf16 v[166:169], v[230:233], v[70:73], v[166:169]
	v_mfma_f32_16x16x32_bf16 v[114:117], v[218:221], v[74:77], v[114:117]
	s_add_u32 m0, s4, 0x8800
	v_mfma_f32_16x16x32_bf16 v[130:133], v[222:225], v[74:77], v[130:133]
	global_load_lds_dwordx4 v100, s[48:49]
	v_mfma_f32_16x16x32_bf16 v[154:157], v[226:229], v[74:77], v[154:157]
	v_mfma_f32_16x16x32_bf16 v[170:173], v[230:233], v[74:77], v[170:173]
	v_mfma_f32_16x16x32_bf16 v[118:121], v[218:221], v[78:81], v[118:121]
	s_add_u32 m0, s4, 0x8c00
	v_mfma_f32_16x16x32_bf16 v[134:137], v[222:225], v[78:81], v[134:137]
	global_load_lds_dwordx4 v101, s[48:49]
	v_mfma_f32_16x16x32_bf16 v[158:161], v[226:229], v[78:81], v[158:161]
	v_mfma_f32_16x16x32_bf16 v[174:177], v[230:233], v[78:81], v[174:177]
	s_waitcnt lgkmcnt(0)
	s_waitcnt vmcnt(8)
	s_barrier
	ds_read_b128 v[218:221], v102 offset:16384
	ds_read_b128 v[222:225], v102 offset:18432
	ds_read_b128 v[226:229], v102 offset:20480
	ds_read_b128 v[230:233], v102 offset:22528
	ds_read_b128 v[66:69], v250 offset:49152
	ds_read_b128 v[70:73], v250 offset:51200
	ds_read_b128 v[74:77], v250 offset:53248
	ds_read_b128 v[78:81], v250 offset:55296
	v_mfma_f32_16x16x32_bf16 v[106:109], v[234:237], v[82:85], v[106:109]
	s_add_u32 m0, s4, 0x0
	v_mfma_f32_16x16x32_bf16 v[122:125], v[238:241], v[82:85], v[122:125]
	global_load_lds_dwordx4 v98, s[28:29]
	v_mfma_f32_16x16x32_bf16 v[138:141], v[242:245], v[82:85], v[138:141]
	v_mfma_f32_16x16x32_bf16 v[162:165], v[246:249], v[82:85], v[162:165]
	v_mfma_f32_16x16x32_bf16 v[110:113], v[234:237], v[86:89], v[110:113]
	s_add_u32 m0, s4, 0x400
	v_mfma_f32_16x16x32_bf16 v[126:129], v[238:241], v[86:89], v[126:129]
	global_load_lds_dwordx4 v99, s[28:29]
	v_mfma_f32_16x16x32_bf16 v[142:145], v[242:245], v[86:89], v[142:145]
	v_mfma_f32_16x16x32_bf16 v[166:169], v[246:249], v[86:89], v[166:169]
	v_mfma_f32_16x16x32_bf16 v[114:117], v[234:237], v[90:93], v[114:117]
	v_mfma_f32_16x16x32_bf16 v[130:133], v[238:241], v[90:93], v[130:133]
	v_mfma_f32_16x16x32_bf16 v[154:157], v[242:245], v[90:93], v[154:157]
	v_mfma_f32_16x16x32_bf16 v[170:173], v[246:249], v[90:93], v[170:173]
	v_mfma_f32_16x16x32_bf16 v[118:121], v[234:237], v[94:97], v[118:121]
	v_mfma_f32_16x16x32_bf16 v[134:137], v[238:241], v[94:97], v[134:137]
	v_mfma_f32_16x16x32_bf16 v[158:161], v[242:245], v[94:97], v[158:161]
	v_mfma_f32_16x16x32_bf16 v[174:177], v[246:249], v[94:97], v[174:177]
	ds_read_b128 v[234:237], v103 offset:16384
	ds_read_b128 v[238:241], v103 offset:18432
	ds_read_b128 v[242:245], v103 offset:20480
	ds_read_b128 v[246:249], v103 offset:22528
	ds_read_b128 v[82:85], v251 offset:49152
	ds_read_b128 v[86:89], v251 offset:51200
	ds_read_b128 v[90:93], v251 offset:53248
	ds_read_b128 v[94:97], v251 offset:55296
	s_waitcnt lgkmcnt(8)
	v_mfma_f32_16x16x32_bf16 v[62:65], v[218:221], v[66:69], v[62:65]
	s_add_u32 m0, s4, 0x800
	v_mfma_f32_16x16x32_bf16 v[46:49], v[222:225], v[66:69], v[46:49]
	global_load_lds_dwordx4 v100, s[28:29]
	v_mfma_f32_16x16x32_bf16 v[30:33], v[226:229], v[66:69], v[30:33]
	v_mfma_f32_16x16x32_bf16 v[14:17], v[230:233], v[66:69], v[14:17]
	v_mfma_f32_16x16x32_bf16 v[58:61], v[218:221], v[70:73], v[58:61]
	s_add_u32 m0, s4, 0xc00
	v_mfma_f32_16x16x32_bf16 v[42:45], v[222:225], v[70:73], v[42:45]
	global_load_lds_dwordx4 v101, s[28:29]
	v_mfma_f32_16x16x32_bf16 v[26:29], v[226:229], v[70:73], v[26:29]
	v_mfma_f32_16x16x32_bf16 v[10:13], v[230:233], v[70:73], v[10:13]
	v_mfma_f32_16x16x32_bf16 v[54:57], v[218:221], v[74:77], v[54:57]
	v_mfma_f32_16x16x32_bf16 v[38:41], v[222:225], v[74:77], v[38:41]
	v_mfma_f32_16x16x32_bf16 v[22:25], v[226:229], v[74:77], v[22:25]
	v_mfma_f32_16x16x32_bf16 v[6:9], v[230:233], v[74:77], v[6:9]
	v_mfma_f32_16x16x32_bf16 v[50:53], v[218:221], v[78:81], v[50:53]
	v_mfma_f32_16x16x32_bf16 v[34:37], v[222:225], v[78:81], v[34:37]
	v_mfma_f32_16x16x32_bf16 v[18:21], v[226:229], v[78:81], v[18:21]
	v_mfma_f32_16x16x32_bf16 v[2:5], v[230:233], v[78:81], v[2:5]
	s_waitcnt lgkmcnt(0)
	s_waitcnt vmcnt(8)
	s_barrier
	ds_read_b128 v[218:221], v102 offset:49152
	ds_read_b128 v[222:225], v102 offset:51200
	ds_read_b128 v[226:229], v102 offset:53248
	ds_read_b128 v[230:233], v102 offset:55296
	v_mfma_f32_16x16x32_bf16 v[62:65], v[234:237], v[82:85], v[62:65]
	s_add_u32 m0, s4, 0x4000
	v_mfma_f32_16x16x32_bf16 v[46:49], v[238:241], v[82:85], v[46:49]
	global_load_lds_dwordx4 v98, s[6:7]
	v_mfma_f32_16x16x32_bf16 v[30:33], v[242:245], v[82:85], v[30:33]
	v_mfma_f32_16x16x32_bf16 v[14:17], v[246:249], v[82:85], v[14:17]
	v_mfma_f32_16x16x32_bf16 v[58:61], v[234:237], v[86:89], v[58:61]
	s_add_u32 m0, s4, 0x4400
	v_mfma_f32_16x16x32_bf16 v[42:45], v[238:241], v[86:89], v[42:45]
	global_load_lds_dwordx4 v99, s[6:7]
	v_mfma_f32_16x16x32_bf16 v[26:29], v[242:245], v[86:89], v[26:29]
	v_mfma_f32_16x16x32_bf16 v[10:13], v[246:249], v[86:89], v[10:13]
	v_mfma_f32_16x16x32_bf16 v[54:57], v[234:237], v[90:93], v[54:57]
	s_add_u32 m0, s4, 0x4800
	v_mfma_f32_16x16x32_bf16 v[38:41], v[238:241], v[90:93], v[38:41]
	global_load_lds_dwordx4 v100, s[6:7]
	v_mfma_f32_16x16x32_bf16 v[22:25], v[242:245], v[90:93], v[22:25]
	v_mfma_f32_16x16x32_bf16 v[6:9], v[246:249], v[90:93], v[6:9]
	v_mfma_f32_16x16x32_bf16 v[50:53], v[234:237], v[94:97], v[50:53]
	s_add_u32 m0, s4, 0x4c00
	v_mfma_f32_16x16x32_bf16 v[34:37], v[238:241], v[94:97], v[34:37]
	global_load_lds_dwordx4 v101, s[6:7]
	v_mfma_f32_16x16x32_bf16 v[18:21], v[242:245], v[94:97], v[18:21]
	v_mfma_f32_16x16x32_bf16 v[2:5], v[246:249], v[94:97], v[2:5]
	v_add_u32_e32 v98, 0x80, v98
	v_add_u32_e32 v99, 0x80, v99
	v_add_u32_e32 v100, 0x80, v100
	v_add_u32_e32 v101, 0x80, v101
	ds_read_b128 v[234:237], v103 offset:49152
	ds_read_b128 v[238:241], v103 offset:51200
	ds_read_b128 v[242:245], v103 offset:53248
	ds_read_b128 v[246:249], v103 offset:55296
	s_waitcnt lgkmcnt(4)
	v_mfma_f32_16x16x32_bf16 v[106:109], v[218:221], v[66:69], v[106:109]
	s_add_u32 m0, s4, 0x10000
	v_mfma_f32_16x16x32_bf16 v[122:125], v[222:225], v[66:69], v[122:125]
	global_load_lds_dwordx4 v98, s[48:49]
	v_mfma_f32_16x16x32_bf16 v[138:141], v[226:229], v[66:69], v[138:141]
	v_mfma_f32_16x16x32_bf16 v[162:165], v[230:233], v[66:69], v[162:165]
	v_mfma_f32_16x16x32_bf16 v[110:113], v[218:221], v[70:73], v[110:113]
	s_add_u32 m0, s4, 0x10400
	v_mfma_f32_16x16x32_bf16 v[126:129], v[222:225], v[70:73], v[126:129]
	global_load_lds_dwordx4 v99, s[48:49]
	v_mfma_f32_16x16x32_bf16 v[142:145], v[226:229], v[70:73], v[142:145]
	v_mfma_f32_16x16x32_bf16 v[166:169], v[230:233], v[70:73], v[166:169]
	v_mfma_f32_16x16x32_bf16 v[114:117], v[218:221], v[74:77], v[114:117]
	s_add_u32 m0, s4, 0x10800
	v_mfma_f32_16x16x32_bf16 v[130:133], v[222:225], v[74:77], v[130:133]
	global_load_lds_dwordx4 v100, s[48:49]
	v_mfma_f32_16x16x32_bf16 v[154:157], v[226:229], v[74:77], v[154:157]
	v_mfma_f32_16x16x32_bf16 v[170:173], v[230:233], v[74:77], v[170:173]
	v_mfma_f32_16x16x32_bf16 v[118:121], v[218:221], v[78:81], v[118:121]
	s_add_u32 m0, s4, 0x10c00
	v_mfma_f32_16x16x32_bf16 v[134:137], v[222:225], v[78:81], v[134:137]
	global_load_lds_dwordx4 v101, s[48:49]
	v_mfma_f32_16x16x32_bf16 v[158:161], v[226:229], v[78:81], v[158:161]
	v_mfma_f32_16x16x32_bf16 v[174:177], v[230:233], v[78:81], v[174:177]
	s_waitcnt lgkmcnt(0)
	s_waitcnt vmcnt(8)
	s_barrier
	ds_read_b128 v[218:221], v102 offset:0
	ds_read_b128 v[222:225], v102 offset:2048
	ds_read_b128 v[226:229], v102 offset:4096
	ds_read_b128 v[230:233], v102 offset:6144
	ds_read_b128 v[66:69], v104 offset:32768
	ds_read_b128 v[70:73], v104 offset:34816
	ds_read_b128 v[74:77], v104 offset:36864
	ds_read_b128 v[78:81], v104 offset:38912
	v_mfma_f32_16x16x32_bf16 v[106:109], v[234:237], v[82:85], v[106:109]
	s_add_u32 m0, s4, 0xc000
	v_mfma_f32_16x16x32_bf16 v[122:125], v[238:241], v[82:85], v[122:125]
	global_load_lds_dwordx4 v98, s[28:29]
	v_mfma_f32_16x16x32_bf16 v[138:141], v[242:245], v[82:85], v[138:141]
	v_mfma_f32_16x16x32_bf16 v[162:165], v[246:249], v[82:85], v[162:165]
	v_mfma_f32_16x16x32_bf16 v[110:113], v[234:237], v[86:89], v[110:113]
	s_add_u32 m0, s4, 0xc400
	v_mfma_f32_16x16x32_bf16 v[126:129], v[238:241], v[86:89], v[126:129]
	global_load_lds_dwordx4 v99, s[28:29]
	v_mfma_f32_16x16x32_bf16 v[142:145], v[242:245], v[86:89], v[142:145]
	v_mfma_f32_16x16x32_bf16 v[166:169], v[246:249], v[86:89], v[166:169]
	v_mfma_f32_16x16x32_bf16 v[114:117], v[234:237], v[90:93], v[114:117]
	v_mfma_f32_16x16x32_bf16 v[130:133], v[238:241], v[90:93], v[130:133]
	v_mfma_f32_16x16x32_bf16 v[154:157], v[242:245], v[90:93], v[154:157]
	v_mfma_f32_16x16x32_bf16 v[170:173], v[246:249], v[90:93], v[170:173]
	v_mfma_f32_16x16x32_bf16 v[118:121], v[234:237], v[94:97], v[118:121]
	v_mfma_f32_16x16x32_bf16 v[134:137], v[238:241], v[94:97], v[134:137]
	v_mfma_f32_16x16x32_bf16 v[158:161], v[242:245], v[94:97], v[158:161]
	v_mfma_f32_16x16x32_bf16 v[174:177], v[246:249], v[94:97], v[174:177]
	ds_read_b128 v[234:237], v103 offset:0
	ds_read_b128 v[238:241], v103 offset:2048
	ds_read_b128 v[242:245], v103 offset:4096
	ds_read_b128 v[246:249], v103 offset:6144
	ds_read_b128 v[82:85], v105 offset:32768
	ds_read_b128 v[86:89], v105 offset:34816
	ds_read_b128 v[90:93], v105 offset:36864
	ds_read_b128 v[94:97], v105 offset:38912
	s_waitcnt lgkmcnt(8)
	v_mfma_f32_16x16x32_bf16 v[62:65], v[218:221], v[66:69], v[62:65]
	s_add_u32 m0, s4, 0xc800
	v_mfma_f32_16x16x32_bf16 v[46:49], v[222:225], v[66:69], v[46:49]
	global_load_lds_dwordx4 v100, s[28:29]
	v_mfma_f32_16x16x32_bf16 v[30:33], v[226:229], v[66:69], v[30:33]
	v_mfma_f32_16x16x32_bf16 v[14:17], v[230:233], v[66:69], v[14:17]
	v_mfma_f32_16x16x32_bf16 v[58:61], v[218:221], v[70:73], v[58:61]
	s_add_u32 m0, s4, 0xcc00
	v_mfma_f32_16x16x32_bf16 v[42:45], v[222:225], v[70:73], v[42:45]
	global_load_lds_dwordx4 v101, s[28:29]
	v_mfma_f32_16x16x32_bf16 v[26:29], v[226:229], v[70:73], v[26:29]
	v_mfma_f32_16x16x32_bf16 v[10:13], v[230:233], v[70:73], v[10:13]
	v_mfma_f32_16x16x32_bf16 v[54:57], v[218:221], v[74:77], v[54:57]
	v_mfma_f32_16x16x32_bf16 v[38:41], v[222:225], v[74:77], v[38:41]
	v_mfma_f32_16x16x32_bf16 v[22:25], v[226:229], v[74:77], v[22:25]
	v_mfma_f32_16x16x32_bf16 v[6:9], v[230:233], v[74:77], v[6:9]
	v_mfma_f32_16x16x32_bf16 v[50:53], v[218:221], v[78:81], v[50:53]
	v_mfma_f32_16x16x32_bf16 v[34:37], v[222:225], v[78:81], v[34:37]
	v_mfma_f32_16x16x32_bf16 v[18:21], v[226:229], v[78:81], v[18:21]
	v_mfma_f32_16x16x32_bf16 v[2:5], v[230:233], v[78:81], v[2:5]
	s_waitcnt lgkmcnt(0)
	s_waitcnt vmcnt(8)
	s_barrier
	ds_read_b128 v[218:221], v102 offset:16384
	ds_read_b128 v[222:225], v102 offset:18432
	ds_read_b128 v[226:229], v102 offset:20480
	ds_read_b128 v[230:233], v102 offset:22528
	v_mfma_f32_16x16x32_bf16 v[62:65], v[234:237], v[82:85], v[62:65]
	s_add_u32 m0, s4, 0x0
	v_mfma_f32_16x16x32_bf16 v[46:49], v[238:241], v[82:85], v[46:49]
	global_load_lds_dwordx4 v98, s[6:7]
	v_mfma_f32_16x16x32_bf16 v[30:33], v[242:245], v[82:85], v[30:33]
	v_mfma_f32_16x16x32_bf16 v[14:17], v[246:249], v[82:85], v[14:17]
	v_mfma_f32_16x16x32_bf16 v[58:61], v[234:237], v[86:89], v[58:61]
	s_add_u32 m0, s4, 0x400
	v_mfma_f32_16x16x32_bf16 v[42:45], v[238:241], v[86:89], v[42:45]
	global_load_lds_dwordx4 v99, s[6:7]
	v_mfma_f32_16x16x32_bf16 v[26:29], v[242:245], v[86:89], v[26:29]
	v_mfma_f32_16x16x32_bf16 v[10:13], v[246:249], v[86:89], v[10:13]
	v_mfma_f32_16x16x32_bf16 v[54:57], v[234:237], v[90:93], v[54:57]
	s_add_u32 m0, s4, 0x800
	v_mfma_f32_16x16x32_bf16 v[38:41], v[238:241], v[90:93], v[38:41]
	global_load_lds_dwordx4 v100, s[6:7]
	v_mfma_f32_16x16x32_bf16 v[22:25], v[242:245], v[90:93], v[22:25]
	v_mfma_f32_16x16x32_bf16 v[6:9], v[246:249], v[90:93], v[6:9]
	v_mfma_f32_16x16x32_bf16 v[50:53], v[234:237], v[94:97], v[50:53]
	s_add_u32 m0, s4, 0xc00
	v_mfma_f32_16x16x32_bf16 v[34:37], v[238:241], v[94:97], v[34:37]
	global_load_lds_dwordx4 v101, s[6:7]
	v_mfma_f32_16x16x32_bf16 v[18:21], v[242:245], v[94:97], v[18:21]
	v_mfma_f32_16x16x32_bf16 v[2:5], v[246:249], v[94:97], v[2:5]
	v_add_u32_e32 v98, 0x80, v98
	v_add_u32_e32 v99, 0x80, v99
	v_add_u32_e32 v100, 0x80, v100
	v_add_u32_e32 v101, 0x80, v101
	ds_read_b128 v[234:237], v103 offset:16384
	ds_read_b128 v[238:241], v103 offset:18432
	ds_read_b128 v[242:245], v103 offset:20480
	ds_read_b128 v[246:249], v103 offset:22528
	s_waitcnt lgkmcnt(4)
	v_mfma_f32_16x16x32_bf16 v[106:109], v[218:221], v[66:69], v[106:109]
	s_add_u32 m0, s4, 0x8000
	v_mfma_f32_16x16x32_bf16 v[122:125], v[222:225], v[66:69], v[122:125]
	global_load_lds_dwordx4 v98, s[48:49]
	v_mfma_f32_16x16x32_bf16 v[138:141], v[226:229], v[66:69], v[138:141]
	v_mfma_f32_16x16x32_bf16 v[162:165], v[230:233], v[66:69], v[162:165]
	v_mfma_f32_16x16x32_bf16 v[110:113], v[218:221], v[70:73], v[110:113]
	s_add_u32 m0, s4, 0x8400
	v_mfma_f32_16x16x32_bf16 v[126:129], v[222:225], v[70:73], v[126:129]
	global_load_lds_dwordx4 v99, s[48:49]
	v_mfma_f32_16x16x32_bf16 v[142:145], v[226:229], v[70:73], v[142:145]
	v_mfma_f32_16x16x32_bf16 v[166:169], v[230:233], v[70:73], v[166:169]
	v_mfma_f32_16x16x32_bf16 v[114:117], v[218:221], v[74:77], v[114:117]
	s_add_u32 m0, s4, 0x8800
	v_mfma_f32_16x16x32_bf16 v[130:133], v[222:225], v[74:77], v[130:133]
	global_load_lds_dwordx4 v100, s[48:49]
	v_mfma_f32_16x16x32_bf16 v[154:157], v[226:229], v[74:77], v[154:157]
	v_mfma_f32_16x16x32_bf16 v[170:173], v[230:233], v[74:77], v[170:173]
	v_mfma_f32_16x16x32_bf16 v[118:121], v[218:221], v[78:81], v[118:121]
	s_add_u32 m0, s4, 0x8c00
	v_mfma_f32_16x16x32_bf16 v[134:137], v[222:225], v[78:81], v[134:137]
	global_load_lds_dwordx4 v101, s[48:49]
	v_mfma_f32_16x16x32_bf16 v[158:161], v[226:229], v[78:81], v[158:161]
	v_mfma_f32_16x16x32_bf16 v[174:177], v[230:233], v[78:81], v[174:177]
	s_waitcnt lgkmcnt(0)
	s_waitcnt vmcnt(8)
	s_barrier
	ds_read_b128 v[218:221], v102 offset:49152
	ds_read_b128 v[222:225], v102 offset:51200
	ds_read_b128 v[226:229], v102 offset:53248
	ds_read_b128 v[230:233], v102 offset:55296
	ds_read_b128 v[66:69], v250 offset:49152
	ds_read_b128 v[70:73], v250 offset:51200
	ds_read_b128 v[74:77], v250 offset:53248
	ds_read_b128 v[78:81], v250 offset:55296
	v_mfma_f32_16x16x32_bf16 v[106:109], v[234:237], v[82:85], v[106:109]
	s_add_u32 m0, s4, 0x4000
	v_mfma_f32_16x16x32_bf16 v[122:125], v[238:241], v[82:85], v[122:125]
	global_load_lds_dwordx4 v98, s[28:29]
	v_mfma_f32_16x16x32_bf16 v[138:141], v[242:245], v[82:85], v[138:141]
	v_mfma_f32_16x16x32_bf16 v[162:165], v[246:249], v[82:85], v[162:165]
	v_mfma_f32_16x16x32_bf16 v[110:113], v[234:237], v[86:89], v[110:113]
	s_add_u32 m0, s4, 0x4400
	v_mfma_f32_16x16x32_bf16 v[126:129], v[238:241], v[86:89], v[126:129]
	global_load_lds_dwordx4 v99, s[28:29]
	v_mfma_f32_16x16x32_bf16 v[142:145], v[242:245], v[86:89], v[142:145]
	v_mfma_f32_16x16x32_bf16 v[166:169], v[246:249], v[86:89], v[166:169]
	v_mfma_f32_16x16x32_bf16 v[114:117], v[234:237], v[90:93], v[114:117]
	v_mfma_f32_16x16x32_bf16 v[130:133], v[238:241], v[90:93], v[130:133]
	v_mfma_f32_16x16x32_bf16 v[154:157], v[242:245], v[90:93], v[154:157]
	v_mfma_f32_16x16x32_bf16 v[170:173], v[246:249], v[90:93], v[170:173]
	v_mfma_f32_16x16x32_bf16 v[118:121], v[234:237], v[94:97], v[118:121]
	v_mfma_f32_16x16x32_bf16 v[134:137], v[238:241], v[94:97], v[134:137]
	v_mfma_f32_16x16x32_bf16 v[158:161], v[242:245], v[94:97], v[158:161]
	v_mfma_f32_16x16x32_bf16 v[174:177], v[246:249], v[94:97], v[174:177]
	ds_read_b128 v[234:237], v103 offset:49152
	ds_read_b128 v[238:241], v103 offset:51200
	ds_read_b128 v[242:245], v103 offset:53248
	ds_read_b128 v[246:249], v103 offset:55296
	ds_read_b128 v[82:85], v251 offset:49152
	ds_read_b128 v[86:89], v251 offset:51200
	ds_read_b128 v[90:93], v251 offset:53248
	ds_read_b128 v[94:97], v251 offset:55296
	s_waitcnt lgkmcnt(8)
	v_mfma_f32_16x16x32_bf16 v[62:65], v[218:221], v[66:69], v[62:65]
	s_add_u32 m0, s4, 0x4800
	v_mfma_f32_16x16x32_bf16 v[46:49], v[222:225], v[66:69], v[46:49]
	global_load_lds_dwordx4 v100, s[28:29]
	v_mfma_f32_16x16x32_bf16 v[30:33], v[226:229], v[66:69], v[30:33]
	v_mfma_f32_16x16x32_bf16 v[14:17], v[230:233], v[66:69], v[14:17]
	v_mfma_f32_16x16x32_bf16 v[58:61], v[218:221], v[70:73], v[58:61]
	s_add_u32 m0, s4, 0x4c00
	v_mfma_f32_16x16x32_bf16 v[42:45], v[222:225], v[70:73], v[42:45]
	global_load_lds_dwordx4 v101, s[28:29]
	v_mfma_f32_16x16x32_bf16 v[26:29], v[226:229], v[70:73], v[26:29]
	v_mfma_f32_16x16x32_bf16 v[10:13], v[230:233], v[70:73], v[10:13]
	v_mfma_f32_16x16x32_bf16 v[54:57], v[218:221], v[74:77], v[54:57]
	v_mfma_f32_16x16x32_bf16 v[38:41], v[222:225], v[74:77], v[38:41]
	v_mfma_f32_16x16x32_bf16 v[22:25], v[226:229], v[74:77], v[22:25]
	v_mfma_f32_16x16x32_bf16 v[6:9], v[230:233], v[74:77], v[6:9]
	v_mfma_f32_16x16x32_bf16 v[50:53], v[218:221], v[78:81], v[50:53]
	v_mfma_f32_16x16x32_bf16 v[34:37], v[222:225], v[78:81], v[34:37]
	v_mfma_f32_16x16x32_bf16 v[18:21], v[226:229], v[78:81], v[18:21]
	v_mfma_f32_16x16x32_bf16 v[2:5], v[230:233], v[78:81], v[2:5]
	s_waitcnt lgkmcnt(0)
	s_waitcnt vmcnt(8)
	s_barrier
	ds_read_b128 v[218:221], v102 offset:0
	ds_read_b128 v[222:225], v102 offset:2048
	ds_read_b128 v[226:229], v102 offset:4096
	ds_read_b128 v[230:233], v102 offset:6144
	v_mfma_f32_16x16x32_bf16 v[62:65], v[234:237], v[82:85], v[62:65]
	s_add_u32 m0, s4, 0xc000
	v_mfma_f32_16x16x32_bf16 v[46:49], v[238:241], v[82:85], v[46:49]
	global_load_lds_dwordx4 v98, s[6:7]
	v_mfma_f32_16x16x32_bf16 v[30:33], v[242:245], v[82:85], v[30:33]
	v_mfma_f32_16x16x32_bf16 v[14:17], v[246:249], v[82:85], v[14:17]
	v_mfma_f32_16x16x32_bf16 v[58:61], v[234:237], v[86:89], v[58:61]
	s_add_u32 m0, s4, 0xc400
	v_mfma_f32_16x16x32_bf16 v[42:45], v[238:241], v[86:89], v[42:45]
	global_load_lds_dwordx4 v99, s[6:7]
	v_mfma_f32_16x16x32_bf16 v[26:29], v[242:245], v[86:89], v[26:29]
	v_mfma_f32_16x16x32_bf16 v[10:13], v[246:249], v[86:89], v[10:13]
	v_mfma_f32_16x16x32_bf16 v[54:57], v[234:237], v[90:93], v[54:57]
	s_add_u32 m0, s4, 0xc800
	v_mfma_f32_16x16x32_bf16 v[38:41], v[238:241], v[90:93], v[38:41]
	global_load_lds_dwordx4 v100, s[6:7]
	v_mfma_f32_16x16x32_bf16 v[22:25], v[242:245], v[90:93], v[22:25]
	v_mfma_f32_16x16x32_bf16 v[6:9], v[246:249], v[90:93], v[6:9]
	v_mfma_f32_16x16x32_bf16 v[50:53], v[234:237], v[94:97], v[50:53]
	s_add_u32 m0, s4, 0xcc00
	v_mfma_f32_16x16x32_bf16 v[34:37], v[238:241], v[94:97], v[34:37]
	global_load_lds_dwordx4 v101, s[6:7]
	v_mfma_f32_16x16x32_bf16 v[18:21], v[242:245], v[94:97], v[18:21]
	v_mfma_f32_16x16x32_bf16 v[2:5], v[246:249], v[94:97], v[2:5]
	v_add_u32_e32 v98, 0x80, v98
	v_add_u32_e32 v99, 0x80, v99
	v_add_u32_e32 v100, 0x80, v100
	v_add_u32_e32 v101, 0x80, v101
	ds_read_b128 v[234:237], v103 offset:0
	ds_read_b128 v[238:241], v103 offset:2048
	ds_read_b128 v[242:245], v103 offset:4096
	ds_read_b128 v[246:249], v103 offset:6144
	s_waitcnt lgkmcnt(4)
	v_mfma_f32_16x16x32_bf16 v[106:109], v[218:221], v[66:69], v[106:109]
	s_add_u32 m0, s4, 0x10000
	v_mfma_f32_16x16x32_bf16 v[122:125], v[222:225], v[66:69], v[122:125]
	global_load_lds_dwordx4 v98, s[48:49]
	v_mfma_f32_16x16x32_bf16 v[138:141], v[226:229], v[66:69], v[138:141]
	v_mfma_f32_16x16x32_bf16 v[162:165], v[230:233], v[66:69], v[162:165]
	v_mfma_f32_16x16x32_bf16 v[110:113], v[218:221], v[70:73], v[110:113]
	s_add_u32 m0, s4, 0x10400
	v_mfma_f32_16x16x32_bf16 v[126:129], v[222:225], v[70:73], v[126:129]
	global_load_lds_dwordx4 v99, s[48:49]
	v_mfma_f32_16x16x32_bf16 v[142:145], v[226:229], v[70:73], v[142:145]
	v_mfma_f32_16x16x32_bf16 v[166:169], v[230:233], v[70:73], v[166:169]
	v_mfma_f32_16x16x32_bf16 v[114:117], v[218:221], v[74:77], v[114:117]
	s_add_u32 m0, s4, 0x10800
	v_mfma_f32_16x16x32_bf16 v[130:133], v[222:225], v[74:77], v[130:133]
	global_load_lds_dwordx4 v100, s[48:49]
	v_mfma_f32_16x16x32_bf16 v[154:157], v[226:229], v[74:77], v[154:157]
	v_mfma_f32_16x16x32_bf16 v[170:173], v[230:233], v[74:77], v[170:173]
	v_mfma_f32_16x16x32_bf16 v[118:121], v[218:221], v[78:81], v[118:121]
	s_add_u32 m0, s4, 0x10c00
	v_mfma_f32_16x16x32_bf16 v[134:137], v[222:225], v[78:81], v[134:137]
	global_load_lds_dwordx4 v101, s[48:49]
	v_mfma_f32_16x16x32_bf16 v[158:161], v[226:229], v[78:81], v[158:161]
	v_mfma_f32_16x16x32_bf16 v[174:177], v[230:233], v[78:81], v[174:177]
	s_waitcnt lgkmcnt(0)
	s_waitcnt vmcnt(8)
	s_barrier
	ds_read_b128 v[218:221], v102 offset:16384
	ds_read_b128 v[222:225], v102 offset:18432
	ds_read_b128 v[226:229], v102 offset:20480
	ds_read_b128 v[230:233], v102 offset:22528
	ds_read_b128 v[66:69], v104 offset:32768
	ds_read_b128 v[70:73], v104 offset:34816
	ds_read_b128 v[74:77], v104 offset:36864
	ds_read_b128 v[78:81], v104 offset:38912
	v_mfma_f32_16x16x32_bf16 v[106:109], v[234:237], v[82:85], v[106:109]
	s_add_u32 m0, s4, 0x0
	v_mfma_f32_16x16x32_bf16 v[122:125], v[238:241], v[82:85], v[122:125]
	global_load_lds_dwordx4 v98, s[28:29]
	v_mfma_f32_16x16x32_bf16 v[138:141], v[242:245], v[82:85], v[138:141]
	v_mfma_f32_16x16x32_bf16 v[162:165], v[246:249], v[82:85], v[162:165]
	v_mfma_f32_16x16x32_bf16 v[110:113], v[234:237], v[86:89], v[110:113]
	s_add_u32 m0, s4, 0x400
	v_mfma_f32_16x16x32_bf16 v[126:129], v[238:241], v[86:89], v[126:129]
	global_load_lds_dwordx4 v99, s[28:29]
	v_mfma_f32_16x16x32_bf16 v[142:145], v[242:245], v[86:89], v[142:145]
	v_mfma_f32_16x16x32_bf16 v[166:169], v[246:249], v[86:89], v[166:169]
	v_mfma_f32_16x16x32_bf16 v[114:117], v[234:237], v[90:93], v[114:117]
	v_mfma_f32_16x16x32_bf16 v[130:133], v[238:241], v[90:93], v[130:133]
	v_mfma_f32_16x16x32_bf16 v[154:157], v[242:245], v[90:93], v[154:157]
	v_mfma_f32_16x16x32_bf16 v[170:173], v[246:249], v[90:93], v[170:173]
	v_mfma_f32_16x16x32_bf16 v[118:121], v[234:237], v[94:97], v[118:121]
	v_mfma_f32_16x16x32_bf16 v[134:137], v[238:241], v[94:97], v[134:137]
	v_mfma_f32_16x16x32_bf16 v[158:161], v[242:245], v[94:97], v[158:161]
	v_mfma_f32_16x16x32_bf16 v[174:177], v[246:249], v[94:97], v[174:177]
	ds_read_b128 v[234:237], v103 offset:16384
	ds_read_b128 v[238:241], v103 offset:18432
	ds_read_b128 v[242:245], v103 offset:20480
	ds_read_b128 v[246:249], v103 offset:22528
	ds_read_b128 v[82:85], v105 offset:32768
	ds_read_b128 v[86:89], v105 offset:34816
	ds_read_b128 v[90:93], v105 offset:36864
	ds_read_b128 v[94:97], v105 offset:38912
	s_waitcnt lgkmcnt(8)
	v_mfma_f32_16x16x32_bf16 v[62:65], v[218:221], v[66:69], v[62:65]
	s_add_u32 m0, s4, 0x800
	v_mfma_f32_16x16x32_bf16 v[46:49], v[222:225], v[66:69], v[46:49]
	global_load_lds_dwordx4 v100, s[28:29]
	v_mfma_f32_16x16x32_bf16 v[30:33], v[226:229], v[66:69], v[30:33]
	v_mfma_f32_16x16x32_bf16 v[14:17], v[230:233], v[66:69], v[14:17]
	v_mfma_f32_16x16x32_bf16 v[58:61], v[218:221], v[70:73], v[58:61]
	s_add_u32 m0, s4, 0xc00
	v_mfma_f32_16x16x32_bf16 v[42:45], v[222:225], v[70:73], v[42:45]
	global_load_lds_dwordx4 v101, s[28:29]
	v_mfma_f32_16x16x32_bf16 v[26:29], v[226:229], v[70:73], v[26:29]
	v_mfma_f32_16x16x32_bf16 v[10:13], v[230:233], v[70:73], v[10:13]
	v_mfma_f32_16x16x32_bf16 v[54:57], v[218:221], v[74:77], v[54:57]
	v_mfma_f32_16x16x32_bf16 v[38:41], v[222:225], v[74:77], v[38:41]
	v_mfma_f32_16x16x32_bf16 v[22:25], v[226:229], v[74:77], v[22:25]
	v_mfma_f32_16x16x32_bf16 v[6:9], v[230:233], v[74:77], v[6:9]
	v_mfma_f32_16x16x32_bf16 v[50:53], v[218:221], v[78:81], v[50:53]
	v_mfma_f32_16x16x32_bf16 v[34:37], v[222:225], v[78:81], v[34:37]
	v_mfma_f32_16x16x32_bf16 v[18:21], v[226:229], v[78:81], v[18:21]
	v_mfma_f32_16x16x32_bf16 v[2:5], v[230:233], v[78:81], v[2:5]
	s_waitcnt lgkmcnt(0)
	s_waitcnt vmcnt(8)
	s_barrier
	ds_read_b128 v[218:221], v102 offset:49152
	ds_read_b128 v[222:225], v102 offset:51200
	ds_read_b128 v[226:229], v102 offset:53248
	ds_read_b128 v[230:233], v102 offset:55296
	v_mfma_f32_16x16x32_bf16 v[62:65], v[234:237], v[82:85], v[62:65]
	s_add_u32 m0, s4, 0x4000
	v_mfma_f32_16x16x32_bf16 v[46:49], v[238:241], v[82:85], v[46:49]
	global_load_lds_dwordx4 v98, s[6:7]
	v_mfma_f32_16x16x32_bf16 v[30:33], v[242:245], v[82:85], v[30:33]
	v_mfma_f32_16x16x32_bf16 v[14:17], v[246:249], v[82:85], v[14:17]
	v_mfma_f32_16x16x32_bf16 v[58:61], v[234:237], v[86:89], v[58:61]
	s_add_u32 m0, s4, 0x4400
	v_mfma_f32_16x16x32_bf16 v[42:45], v[238:241], v[86:89], v[42:45]
	global_load_lds_dwordx4 v99, s[6:7]
	v_mfma_f32_16x16x32_bf16 v[26:29], v[242:245], v[86:89], v[26:29]
	v_mfma_f32_16x16x32_bf16 v[10:13], v[246:249], v[86:89], v[10:13]
	v_mfma_f32_16x16x32_bf16 v[54:57], v[234:237], v[90:93], v[54:57]
	s_add_u32 m0, s4, 0x4800
	v_mfma_f32_16x16x32_bf16 v[38:41], v[238:241], v[90:93], v[38:41]
	global_load_lds_dwordx4 v100, s[6:7]
	v_mfma_f32_16x16x32_bf16 v[22:25], v[242:245], v[90:93], v[22:25]
	v_mfma_f32_16x16x32_bf16 v[6:9], v[246:249], v[90:93], v[6:9]
	v_mfma_f32_16x16x32_bf16 v[50:53], v[234:237], v[94:97], v[50:53]
	s_add_u32 m0, s4, 0x4c00
	v_mfma_f32_16x16x32_bf16 v[34:37], v[238:241], v[94:97], v[34:37]
	global_load_lds_dwordx4 v101, s[6:7]
	v_mfma_f32_16x16x32_bf16 v[18:21], v[242:245], v[94:97], v[18:21]
	v_mfma_f32_16x16x32_bf16 v[2:5], v[246:249], v[94:97], v[2:5]
	v_add_u32_e32 v98, 0x80, v98
	v_add_u32_e32 v99, 0x80, v99
	v_add_u32_e32 v100, 0x80, v100
	v_add_u32_e32 v101, 0x80, v101
	ds_read_b128 v[234:237], v103 offset:49152
	ds_read_b128 v[238:241], v103 offset:51200
	ds_read_b128 v[242:245], v103 offset:53248
	ds_read_b128 v[246:249], v103 offset:55296
	s_waitcnt lgkmcnt(4)
	v_mfma_f32_16x16x32_bf16 v[106:109], v[218:221], v[66:69], v[106:109]
	s_add_u32 m0, s4, 0x8000
	v_mfma_f32_16x16x32_bf16 v[122:125], v[222:225], v[66:69], v[122:125]
	global_load_lds_dwordx4 v98, s[48:49]
	v_mfma_f32_16x16x32_bf16 v[138:141], v[226:229], v[66:69], v[138:141]
	v_mfma_f32_16x16x32_bf16 v[162:165], v[230:233], v[66:69], v[162:165]
	v_mfma_f32_16x16x32_bf16 v[110:113], v[218:221], v[70:73], v[110:113]
	s_add_u32 m0, s4, 0x8400
	v_mfma_f32_16x16x32_bf16 v[126:129], v[222:225], v[70:73], v[126:129]
	global_load_lds_dwordx4 v99, s[48:49]
	v_mfma_f32_16x16x32_bf16 v[142:145], v[226:229], v[70:73], v[142:145]
	v_mfma_f32_16x16x32_bf16 v[166:169], v[230:233], v[70:73], v[166:169]
	v_mfma_f32_16x16x32_bf16 v[114:117], v[218:221], v[74:77], v[114:117]
	s_add_u32 m0, s4, 0x8800
	v_mfma_f32_16x16x32_bf16 v[130:133], v[222:225], v[74:77], v[130:133]
	global_load_lds_dwordx4 v100, s[48:49]
	v_mfma_f32_16x16x32_bf16 v[154:157], v[226:229], v[74:77], v[154:157]
	v_mfma_f32_16x16x32_bf16 v[170:173], v[230:233], v[74:77], v[170:173]
	v_mfma_f32_16x16x32_bf16 v[118:121], v[218:221], v[78:81], v[118:121]
	s_add_u32 m0, s4, 0x8c00
	v_mfma_f32_16x16x32_bf16 v[134:137], v[222:225], v[78:81], v[134:137]
	global_load_lds_dwordx4 v101, s[48:49]
	v_mfma_f32_16x16x32_bf16 v[158:161], v[226:229], v[78:81], v[158:161]
	v_mfma_f32_16x16x32_bf16 v[174:177], v[230:233], v[78:81], v[174:177]
	s_waitcnt lgkmcnt(0)
	s_waitcnt vmcnt(8)
	s_barrier
	ds_read_b128 v[218:221], v102 offset:0
	ds_read_b128 v[222:225], v102 offset:2048
	ds_read_b128 v[226:229], v102 offset:4096
	ds_read_b128 v[230:233], v102 offset:6144
	ds_read_b128 v[66:69], v250 offset:49152
	ds_read_b128 v[70:73], v250 offset:51200
	ds_read_b128 v[74:77], v250 offset:53248
	ds_read_b128 v[78:81], v250 offset:55296
	v_mfma_f32_16x16x32_bf16 v[106:109], v[234:237], v[82:85], v[106:109]
	s_add_u32 m0, s4, 0xc000
	v_mfma_f32_16x16x32_bf16 v[122:125], v[238:241], v[82:85], v[122:125]
	global_load_lds_dwordx4 v98, s[28:29]
	v_mfma_f32_16x16x32_bf16 v[138:141], v[242:245], v[82:85], v[138:141]
	v_mfma_f32_16x16x32_bf16 v[162:165], v[246:249], v[82:85], v[162:165]
	v_mfma_f32_16x16x32_bf16 v[110:113], v[234:237], v[86:89], v[110:113]
	s_add_u32 m0, s4, 0xc400
	v_mfma_f32_16x16x32_bf16 v[126:129], v[238:241], v[86:89], v[126:129]
	global_load_lds_dwordx4 v99, s[28:29]
	v_mfma_f32_16x16x32_bf16 v[142:145], v[242:245], v[86:89], v[142:145]
	v_mfma_f32_16x16x32_bf16 v[166:169], v[246:249], v[86:89], v[166:169]
	v_mfma_f32_16x16x32_bf16 v[114:117], v[234:237], v[90:93], v[114:117]
	v_mfma_f32_16x16x32_bf16 v[130:133], v[238:241], v[90:93], v[130:133]
	v_mfma_f32_16x16x32_bf16 v[154:157], v[242:245], v[90:93], v[154:157]
	v_mfma_f32_16x16x32_bf16 v[170:173], v[246:249], v[90:93], v[170:173]
	v_mfma_f32_16x16x32_bf16 v[118:121], v[234:237], v[94:97], v[118:121]
	v_mfma_f32_16x16x32_bf16 v[134:137], v[238:241], v[94:97], v[134:137]
	v_mfma_f32_16x16x32_bf16 v[158:161], v[242:245], v[94:97], v[158:161]
	v_mfma_f32_16x16x32_bf16 v[174:177], v[246:249], v[94:97], v[174:177]
	ds_read_b128 v[234:237], v103 offset:0
	ds_read_b128 v[238:241], v103 offset:2048
	ds_read_b128 v[242:245], v103 offset:4096
	ds_read_b128 v[246:249], v103 offset:6144
	ds_read_b128 v[82:85], v251 offset:49152
	ds_read_b128 v[86:89], v251 offset:51200
	ds_read_b128 v[90:93], v251 offset:53248
	ds_read_b128 v[94:97], v251 offset:55296
	s_waitcnt lgkmcnt(8)
	v_mfma_f32_16x16x32_bf16 v[62:65], v[218:221], v[66:69], v[62:65]
	s_add_u32 m0, s4, 0xc800
	v_mfma_f32_16x16x32_bf16 v[46:49], v[222:225], v[66:69], v[46:49]
	global_load_lds_dwordx4 v100, s[28:29]
	v_mfma_f32_16x16x32_bf16 v[30:33], v[226:229], v[66:69], v[30:33]
	v_mfma_f32_16x16x32_bf16 v[14:17], v[230:233], v[66:69], v[14:17]
	v_mfma_f32_16x16x32_bf16 v[58:61], v[218:221], v[70:73], v[58:61]
	s_add_u32 m0, s4, 0xcc00
	v_mfma_f32_16x16x32_bf16 v[42:45], v[222:225], v[70:73], v[42:45]
	global_load_lds_dwordx4 v101, s[28:29]
	v_mfma_f32_16x16x32_bf16 v[26:29], v[226:229], v[70:73], v[26:29]
	v_mfma_f32_16x16x32_bf16 v[10:13], v[230:233], v[70:73], v[10:13]
	v_mfma_f32_16x16x32_bf16 v[54:57], v[218:221], v[74:77], v[54:57]
	v_mfma_f32_16x16x32_bf16 v[38:41], v[222:225], v[74:77], v[38:41]
	v_mfma_f32_16x16x32_bf16 v[22:25], v[226:229], v[74:77], v[22:25]
	v_mfma_f32_16x16x32_bf16 v[6:9], v[230:233], v[74:77], v[6:9]
	v_mfma_f32_16x16x32_bf16 v[50:53], v[218:221], v[78:81], v[50:53]
	v_mfma_f32_16x16x32_bf16 v[34:37], v[222:225], v[78:81], v[34:37]
	v_mfma_f32_16x16x32_bf16 v[18:21], v[226:229], v[78:81], v[18:21]
	v_mfma_f32_16x16x32_bf16 v[2:5], v[230:233], v[78:81], v[2:5]
	s_waitcnt lgkmcnt(0)
	s_waitcnt vmcnt(8)
	s_barrier
	ds_read_b128 v[218:221], v102 offset:16384
	ds_read_b128 v[222:225], v102 offset:18432
	ds_read_b128 v[226:229], v102 offset:20480
	ds_read_b128 v[230:233], v102 offset:22528
	v_mfma_f32_16x16x32_bf16 v[62:65], v[234:237], v[82:85], v[62:65]
	s_add_u32 m0, s4, 0x0
	v_mfma_f32_16x16x32_bf16 v[46:49], v[238:241], v[82:85], v[46:49]
	global_load_lds_dwordx4 v98, s[6:7]
	v_mfma_f32_16x16x32_bf16 v[30:33], v[242:245], v[82:85], v[30:33]
	v_mfma_f32_16x16x32_bf16 v[14:17], v[246:249], v[82:85], v[14:17]
	v_mfma_f32_16x16x32_bf16 v[58:61], v[234:237], v[86:89], v[58:61]
	s_add_u32 m0, s4, 0x400
	v_mfma_f32_16x16x32_bf16 v[42:45], v[238:241], v[86:89], v[42:45]
	global_load_lds_dwordx4 v99, s[6:7]
	v_mfma_f32_16x16x32_bf16 v[26:29], v[242:245], v[86:89], v[26:29]
	v_mfma_f32_16x16x32_bf16 v[10:13], v[246:249], v[86:89], v[10:13]
	v_mfma_f32_16x16x32_bf16 v[54:57], v[234:237], v[90:93], v[54:57]
	s_add_u32 m0, s4, 0x800
	v_mfma_f32_16x16x32_bf16 v[38:41], v[238:241], v[90:93], v[38:41]
	global_load_lds_dwordx4 v100, s[6:7]
	v_mfma_f32_16x16x32_bf16 v[22:25], v[242:245], v[90:93], v[22:25]
	v_mfma_f32_16x16x32_bf16 v[6:9], v[246:249], v[90:93], v[6:9]
	v_mfma_f32_16x16x32_bf16 v[50:53], v[234:237], v[94:97], v[50:53]
	s_add_u32 m0, s4, 0xc00
	v_mfma_f32_16x16x32_bf16 v[34:37], v[238:241], v[94:97], v[34:37]
	global_load_lds_dwordx4 v101, s[6:7]
	v_mfma_f32_16x16x32_bf16 v[18:21], v[242:245], v[94:97], v[18:21]
	v_mfma_f32_16x16x32_bf16 v[2:5], v[246:249], v[94:97], v[2:5]
	v_add_u32_e32 v98, 0x80, v98
	v_add_u32_e32 v99, 0x80, v99
	v_add_u32_e32 v100, 0x80, v100
	v_add_u32_e32 v101, 0x80, v101
	ds_read_b128 v[234:237], v103 offset:16384
	ds_read_b128 v[238:241], v103 offset:18432
	ds_read_b128 v[242:245], v103 offset:20480
	ds_read_b128 v[246:249], v103 offset:22528
	s_waitcnt lgkmcnt(4)
	v_mfma_f32_16x16x32_bf16 v[106:109], v[218:221], v[66:69], v[106:109]
	v_mfma_f32_16x16x32_bf16 v[122:125], v[222:225], v[66:69], v[122:125]
	v_mfma_f32_16x16x32_bf16 v[138:141], v[226:229], v[66:69], v[138:141]
	v_mfma_f32_16x16x32_bf16 v[162:165], v[230:233], v[66:69], v[162:165]
	v_mfma_f32_16x16x32_bf16 v[110:113], v[218:221], v[70:73], v[110:113]
	v_mfma_f32_16x16x32_bf16 v[126:129], v[222:225], v[70:73], v[126:129]
	v_mfma_f32_16x16x32_bf16 v[142:145], v[226:229], v[70:73], v[142:145]
	v_mfma_f32_16x16x32_bf16 v[166:169], v[230:233], v[70:73], v[166:169]
	v_mfma_f32_16x16x32_bf16 v[114:117], v[218:221], v[74:77], v[114:117]
	v_mfma_f32_16x16x32_bf16 v[130:133], v[222:225], v[74:77], v[130:133]
	v_mfma_f32_16x16x32_bf16 v[154:157], v[226:229], v[74:77], v[154:157]
	v_mfma_f32_16x16x32_bf16 v[170:173], v[230:233], v[74:77], v[170:173]
	v_mfma_f32_16x16x32_bf16 v[118:121], v[218:221], v[78:81], v[118:121]
	v_mfma_f32_16x16x32_bf16 v[134:137], v[222:225], v[78:81], v[134:137]
	v_mfma_f32_16x16x32_bf16 v[158:161], v[226:229], v[78:81], v[158:161]
	v_mfma_f32_16x16x32_bf16 v[174:177], v[230:233], v[78:81], v[174:177]
	s_waitcnt lgkmcnt(0)
	s_waitcnt vmcnt(4)
	s_barrier
	ds_read_b128 v[218:221], v102 offset:49152
	ds_read_b128 v[222:225], v102 offset:51200
	ds_read_b128 v[226:229], v102 offset:53248
	ds_read_b128 v[230:233], v102 offset:55296
	ds_read_b128 v[66:69], v104 offset:32768
	ds_read_b128 v[70:73], v104 offset:34816
	ds_read_b128 v[74:77], v104 offset:36864
	ds_read_b128 v[78:81], v104 offset:38912
	v_mfma_f32_16x16x32_bf16 v[106:109], v[234:237], v[82:85], v[106:109]
	v_mfma_f32_16x16x32_bf16 v[122:125], v[238:241], v[82:85], v[122:125]
	v_mfma_f32_16x16x32_bf16 v[138:141], v[242:245], v[82:85], v[138:141]
	v_mfma_f32_16x16x32_bf16 v[162:165], v[246:249], v[82:85], v[162:165]
	v_mfma_f32_16x16x32_bf16 v[110:113], v[234:237], v[86:89], v[110:113]
	v_mfma_f32_16x16x32_bf16 v[126:129], v[238:241], v[86:89], v[126:129]
	v_mfma_f32_16x16x32_bf16 v[142:145], v[242:245], v[86:89], v[142:145]
	v_mfma_f32_16x16x32_bf16 v[166:169], v[246:249], v[86:89], v[166:169]
	v_mfma_f32_16x16x32_bf16 v[114:117], v[234:237], v[90:93], v[114:117]
	v_mfma_f32_16x16x32_bf16 v[130:133], v[238:241], v[90:93], v[130:133]
	v_mfma_f32_16x16x32_bf16 v[154:157], v[242:245], v[90:93], v[154:157]
	v_mfma_f32_16x16x32_bf16 v[170:173], v[246:249], v[90:93], v[170:173]
	v_mfma_f32_16x16x32_bf16 v[118:121], v[234:237], v[94:97], v[118:121]
	v_mfma_f32_16x16x32_bf16 v[134:137], v[238:241], v[94:97], v[134:137]
	v_mfma_f32_16x16x32_bf16 v[158:161], v[242:245], v[94:97], v[158:161]
	v_mfma_f32_16x16x32_bf16 v[174:177], v[246:249], v[94:97], v[174:177]
	ds_read_b128 v[234:237], v103 offset:49152
	ds_read_b128 v[238:241], v103 offset:51200
	ds_read_b128 v[242:245], v103 offset:53248
	ds_read_b128 v[246:249], v103 offset:55296
	ds_read_b128 v[82:85], v105 offset:32768
	ds_read_b128 v[86:89], v105 offset:34816
	ds_read_b128 v[90:93], v105 offset:36864
	ds_read_b128 v[94:97], v105 offset:38912
	s_waitcnt lgkmcnt(8)
	v_mfma_f32_16x16x32_bf16 v[62:65], v[218:221], v[66:69], v[62:65]
	v_mfma_f32_16x16x32_bf16 v[46:49], v[222:225], v[66:69], v[46:49]
	v_mfma_f32_16x16x32_bf16 v[30:33], v[226:229], v[66:69], v[30:33]
	v_mfma_f32_16x16x32_bf16 v[14:17], v[230:233], v[66:69], v[14:17]
	v_mfma_f32_16x16x32_bf16 v[58:61], v[218:221], v[70:73], v[58:61]
	v_mfma_f32_16x16x32_bf16 v[42:45], v[222:225], v[70:73], v[42:45]
	v_mfma_f32_16x16x32_bf16 v[26:29], v[226:229], v[70:73], v[26:29]
	v_mfma_f32_16x16x32_bf16 v[10:13], v[230:233], v[70:73], v[10:13]
	v_mfma_f32_16x16x32_bf16 v[54:57], v[218:221], v[74:77], v[54:57]
	v_mfma_f32_16x16x32_bf16 v[38:41], v[222:225], v[74:77], v[38:41]
	v_mfma_f32_16x16x32_bf16 v[22:25], v[226:229], v[74:77], v[22:25]
	v_mfma_f32_16x16x32_bf16 v[6:9], v[230:233], v[74:77], v[6:9]
	v_mfma_f32_16x16x32_bf16 v[50:53], v[218:221], v[78:81], v[50:53]
	v_mfma_f32_16x16x32_bf16 v[34:37], v[222:225], v[78:81], v[34:37]
	v_mfma_f32_16x16x32_bf16 v[18:21], v[226:229], v[78:81], v[18:21]
	v_mfma_f32_16x16x32_bf16 v[2:5], v[230:233], v[78:81], v[2:5]
	s_waitcnt lgkmcnt(0)
	s_waitcnt vmcnt(0)
	s_barrier
	ds_read_b128 v[218:221], v102 offset:0
	ds_read_b128 v[222:225], v102 offset:2048
	ds_read_b128 v[226:229], v102 offset:4096
	ds_read_b128 v[230:233], v102 offset:6144
	v_mfma_f32_16x16x32_bf16 v[62:65], v[234:237], v[82:85], v[62:65]
	v_mfma_f32_16x16x32_bf16 v[46:49], v[238:241], v[82:85], v[46:49]
	v_mfma_f32_16x16x32_bf16 v[30:33], v[242:245], v[82:85], v[30:33]
	v_mfma_f32_16x16x32_bf16 v[14:17], v[246:249], v[82:85], v[14:17]
	v_mfma_f32_16x16x32_bf16 v[58:61], v[234:237], v[86:89], v[58:61]
	v_mfma_f32_16x16x32_bf16 v[42:45], v[238:241], v[86:89], v[42:45]
	v_mfma_f32_16x16x32_bf16 v[26:29], v[242:245], v[86:89], v[26:29]
	v_mfma_f32_16x16x32_bf16 v[10:13], v[246:249], v[86:89], v[10:13]
	v_mfma_f32_16x16x32_bf16 v[54:57], v[234:237], v[90:93], v[54:57]
	v_mfma_f32_16x16x32_bf16 v[38:41], v[238:241], v[90:93], v[38:41]
	v_mfma_f32_16x16x32_bf16 v[22:25], v[242:245], v[90:93], v[22:25]
	v_mfma_f32_16x16x32_bf16 v[6:9], v[246:249], v[90:93], v[6:9]
	v_mfma_f32_16x16x32_bf16 v[50:53], v[234:237], v[94:97], v[50:53]
	v_mfma_f32_16x16x32_bf16 v[34:37], v[238:241], v[94:97], v[34:37]
	v_mfma_f32_16x16x32_bf16 v[18:21], v[242:245], v[94:97], v[18:21]
	v_mfma_f32_16x16x32_bf16 v[2:5], v[246:249], v[94:97], v[2:5]
	ds_read_b128 v[234:237], v103 offset:0
	ds_read_b128 v[238:241], v103 offset:2048
	ds_read_b128 v[242:245], v103 offset:4096
	ds_read_b128 v[246:249], v103 offset:6144
	s_waitcnt lgkmcnt(4)
	v_mfma_f32_16x16x32_bf16 v[106:109], v[218:221], v[66:69], v[106:109]
	v_mfma_f32_16x16x32_bf16 v[122:125], v[222:225], v[66:69], v[122:125]
	v_mfma_f32_16x16x32_bf16 v[138:141], v[226:229], v[66:69], v[138:141]
	v_mfma_f32_16x16x32_bf16 v[162:165], v[230:233], v[66:69], v[162:165]
	v_mfma_f32_16x16x32_bf16 v[110:113], v[218:221], v[70:73], v[110:113]
	v_mfma_f32_16x16x32_bf16 v[126:129], v[222:225], v[70:73], v[126:129]
	v_mfma_f32_16x16x32_bf16 v[142:145], v[226:229], v[70:73], v[142:145]
	v_mfma_f32_16x16x32_bf16 v[166:169], v[230:233], v[70:73], v[166:169]
	v_mfma_f32_16x16x32_bf16 v[114:117], v[218:221], v[74:77], v[114:117]
	v_mfma_f32_16x16x32_bf16 v[130:133], v[222:225], v[74:77], v[130:133]
	v_mfma_f32_16x16x32_bf16 v[154:157], v[226:229], v[74:77], v[154:157]
	v_mfma_f32_16x16x32_bf16 v[170:173], v[230:233], v[74:77], v[170:173]
	v_mfma_f32_16x16x32_bf16 v[118:121], v[218:221], v[78:81], v[118:121]
	v_mfma_f32_16x16x32_bf16 v[134:137], v[222:225], v[78:81], v[134:137]
	v_mfma_f32_16x16x32_bf16 v[158:161], v[226:229], v[78:81], v[158:161]
	v_mfma_f32_16x16x32_bf16 v[174:177], v[230:233], v[78:81], v[174:177]
	s_waitcnt lgkmcnt(0)
	v_mfma_f32_16x16x32_bf16 v[106:109], v[234:237], v[82:85], v[106:109]
	v_mfma_f32_16x16x32_bf16 v[122:125], v[238:241], v[82:85], v[122:125]
	v_mfma_f32_16x16x32_bf16 v[138:141], v[242:245], v[82:85], v[138:141]
	v_mfma_f32_16x16x32_bf16 v[162:165], v[246:249], v[82:85], v[162:165]
	v_mfma_f32_16x16x32_bf16 v[110:113], v[234:237], v[86:89], v[110:113]
	v_mfma_f32_16x16x32_bf16 v[126:129], v[238:241], v[86:89], v[126:129]
	v_mfma_f32_16x16x32_bf16 v[142:145], v[242:245], v[86:89], v[142:145]
	v_mfma_f32_16x16x32_bf16 v[166:169], v[246:249], v[86:89], v[166:169]
	v_mfma_f32_16x16x32_bf16 v[114:117], v[234:237], v[90:93], v[114:117]
	v_mfma_f32_16x16x32_bf16 v[130:133], v[238:241], v[90:93], v[130:133]
	v_mfma_f32_16x16x32_bf16 v[154:157], v[242:245], v[90:93], v[154:157]
	v_mfma_f32_16x16x32_bf16 v[170:173], v[246:249], v[90:93], v[170:173]
	v_mfma_f32_16x16x32_bf16 v[118:121], v[234:237], v[94:97], v[118:121]
	v_mfma_f32_16x16x32_bf16 v[134:137], v[238:241], v[94:97], v[134:137]
	v_mfma_f32_16x16x32_bf16 v[158:161], v[242:245], v[94:97], v[158:161]
	v_mfma_f32_16x16x32_bf16 v[174:177], v[246:249], v[94:97], v[174:177]
	s_nop 7
	s_barrier
	s_and_b32 s5, s100, 0xff
	s_cmp_lt_u32 s5, 4
	s_cbranch_scc0 .Lpk_tt_nopf
	s_add_i32 s5, s5, 1
	s_lshl_b32 s5, s5, 6
	v_readlane_b32 s6, v254, 7
	s_add_i32 s5, s5, s6
	s_mul_hi_u32 s6, s5, 0x924924a
	s_mul_i32 s7, s6, 28
	s_sub_u32 s5, s5, s7
	s_mul_hi_u32 s7, s5, 0x24924925
	s_mul_i32 s28, s7, 7
	s_sub_u32 s5, s5, s28
	s_and_b32 s28, s6, 3
	s_mul_i32 s28, s28, 7
	s_add_i32 s28, s28, s5
	s_lshl_b32 s48, s28, 18
	s_add_u32 s48, s12, s48
	s_addc_u32 s49, s13, 0
	s_lshr_b32 s6, s6, 2
	s_lshl_b32 s6, s6, 3
	v_readlane_b32 s5, v254, 6
	s_or_b32 s6, s6, s5
	s_lshl_b32 s6, s6, 3
	s_lshl_b32 s7, s7, 1
	s_add_i32 s6, s6, s7
	s_lshl_b32 s6, s6, 18
	s_add_u32 s28, s94, s6
	s_addc_u32 s29, s95, 0
	v_add_u32_e32 v98, 0xfffff800, v98
	v_add_u32_e32 v99, 0xfffff800, v99
	v_add_u32_e32 v100, 0xfffff800, v100
	v_add_u32_e32 v101, 0xfffff800, v101
	s_add_u32 m0, s4, 0xc000
	s_nop 0
	global_load_lds_dwordx4 v98, s[28:29]
	s_add_u32 m0, s4, 0xc400
	s_nop 0
	global_load_lds_dwordx4 v99, s[28:29]
	s_add_u32 m0, s4, 0xc800
	s_nop 0
	global_load_lds_dwordx4 v100, s[28:29]
	s_add_u32 m0, s4, 0xcc00
	s_nop 0
	global_load_lds_dwordx4 v101, s[28:29]
	s_add_u32 m0, s4, 0x10000
	s_nop 0
	global_load_lds_dwordx4 v98, s[48:49]
	s_add_u32 m0, s4, 0x10400
	s_nop 0
	global_load_lds_dwordx4 v99, s[48:49]
	s_add_u32 m0, s4, 0x10800
	s_nop 0
	global_load_lds_dwordx4 v100, s[48:49]
	s_add_u32 m0, s4, 0x10c00
	s_nop 0
	global_load_lds_dwordx4 v101, s[48:49]
	s_or_b32 s100, s100, 0x1000
	s_branch .Lpk_tt_end
